# asm 7.5: v_pk_add/mul/fma_f32 split into scalar pairs in NSA1/NSA2/MoBA phases (bit-identical)
# baseline (speedup 1.0000x reference)
.Lnsa1_enter:
	v_mov_b32_e32 v221, v220
	v_mov_b64_e32 v[0:1], v[204:205]
	v_mov_b64_e32 v[2:3], v[206:207]
	v_mov_b64_e32 v[72:73], v[208:209]
	v_mov_b64_e32 v[74:75], v[210:211]
	ds_read_b128 v[4:7], v162
	ds_read_b128 v[76:79], v162 offset:32
	v_readfirstlane_b32 s0, v94
	s_mov_b64 s[4:5], -1
	s_cmpk_lt_i32 s0, 0x28f
	s_waitcnt lgkmcnt(1)
	v_mfma_f32_32x32x16_bf16 v[48:63], v[4:7], v[0:3], 0
	ds_read_b128 v[4:7], v162 offset:4608
	ds_read_b128 v[80:83], v162 offset:4640
	s_waitcnt lgkmcnt(1)
	v_mfma_f32_32x32x16_bf16 v[32:47], v[4:7], v[0:3], 0
	ds_read_b128 v[4:7], v162 offset:9216
	ds_read_b128 v[84:87], v162 offset:9248
	s_waitcnt lgkmcnt(1)
	v_mfma_f32_32x32x16_bf16 v[16:31], v[4:7], v[0:3], 0
	ds_read_b128 v[4:7], v162 offset:13824
	ds_read_b128 v[164:167], v162 offset:13856
	v_mov_b64_e32 v[168:169], v[216:217]
	v_mov_b64_e32 v[170:171], v[218:219]
	v_mfma_f32_32x32x16_bf16 v[48:63], v[76:79], v[72:75], v[48:63]
	v_mov_b64_e32 v[76:77], v[212:213]
	v_mov_b64_e32 v[78:79], v[214:215]
	global_load_dwordx4 v[204:207], v[68:69], off offset:64
	global_load_dwordx4 v[208:211], v[68:69], off offset:96
	global_load_dwordx4 v[212:215], v[68:69], off offset:128
	global_load_dwordx4 v[216:219], v[68:69], off offset:160
	global_load_ushort v220, v[66:67], off offset:6
	s_waitcnt lgkmcnt(1)
	v_mfma_f32_32x32x16_bf16 v[0:15], v[4:7], v[0:3], 0
	v_mfma_f32_32x32x16_bf16 v[32:47], v[80:83], v[72:75], v[32:47]
	v_mfma_f32_32x32x16_bf16 v[16:31], v[84:87], v[72:75], v[16:31]
	s_waitcnt lgkmcnt(0)
	v_mfma_f32_32x32x16_bf16 v[0:15], v[164:167], v[72:75], v[0:15]
	ds_read_b128 v[72:75], v162 offset:64
	ds_read_b128 v[80:83], v162 offset:96
	s_waitcnt lgkmcnt(1)
	v_mfma_f32_32x32x16_bf16 v[48:63], v[72:75], v[76:79], v[48:63]
	ds_read_b128 v[72:75], v162 offset:4672
	ds_read_b128 v[84:87], v162 offset:4704
	s_waitcnt lgkmcnt(1)
	v_mfma_f32_32x32x16_bf16 v[32:47], v[72:75], v[76:79], v[32:47]
	ds_read_b128 v[72:75], v162 offset:9280
	ds_read_b128 v[164:167], v162 offset:9312
	s_waitcnt lgkmcnt(1)
	v_mfma_f32_32x32x16_bf16 v[16:31], v[72:75], v[76:79], v[16:31]
	ds_read_b128 v[72:75], v162 offset:13888
	ds_read_b128 v[172:175], v162 offset:13920
	s_waitcnt lgkmcnt(1)
	v_mfma_f32_32x32x16_bf16 v[0:15], v[72:75], v[76:79], v[0:15]
	v_mfma_f32_32x32x16_bf16 v[48:63], v[80:83], v[168:171], v[48:63]
	v_mfma_f32_32x32x16_bf16 v[32:47], v[84:87], v[168:171], v[32:47]
	v_mfma_f32_32x32x16_bf16 v[16:31], v[164:167], v[168:171], v[16:31]
	s_waitcnt lgkmcnt(0)
	v_mfma_f32_32x32x16_bf16 v[0:15], v[172:175], v[168:171], v[0:15]
	s_cbranch_scc1 .LBB0_520
	s_add_i32 s1, s20, 0
	v_mov_b32_e32 v72, s1
	ds_read_b32 v82, v72 offset:43524
	s_mov_b64 s[4:5], 0
	s_waitcnt lgkmcnt(0)
	s_nop 1
	v_add_f32_e32 v78, v48, v82
	v_add_f32_e32 v79, v49, v82
	v_add_f32_e32 v76, v50, v82
	v_add_f32_e32 v77, v51, v82
	v_max3_f32 v80, v78, s71, v79
	v_add_f32_e32 v72, v52, v82
	v_add_f32_e32 v73, v53, v82
	v_max3_f32 v80, v80, v76, v77
	v_add_f32_e32 v74, v54, v82
	v_add_f32_e32 v75, v55, v82
	v_max3_f32 v80, v80, v72, v73
	v_add_f32_e32 v84, v56, v82
	v_add_f32_e32 v85, v57, v82
	v_max3_f32 v80, v80, v74, v75
	v_max3_f32 v80, v80, v84, v85
	v_add_f32_e32 v86, v58, v82
	v_add_f32_e32 v87, v59, v82
	s_nop 0
	v_max3_f32 v83, v80, v86, v87
	v_add_f32_e32 v80, v60, v82
	v_add_f32_e32 v81, v61, v82
	s_nop 0
	v_max3_f32 v164, v83, v80, v81
	v_add_f32_e32 v83, v63, v82
	v_add_f32_e32 v82, v62, v82
	s_nop 0
	v_max3_f32 v164, v164, v82, v83
.LBB0_520:
	s_andn2_b64 vcc, exec, s[4:5]
	s_cbranch_vccnz .LBB0_523
	v_mov_b32_e32 v83, 0xf149f2ca
	s_cmp_lt_i32 s0, 0
	v_mov_b32_e32 v82, 0xf149f2ca
	v_mov_b32_e32 v81, 0xf149f2ca
	v_mov_b32_e32 v80, 0xf149f2ca
	v_mov_b32_e32 v87, 0xf149f2ca
	v_mov_b32_e32 v86, 0xf149f2ca
	v_mov_b32_e32 v85, 0xf149f2ca
	v_mov_b32_e32 v84, 0xf149f2ca
	v_mov_b32_e32 v75, 0xf149f2ca
	v_mov_b32_e32 v74, 0xf149f2ca
	v_mov_b32_e32 v73, 0xf149f2ca
	v_mov_b32_e32 v72, 0xf149f2ca
	v_mov_b32_e32 v77, 0xf149f2ca
	v_mov_b32_e32 v76, 0xf149f2ca
	v_mov_b32_e32 v79, 0xf149f2ca
	v_mov_b32_e32 v78, 0xf149f2ca
	v_mov_b32_e32 v164, 0xf149f2ca
	s_cbranch_scc1 .LBB0_523
	v_add_u32_e32 v72, s20, v161
	v_add_u32_e32 v73, s20, v160
	v_add_u32_e32 v74, s20, v159
	v_add_u32_e32 v75, s20, v158
	v_add_u32_e32 v76, s20, v157
	v_add_u32_e32 v77, s20, v156
	v_add_u32_e32 v78, s20, v155
	v_add_u32_e32 v79, s20, v154
	ds_read_b32 v72, v72
	ds_read_b32 v73, v73
	ds_read_b32 v74, v74
	ds_read_b32 v75, v75
	ds_read_b32 v80, v76
	ds_read_b32 v81, v77
	ds_read_b32 v82, v78
	ds_read_b32 v83, v79
	s_waitcnt lgkmcnt(6)
	v_add_f32_e32 v78, v48, v72
	v_add_f32_e32 v79, v49, v73
	s_waitcnt lgkmcnt(4)
	v_add_f32_e32 v76, v50, v74
	v_add_f32_e32 v77, v51, v75
	v_max3_f32 v48, v78, s71, v79
	v_max3_f32 v48, v48, v76, v77
	s_waitcnt lgkmcnt(2)
	v_add_f32_e32 v72, v52, v80
	v_add_f32_e32 v73, v53, v81
	s_waitcnt lgkmcnt(0)
	v_add_f32_e32 v74, v54, v82
	v_add_f32_e32 v75, v55, v83
	v_max3_f32 v48, v48, v72, v73
	v_max3_f32 v80, v48, v74, v75
	v_add_u32_e32 v48, s20, v153
	v_add_u32_e32 v49, s20, v152
	v_add_u32_e32 v50, s20, v151
	v_add_u32_e32 v51, s20, v150
	v_add_u32_e32 v52, s20, v149
	v_add_u32_e32 v53, s20, v148
	v_add_u32_e32 v54, s20, v147
	v_add_u32_e32 v55, s20, v146
	ds_read_b32 v48, v48
	ds_read_b32 v49, v49
	ds_read_b32 v50, v50
	ds_read_b32 v51, v51
	ds_read_b32 v52, v52
	ds_read_b32 v53, v53
	ds_read_b32 v54, v54
	ds_read_b32 v55, v55
	s_waitcnt lgkmcnt(6)
	v_add_f32_e32 v84, v56, v48
	v_add_f32_e32 v85, v57, v49
	s_waitcnt lgkmcnt(4)
	v_add_f32_e32 v86, v58, v50
	v_add_f32_e32 v87, v59, v51
	v_max3_f32 v48, v80, v84, v85
	v_max3_f32 v48, v48, v86, v87
	s_waitcnt lgkmcnt(2)
	v_add_f32_e32 v80, v60, v52
	v_add_f32_e32 v81, v61, v53
	s_waitcnt lgkmcnt(0)
	v_add_f32_e32 v82, v62, v54
	v_add_f32_e32 v83, v63, v55
	v_max3_f32 v48, v48, v80, v81
	v_max3_f32 v164, v48, v82, v83
.LBB0_523:
	s_cmpk_lt_i32 s0, 0x48f
	s_mov_b64 s[4:5], -1
	s_cbranch_scc1 .LBB0_529
	s_add_i32 s1, s20, 0
	s_nop 0
	v_mov_b32_e32 v48, s1
	ds_read_b32 v56, v48 offset:43524
	s_waitcnt lgkmcnt(0)
	v_add_f32_e32 v54, v32, v56
	v_add_f32_e32 v55, v33, v56
	v_add_f32_e32 v52, v34, v56
	v_add_f32_e32 v53, v35, v56
	v_add_f32_e32 v48, v36, v56
	v_add_f32_e32 v49, v37, v56
	v_add_f32_e32 v50, v38, v56
	v_add_f32_e32 v51, v39, v56
	v_add_f32_e32 v60, v40, v56
	v_add_f32_e32 v61, v41, v56
	v_max3_f32 v57, v164, v54, v55
	v_max3_f32 v57, v57, v52, v53
	v_max3_f32 v57, v57, v48, v49
	v_max3_f32 v57, v57, v50, v51
	v_max3_f32 v57, v57, v60, v61
	v_add_f32_e32 v62, v42, v56
	v_add_f32_e32 v63, v43, v56
	s_nop 0
	v_max3_f32 v57, v57, v62, v63
	v_add_f32_e32 v58, v44, v56
	v_add_f32_e32 v59, v45, v56
	s_nop 0
	v_max3_f32 v165, v57, v58, v59
	v_add_f32_e32 v57, v47, v56
	v_add_f32_e32 v56, v46, v56
	s_nop 0
	v_max3_f32 v165, v165, v56, v57
	s_cbranch_execz .LBB0_530

.LBB0_526:
	s_add_i32 s1, s20, 0
	v_mov_b32_e32 v32, s1
	ds_read_b32 v40, v32 offset:43524
	s_waitcnt lgkmcnt(0)
	v_add_f32_e32 v38, v16, v40
	v_add_f32_e32 v39, v17, v40
	v_add_f32_e32 v36, v18, v40
	v_add_f32_e32 v37, v19, v40
	v_add_f32_e32 v32, v20, v40
	v_add_f32_e32 v33, v21, v40
	v_add_f32_e32 v34, v22, v40
	v_add_f32_e32 v35, v23, v40
	v_add_f32_e32 v44, v24, v40
	v_add_f32_e32 v45, v25, v40
	v_max3_f32 v41, v165, v38, v39
	v_max3_f32 v41, v41, v36, v37
	v_max3_f32 v41, v41, v32, v33
	v_max3_f32 v41, v41, v34, v35
	v_max3_f32 v41, v41, v44, v45
	v_add_f32_e32 v46, v26, v40
	v_add_f32_e32 v47, v27, v40
	s_nop 0
	v_max3_f32 v41, v41, v46, v47
	v_add_f32_e32 v42, v28, v40
	v_add_f32_e32 v43, v29, v40
	s_nop 0
	v_max3_f32 v164, v41, v42, v43
	v_add_f32_e32 v41, v31, v40
	v_add_f32_e32 v40, v30, v40
	s_nop 0
	v_max3_f32 v164, v164, v40, v41
	s_cbranch_execz .LBB0_534

.LBB0_528:
	s_add_i32 s1, s20, 0
	v_mov_b32_e32 v16, s1
	ds_read_b32 v24, v16 offset:43524
	s_waitcnt lgkmcnt(0)
	v_add_f32_e32 v22, v0, v24
	v_add_f32_e32 v23, v1, v24
	v_add_f32_e32 v20, v2, v24
	v_add_f32_e32 v21, v3, v24
	v_add_f32_e32 v16, v4, v24
	v_add_f32_e32 v17, v5, v24
	v_add_f32_e32 v18, v6, v24
	v_add_f32_e32 v19, v7, v24
	v_add_f32_e32 v28, v8, v24
	v_add_f32_e32 v29, v9, v24
	v_max3_f32 v25, v164, v22, v23
	v_max3_f32 v25, v25, v20, v21
	v_max3_f32 v25, v25, v16, v17
	v_max3_f32 v25, v25, v18, v19
	v_max3_f32 v25, v25, v28, v29
	v_add_f32_e32 v30, v10, v24
	v_add_f32_e32 v31, v11, v24
	s_nop 0
	v_max3_f32 v25, v25, v30, v31
	v_add_f32_e32 v26, v12, v24
	v_add_f32_e32 v27, v13, v24
	s_nop 0
	v_max3_f32 v165, v25, v26, v27
	v_add_f32_e32 v25, v15, v24
	v_add_f32_e32 v24, v14, v24
	s_nop 0
	v_max3_f32 v165, v165, v24, v25
	s_cbranch_execnz .LBB0_542
	s_branch .LBB0_538

.LBB0_530:
	s_cmpk_lt_i32 s0, 0x200
	v_mov_b32_e32 v57, 0xf149f2ca
	s_cbranch_scc1 .LBB0_532
	v_add_u32_e32 v48, s20, v145
	v_add_u32_e32 v49, s20, v144
	v_add_u32_e32 v50, s20, v143
	v_add_u32_e32 v51, s20, v142
	v_add_u32_e32 v52, s20, v141
	v_add_u32_e32 v53, s20, v140
	v_add_u32_e32 v54, s20, v139
	v_add_u32_e32 v55, s20, v138
	ds_read_b32 v48, v48
	ds_read_b32 v49, v49
	ds_read_b32 v50, v50
	ds_read_b32 v51, v51
	ds_read_b32 v56, v52
	ds_read_b32 v57, v53
	ds_read_b32 v58, v54
	ds_read_b32 v59, v55
	s_waitcnt lgkmcnt(6)
	v_add_f32_e32 v54, v32, v48
	v_add_f32_e32 v55, v33, v49
	s_waitcnt lgkmcnt(4)
	v_add_f32_e32 v52, v34, v50
	v_add_f32_e32 v53, v35, v51
	v_max3_f32 v32, v164, v54, v55
	v_max3_f32 v32, v32, v52, v53
	s_waitcnt lgkmcnt(2)
	v_add_f32_e32 v48, v36, v56
	v_add_f32_e32 v49, v37, v57
	s_waitcnt lgkmcnt(0)
	v_add_f32_e32 v50, v38, v58
	v_add_f32_e32 v51, v39, v59
	v_max3_f32 v32, v32, v48, v49
	v_max3_f32 v56, v32, v50, v51
	v_add_u32_e32 v32, s20, v137
	v_add_u32_e32 v33, s20, v136
	v_add_u32_e32 v34, s20, v135
	v_add_u32_e32 v35, s20, v134
	v_add_u32_e32 v36, s20, v133
	v_add_u32_e32 v37, s20, v132
	v_add_u32_e32 v38, s20, v131
	v_add_u32_e32 v39, s20, v130
	ds_read_b32 v32, v32
	ds_read_b32 v33, v33
	ds_read_b32 v34, v34
	ds_read_b32 v35, v35
	ds_read_b32 v36, v36
	ds_read_b32 v37, v37
	ds_read_b32 v38, v38
	ds_read_b32 v39, v39
	s_waitcnt lgkmcnt(6)
	v_add_f32_e32 v60, v40, v32
	v_add_f32_e32 v61, v41, v33
	s_waitcnt lgkmcnt(4)
	v_add_f32_e32 v62, v42, v34
	v_add_f32_e32 v63, v43, v35
	v_max3_f32 v32, v56, v60, v61
	v_max3_f32 v32, v32, v62, v63
	s_waitcnt lgkmcnt(2)
	v_add_f32_e32 v58, v44, v36
	v_add_f32_e32 v59, v45, v37
	s_waitcnt lgkmcnt(0)
	v_add_f32_e32 v56, v46, v38
	v_add_f32_e32 v57, v47, v39
	v_max3_f32 v32, v32, v58, v59
	v_max3_f32 v164, v32, v56, v57
	v_mov_b32_e32 v165, v164
	s_cmpk_lt_i32 s0, 0x68f
	s_mov_b64 s[4:5], -1
	s_cbranch_scc1 .LBB0_533
	s_branch .LBB0_526

.LBB0_534:
	s_cmpk_lt_i32 s0, 0x400
	v_mov_b32_e32 v41, 0xf149f2ca
	s_cbranch_scc1 .LBB0_536
	v_add_u32_e32 v32, s20, v129
	v_add_u32_e32 v33, s20, v128
	v_add_u32_e32 v34, s20, v127
	v_add_u32_e32 v35, s20, v126
	v_add_u32_e32 v36, s20, v125
	v_add_u32_e32 v37, s20, v124
	v_add_u32_e32 v38, s20, v123
	v_add_u32_e32 v39, s20, v122
	ds_read_b32 v32, v32
	ds_read_b32 v33, v33
	ds_read_b32 v34, v34
	ds_read_b32 v35, v35
	ds_read_b32 v40, v36
	ds_read_b32 v41, v37
	ds_read_b32 v42, v38
	ds_read_b32 v43, v39
	s_waitcnt lgkmcnt(6)
	v_add_f32_e32 v38, v16, v32
	v_add_f32_e32 v39, v17, v33
	s_waitcnt lgkmcnt(4)
	v_add_f32_e32 v36, v18, v34
	v_add_f32_e32 v37, v19, v35
	v_max3_f32 v16, v165, v38, v39
	v_max3_f32 v16, v16, v36, v37
	s_waitcnt lgkmcnt(2)
	v_add_f32_e32 v32, v20, v40
	v_add_f32_e32 v33, v21, v41
	s_waitcnt lgkmcnt(0)
	v_add_f32_e32 v34, v22, v42
	v_add_f32_e32 v35, v23, v43
	v_max3_f32 v16, v16, v32, v33
	v_max3_f32 v40, v16, v34, v35
	v_add_u32_e32 v16, s20, v121
	v_add_u32_e32 v17, s20, v120
	v_add_u32_e32 v18, s20, v119
	v_add_u32_e32 v19, s20, v118
	v_add_u32_e32 v20, s20, v117
	v_add_u32_e32 v21, s20, v116
	v_add_u32_e32 v22, s20, v115
	v_add_u32_e32 v23, s20, v114
	ds_read_b32 v16, v16
	ds_read_b32 v17, v17
	ds_read_b32 v18, v18
	ds_read_b32 v19, v19
	ds_read_b32 v20, v20
	ds_read_b32 v21, v21
	ds_read_b32 v22, v22
	ds_read_b32 v23, v23
	s_waitcnt lgkmcnt(6)
	v_add_f32_e32 v44, v24, v16
	v_add_f32_e32 v45, v25, v17
	s_waitcnt lgkmcnt(4)
	v_add_f32_e32 v46, v26, v18
	v_add_f32_e32 v47, v27, v19
	v_max3_f32 v16, v40, v44, v45
	v_max3_f32 v16, v16, v46, v47
	s_waitcnt lgkmcnt(2)
	v_add_f32_e32 v42, v28, v20
	v_add_f32_e32 v43, v29, v21
	s_waitcnt lgkmcnt(0)
	v_add_f32_e32 v40, v30, v22
	v_add_f32_e32 v41, v31, v23
	v_max3_f32 v16, v16, v42, v43
	v_max3_f32 v165, v16, v40, v41
	v_mov_b32_e32 v164, v165
	s_cmpk_lt_i32 s0, 0x88f
	s_mov_b64 s[4:5], -1
	s_cbranch_scc1 .LBB0_537
	s_branch .LBB0_528

.LBB0_538:
	s_cmpk_lt_i32 s0, 0x600
	v_mov_b32_e32 v25, 0xf149f2ca
	s_cbranch_scc1 .LBB0_540
	v_add_u32_e32 v16, s20, v113
	v_add_u32_e32 v17, s20, v112
	v_add_u32_e32 v18, s20, v111
	v_add_u32_e32 v19, s20, v110
	v_add_u32_e32 v20, s20, v109
	v_add_u32_e32 v21, s20, v108
	v_add_u32_e32 v22, s20, v107
	v_add_u32_e32 v23, s20, v106
	ds_read_b32 v16, v16
	ds_read_b32 v17, v17
	ds_read_b32 v18, v18
	ds_read_b32 v19, v19
	ds_read_b32 v24, v20
	ds_read_b32 v25, v21
	ds_read_b32 v26, v22
	ds_read_b32 v27, v23
	s_waitcnt lgkmcnt(6)
	v_add_f32_e32 v22, v0, v16
	v_add_f32_e32 v23, v1, v17
	s_waitcnt lgkmcnt(4)
	v_add_f32_e32 v20, v2, v18
	v_add_f32_e32 v21, v3, v19
	v_max3_f32 v0, v164, v22, v23
	v_max3_f32 v0, v0, v20, v21
	s_waitcnt lgkmcnt(2)
	v_add_f32_e32 v16, v4, v24
	v_add_f32_e32 v17, v5, v25
	s_waitcnt lgkmcnt(0)
	v_add_f32_e32 v18, v6, v26
	v_add_f32_e32 v19, v7, v27
	v_max3_f32 v0, v0, v16, v17
	v_max3_f32 v24, v0, v18, v19
	v_add_u32_e32 v0, s20, v105
	v_add_u32_e32 v1, s20, v104
	v_add_u32_e32 v2, s20, v103
	v_add_u32_e32 v3, s20, v102
	v_add_u32_e32 v4, s20, v101
	v_add_u32_e32 v5, s20, v100
	v_add_u32_e32 v6, s20, v99
	v_add_u32_e32 v7, s20, v98
	ds_read_b32 v0, v0
	ds_read_b32 v1, v1
	ds_read_b32 v2, v2
	ds_read_b32 v3, v3
	ds_read_b32 v4, v4
	ds_read_b32 v5, v5
	ds_read_b32 v6, v6
	ds_read_b32 v7, v7
	s_waitcnt lgkmcnt(6)
	v_add_f32_e32 v28, v8, v0
	v_add_f32_e32 v29, v9, v1
	s_waitcnt lgkmcnt(4)
	v_add_f32_e32 v30, v10, v2
	v_add_f32_e32 v31, v11, v3
	v_max3_f32 v0, v24, v28, v29
	v_max3_f32 v0, v0, v30, v31
	s_waitcnt lgkmcnt(2)
	v_add_f32_e32 v26, v12, v4
	v_add_f32_e32 v27, v13, v5
	s_waitcnt lgkmcnt(0)
	v_add_f32_e32 v24, v14, v6
	v_add_f32_e32 v25, v15, v7
	v_max3_f32 v0, v0, v26, v27
	v_max3_f32 v164, v0, v24, v25
	s_branch .LBB0_541

.LBB0_556:
	v_fma_f32 v64, v64, s20, -v197
	v_exp_f32_e32 v131, v64
	v_fma_f32 v64, v113, s20, -v170
	v_fma_f32 v96, v96, s20, -v197
	v_exp_f32_e32 v113, v64
	v_fma_f32 v64, v97, s20, -v197
	v_fma_f32 v112, v112, s20, -v170
	v_exp_f32_e32 v130, v96
	v_exp_f32_e32 v96, v64
	v_fma_f32 v64, v81, s20, -v170
	v_fma_f32 v66, v66, s20, -v197
	v_exp_f32_e32 v129, v112
	v_exp_f32_e32 v112, v64
	v_fma_f32 v64, v65, s20, -v197
	v_exp_f32_e32 v133, v66
	v_fma_f32 v66, v115, s20, -v170
	v_exp_f32_e32 v97, v64
	v_fma_f32 v64, v114, s20, -v170
	v_exp_f32_e32 v81, v66
	v_fma_f32 v66, v99, s20, -v197
	v_fma_f32 v80, v80, s20, -v170
	v_exp_f32_e32 v65, v64
	v_fma_f32 v64, v98, s20, -v197
	v_exp_f32_e32 v98, v66
	v_fma_f32 v66, v83, s20, -v170
	v_fma_f32 v68, v68, s20, -v197
	v_exp_f32_e32 v128, v80
	v_exp_f32_e32 v80, v66
	v_fma_f32 v66, v67, s20, -v197
	v_exp_f32_e32 v115, v68
	v_fma_f32 v68, v117, s20, -v170
	v_exp_f32_e32 v99, v66
	v_fma_f32 v66, v116, s20, -v170
	v_exp_f32_e32 v83, v68
	v_fma_f32 v68, v101, s20, -v197
	v_exp_f32_e32 v67, v66
	v_fma_f32 v66, v100, s20, -v197
	v_exp_f32_e32 v100, v68
	v_fma_f32 v68, v85, s20, -v170
	v_exp_f32_e32 v132, v64
	v_fma_f32 v64, v82, s20, -v170
	v_exp_f32_e32 v82, v68
	v_fma_f32 v68, v69, s20, -v197
	v_exp_f32_e32 v114, v66
	v_fma_f32 v66, v84, s20, -v170
	v_exp_f32_e32 v101, v68
	v_fma_f32 v68, v118, s20, -v170
	v_fma_f32 v84, v119, s20, -v170
	v_exp_f32_e32 v69, v68
	v_fma_f32 v68, v102, s20, -v197
	v_exp_f32_e32 v85, v84
	v_fma_f32 v84, v103, s20, -v197
	v_exp_f32_e32 v116, v68
	v_fma_f32 v68, v86, s20, -v170
	v_exp_f32_e32 v86, v84
	v_fma_f32 v84, v120, s20, -v170
	v_exp_f32_e32 v103, v84
	v_fma_f32 v84, v104, s20, -v197
	v_exp_f32_e32 v120, v84
	v_fma_f32 v84, v121, s20, -v170
	v_exp_f32_e32 v119, v84
	v_fma_f32 v84, v105, s20, -v197
	v_exp_f32_e32 v134, v84
	v_fma_f32 v84, v122, s20, -v170
	v_exp_f32_e32 v105, v84
	v_fma_f32 v84, v106, s20, -v197
	v_exp_f32_e32 v106, v84
	v_fma_f32 v84, v123, s20, -v170
	v_exp_f32_e32 v153, v84
	v_fma_f32 v84, v107, s20, -v197
	v_cvt_pk_bf16_f32 v136, v129, v113
	v_cvt_pk_bf16_f32 v137, v65, v81
	v_cvt_pk_bf16_f32 v138, v67, v83
	v_cvt_pk_bf16_f32 v139, v69, v85
	v_cvt_pk_bf16_f32 v140, v130, v96
	v_cvt_pk_bf16_f32 v141, v132, v98
	v_cvt_pk_bf16_f32 v142, v114, v100
	v_cvt_pk_bf16_f32 v143, v116, v86
	ds_read_b64_tr_b16 v[144:145], v179 offset:30720
	ds_read_b64_tr_b16 v[146:147], v179 offset:32256
	v_exp_f32_e32 v154, v84
	v_fma_f32 v84, v124, s20, -v170
	v_exp_f32_e32 v157, v84
	v_fma_f32 v84, v108, s20, -v197
	v_exp_f32_e32 v158, v84
	v_fma_f32 v84, v125, s20, -v170
	v_exp_f32_e32 v161, v84
	v_fma_f32 v84, v109, s20, -v197
	v_exp_f32_e32 v162, v84
	v_fma_f32 v84, v126, s20, -v170
	s_waitcnt lgkmcnt(0)
	v_mfma_f32_32x32x16_bf16 v[48:63], v[144:147], v[136:139], v[48:63]
	v_fma_f32 v70, v70, s20, -v197
	v_exp_f32_e32 v117, v70
	v_fma_f32 v70, v87, s20, -v170
	ds_read_b64_tr_b16 v[150:151], v179 offset:32320
	ds_read_b64_tr_b16 v[148:149], v179 offset:30784
	v_exp_f32_e32 v64, v64
	v_exp_f32_e32 v66, v66
	v_exp_f32_e32 v68, v68
	v_mfma_f32_32x32x16_bf16 v[0:15], v[144:147], v[140:143], v[0:15]
	v_exp_f32_e32 v145, v84
	v_fma_f32 v84, v110, s20, -v197
	v_exp_f32_e32 v126, v84
	v_fma_f32 v84, v127, s20, -v170
	v_exp_f32_e32 v147, v84
	v_fma_f32 v84, v111, s20, -v197
	v_exp_f32_e32 v164, v84
	v_exp_f32_e32 v84, v70
	v_fma_f32 v70, v71, s20, -v197
	v_exp_f32_e32 v87, v70
	v_fma_f32 v70, v88, s20, -v170
	v_exp_f32_e32 v102, v70
	v_fma_f32 v70, v72, s20, -v197
	v_exp_f32_e32 v121, v70
	v_fma_f32 v70, v89, s20, -v170
	v_exp_f32_e32 v118, v70
	v_fma_f32 v70, v73, s20, -v197
	v_exp_f32_e32 v135, v70
	v_fma_f32 v70, v90, s20, -v170
	v_exp_f32_e32 v104, v70
	v_fma_f32 v70, v74, s20, -v197
	v_fma_f32 v74, v91, s20, -v170
	v_exp_f32_e32 v152, v74
	v_fma_f32 v74, v75, s20, -v197
	v_exp_f32_e32 v155, v74
	v_fma_f32 v74, v92, s20, -v170
	v_exp_f32_e32 v156, v74
	v_fma_f32 v74, v76, s20, -v197
	v_exp_f32_e32 v159, v74
	v_fma_f32 v74, v93, s20, -v170
	v_exp_f32_e32 v160, v74
	v_fma_f32 v74, v77, s20, -v197
	v_exp_f32_e32 v163, v74
	v_fma_f32 v74, v94, s20, -v170
	v_exp_f32_e32 v144, v74
	v_fma_f32 v74, v78, s20, -v197
	v_exp_f32_e32 v127, v74
	v_fma_f32 v74, v95, s20, -v170
	v_exp_f32_e32 v146, v74
	v_fma_f32 v74, v79, s20, -v197
	v_add_f32_e32 v78, 0, v130
	v_add_f32_e32 v79, 0, v131
	s_waitcnt lgkmcnt(0)
	v_mfma_f32_32x32x16_bf16 v[32:47], v[148:151], v[136:139], v[32:47]
	v_add_f32_e64 v78, v96, v78
	v_add_f32_e64 v79, v97, v79
	v_cvt_pk_bf16_f32 v108, v103, v119
	v_cvt_pk_bf16_f32 v109, v105, v153
	v_cvt_pk_bf16_f32 v110, v157, v161
	v_cvt_pk_bf16_f32 v111, v145, v147
	v_cvt_pk_bf16_f32 v122, v120, v134
	v_add_f32_e64 v78, v132, v78
	v_add_f32_e64 v79, v133, v79
	v_cvt_pk_bf16_f32 v123, v106, v154
	v_cvt_pk_bf16_f32 v124, v158, v162
	v_cvt_pk_bf16_f32 v125, v126, v164
	ds_read_b64_tr_b16 v[136:137], v179 offset:33792
	ds_read_b64_tr_b16 v[138:139], v179 offset:35328
	v_add_f32_e32 v78, v98, v78
	v_add_f32_e32 v79, v99, v79
	v_mfma_f32_32x32x16_bf16 v[16:31], v[148:151], v[140:143], v[16:31]
	v_add_f32_e64 v78, v114, v78
	v_add_f32_e64 v79, v115, v79
	ds_read_b64_tr_b16 v[142:143], v179 offset:35392
	ds_read_b64_tr_b16 v[140:141], v179 offset:33856
	v_add_f32_e64 v78, v100, v78
	v_add_f32_e64 v79, v101, v79
	v_exp_f32_e32 v107, v70
	v_add_f32_e32 v78, v116, v78
	v_add_f32_e32 v79, v117, v79
	v_cvt_pk_bf16_f32 v70, v128, v112
	v_cvt_pk_bf16_f32 v71, v64, v80
	v_cvt_pk_bf16_f32 v72, v66, v82
	v_cvt_pk_bf16_f32 v73, v68, v84
	v_cvt_pk_bf16_f32 v88, v131, v97
	v_cvt_pk_bf16_f32 v89, v133, v99
	v_cvt_pk_bf16_f32 v90, v115, v101
	v_cvt_pk_bf16_f32 v91, v117, v87
	s_nop 0
	v_add_f32_e32 v78, v86, v78
	v_add_f32_e32 v79, v87, v79
	v_add_f32_e32 v86, 0, v128
	v_add_f32_e32 v87, 0, v129
	s_waitcnt lgkmcnt(0)
	v_mfma_f32_32x32x16_bf16 v[32:47], v[140:143], v[108:111], v[32:47]
	v_add_f32_e64 v86, v112, v86
	v_add_f32_e64 v87, v113, v87
	v_add_f32_e64 v78, v120, v78
	v_add_f32_e64 v79, v121, v79
	v_add_f32_e64 v64, v64, v86
	v_add_f32_e64 v65, v65, v87
	v_add_f32_e32 v78, v134, v78
	v_add_f32_e32 v79, v135, v79
	v_add_f32_e32 v64, v80, v64
	v_add_f32_e32 v65, v81, v65
	v_add_f32_e32 v78, v106, v78
	v_add_f32_e32 v79, v107, v79
	v_add_f32_e32 v64, v66, v64
	v_add_f32_e32 v65, v67, v65
	v_mfma_f32_32x32x16_bf16 v[48:63], v[136:139], v[108:111], v[48:63]
	v_add_f32_e64 v64, v82, v64
	v_add_f32_e64 v65, v83, v65
	ds_read_b64_tr_b16 v[108:109], v179 offset:36864
	ds_read_b64_tr_b16 v[110:111], v179 offset:38400
	v_add_f32_e64 v64, v68, v64
	v_add_f32_e64 v65, v69, v65
	v_exp_f32_e32 v165, v74
	v_add_f32_e32 v64, v84, v64
	v_add_f32_e32 v65, v85, v65
	v_add_f32_e32 v78, v154, v78
	v_add_f32_e32 v79, v155, v79
	v_add_f32_e32 v64, v102, v64
	v_add_f32_e32 v65, v103, v65
	v_mfma_f32_32x32x16_bf16 v[0:15], v[136:139], v[122:125], v[0:15]
	v_add_f32_e64 v64, v118, v64
	v_add_f32_e64 v65, v119, v65
	v_add_f32_e64 v78, v158, v78
	v_add_f32_e64 v79, v159, v79
	v_add_f32_e64 v64, v104, v64
	v_add_f32_e64 v65, v105, v65
	v_add_f32_e32 v78, v162, v78
	v_add_f32_e32 v79, v163, v79
	v_add_f32_e32 v64, v152, v64
	v_add_f32_e32 v65, v153, v65
	v_add_f32_e32 v78, v126, v78
	v_add_f32_e32 v79, v127, v79
	v_add_f32_e32 v64, v156, v64
	v_add_f32_e32 v65, v157, v65
	v_mfma_f32_32x32x16_bf16 v[16:31], v[140:143], v[122:125], v[16:31]
	v_add_f32_e64 v64, v160, v64
	v_add_f32_e64 v65, v161, v65
	ds_read_b64_tr_b16 v[124:125], v179 offset:38464
	ds_read_b64_tr_b16 v[122:123], v179 offset:36928
	v_add_f32_e64 v64, v144, v64
	v_add_f32_e64 v65, v145, v65
	s_lshl_b32 s6, s34, 1
	v_add_f32_e32 v64, v146, v64
	v_add_f32_e32 v65, v147, v65
	v_lshlrev_b32_e32 v170, 3, v195
	v_add_f32_e32 v64, v64, v65
	v_add_f32_e32 v66, v175, v64
	ds_bpermute_b32 v67, v196, v66
	s_waitcnt lgkmcnt(1)
	v_mfma_f32_32x32x16_bf16 v[32:47], v[122:125], v[70:73], v[32:47]
	v_add_f32_e64 v64, v164, v78
	v_add_f32_e64 v65, v165, v79
	s_add_i32 s17, s17, s30
	v_add_f32_e32 v64, v64, v65
	s_waitcnt lgkmcnt(0)
	v_add_f32_e32 v65, v66, v67
	v_max_f32_e32 v65, 0xda24260, v65
	v_div_scale_f32 v66, s[0:1], v65, v65, 1.0
	v_mfma_f32_32x32x16_bf16 v[48:63], v[108:111], v[70:73], v[48:63]
	v_cvt_pk_bf16_f32 v70, v102, v118
	v_cvt_pk_bf16_f32 v71, v104, v152
	v_cvt_pk_bf16_f32 v72, v156, v160
	v_cvt_pk_bf16_f32 v73, v144, v146
	v_cvt_pk_bf16_f32 v74, v121, v135
	v_cvt_pk_bf16_f32 v75, v107, v155
	v_cvt_pk_bf16_f32 v76, v159, v163
	v_mfma_f32_32x32x16_bf16 v[0:15], v[108:111], v[88:91], v[0:15]
	v_cvt_pk_bf16_f32 v77, v127, v165
	ds_read_b64_tr_b16 v[92:93], v179 offset:39936
	ds_read_b64_tr_b16 v[94:95], v179 offset:41472
	v_rcp_f32_e32 v67, v66
	v_add_f32_e32 v64, v174, v64
	s_cmpk_lt_i32 s17, 0x200
	v_fma_f32 v68, -v66, v67, 1.0
	v_mfma_f32_32x32x16_bf16 v[16:31], v[122:125], v[88:91], v[16:31]
	ds_read_b64_tr_b16 v[90:91], v179 offset:41536
	ds_read_b64_tr_b16 v[88:89], v179 offset:40000
	v_fmac_f32_e32 v67, v68, v67
	v_div_scale_f32 v68, vcc, 1.0, v65, 1.0
	v_mul_f32_e32 v69, v68, v67
	s_waitcnt lgkmcnt(0)
	s_barrier
	v_mfma_f32_32x32x16_bf16 v[32:47], v[88:91], v[70:73], v[32:47]
	v_mfma_f32_32x32x16_bf16 v[48:63], v[92:95], v[70:73], v[48:63]
	v_fma_f32 v70, -v66, v69, v68
	v_fmac_f32_e32 v69, v70, v67
	v_fma_f32 v66, -v66, v69, v68
	v_div_fmas_f32 v66, v66, v67, v69
	v_div_fixup_f32 v65, v66, v65, 1.0
	s_nop 5
	v_mul_f32_e32 v66, v32, v65
	v_mul_f32_e32 v67, v33, v65
	v_lshlrev_b64 v[32:33], 11, v[172:173]
	v_mul_f32_e32 v68, v34, v65
	v_mul_f32_e32 v69, v35, v65
	v_lshl_add_u64 v[34:35], s[4:5], 0, v[32:33]
	v_lshl_add_u64 v[34:35], v[34:35], 0, s[6:7]
	v_mul_f32_e32 v48, v48, v65
	v_mul_f32_e32 v49, v49, v65
	v_mul_f32_e32 v50, v50, v65
	v_mul_f32_e32 v51, v51, v65
	v_mul_f32_e32 v70, v36, v65
	v_mul_f32_e32 v71, v37, v65
	v_mul_f32_e32 v72, v38, v65
	v_lshl_add_u64 v[34:35], v[34:35], 0, v[170:171]
	v_cvt_pk_bf16_f32 v232, v48, v49
	v_cvt_pk_bf16_f32 v233, v50, v51
	v_cvt_pk_bf16_f32 v240, v66, v67
	v_mul_f32_e32 v52, v52, v65
	v_mul_f32_e32 v53, v53, v65
	v_mul_f32_e32 v54, v54, v65
	v_mul_f32_e32 v55, v55, v65
	v_mul_f32_e32 v73, v39, v65
	v_mul_f32_e32 v40, v40, v65
	v_cvt_pk_bf16_f32 v241, v68, v69
	s_nop 0
	s_nop 0
	v_cvt_pk_bf16_f32 v234, v52, v53
	v_cvt_pk_bf16_f32 v235, v54, v55
	v_cvt_pk_bf16_f32 v242, v70, v71
	v_mul_f32_e32 v56, v56, v65
	v_mul_f32_e32 v57, v57, v65
	v_mul_f32_e32 v41, v41, v65
	v_mul_f32_e32 v58, v58, v65
	v_mul_f32_e32 v59, v59, v65
	v_cvt_pk_bf16_f32 v243, v72, v73
	v_and_b32_e32 v248, 32, v200
	v_lshrrev_b32_e32 v248, 2, v248
	v_mov_b32_e32 v249, 0
	v_lshl_add_u64 v[248:249], v[34:35], 0, v[248:249]
	v_permlane32_swap_b32_e32 v232, v234
	v_permlane32_swap_b32_e32 v233, v235
	global_store_dwordx4 v[248:249], v[232:235], off offset:1536
	s_nop 1
	v_permlane32_swap_b32_e32 v240, v242
	v_permlane32_swap_b32_e32 v241, v243
	global_store_dwordx4 v[248:249], v[240:243], off offset:1600
	v_cvt_pk_bf16_f32 v236, v56, v57
	v_cvt_pk_bf16_f32 v237, v58, v59
	v_cvt_pk_bf16_f32 v244, v40, v41
	ds_bpermute_b32 v40, v196, v64
	v_mul_f32_e32 v42, v42, v65
	v_mul_f32_e32 v43, v43, v65
	v_cvt_pk_bf16_f32 v245, v42, v43
	s_nop 0
	s_waitcnt lgkmcnt(0)
	v_add_f32_e32 v39, v64, v40
	v_max_f32_e32 v40, 0xda24260, v39
	v_div_scale_f32 v41, s[0:1], v40, v40, 1.0
	v_rcp_f32_e32 v42, v41
	v_mul_f32_e32 v60, v60, v65
	v_mul_f32_e32 v61, v61, v65
	v_mul_f32_e32 v62, v62, v65
	v_mul_f32_e32 v63, v63, v65
	s_nop 0
	v_cvt_pk_bf16_f32 v238, v60, v61
	v_cvt_pk_bf16_f32 v239, v62, v63
	v_mfma_f32_32x32x16_bf16 v[0:15], v[92:95], v[74:77], v[0:15]
	v_mul_f32_e32 v44, v44, v65
	v_mul_f32_e32 v45, v45, v65
	v_mul_f32_e32 v46, v46, v65
	v_mul_f32_e32 v47, v47, v65
	v_cvt_pk_bf16_f32 v246, v44, v45
	v_cvt_pk_bf16_f32 v247, v46, v47
	v_permlane32_swap_b32_e32 v236, v238
	v_permlane32_swap_b32_e32 v237, v239
	global_store_dwordx4 v[248:249], v[236:239], off offset:1568
	s_nop 1
	v_permlane32_swap_b32_e32 v244, v246
	v_permlane32_swap_b32_e32 v245, v247
	global_store_dwordx4 v[248:249], v[244:247], off offset:1632
	v_fma_f32 v34, -v41, v42, 1.0
	v_fmac_f32_e32 v42, v34, v42
	v_div_scale_f32 v34, vcc, 1.0, v40, 1.0
	v_mfma_f32_32x32x16_bf16 v[16:31], v[88:91], v[74:77], v[16:31]
	v_mul_f32_e32 v35, v34, v42
	v_fma_f32 v36, -v41, v35, v34
	v_fmac_f32_e32 v35, v36, v42
	v_fma_f32 v34, -v41, v35, v34
	v_div_fmas_f32 v34, v34, v42, v35
	v_div_fixup_f32 v34, v34, v40, 1.0
	v_or_b32_e32 v32, 0x10000, v32
	v_mul_f32_e32 v35, v0, v34
	v_mul_f32_e32 v36, v1, v34
	v_lshl_add_u64 v[0:1], s[4:5], 0, v[32:33]
	v_mul_f32_e32 v3, v3, v34
	v_lshl_add_u64 v[0:1], v[0:1], 0, s[6:7]
	v_mul_f32_e32 v16, v16, v34
	v_mul_f32_e32 v17, v17, v34
	v_mul_f32_e32 v37, v2, v34
	v_mul_f32_e32 v18, v18, v34
	v_mul_f32_e32 v19, v19, v34
	v_mul_f32_e32 v38, v4, v34
	v_mul_f32_e32 v39, v5, v34
	v_lshl_add_u64 v[0:1], v[0:1], 0, v[170:171]
	v_cvt_pk_bf16_f32 v232, v35, v36
	v_cvt_pk_bf16_f32 v233, v37, v3
	v_cvt_pk_bf16_f32 v240, v16, v17
	v_cvt_pk_bf16_f32 v241, v18, v19
	v_mul_f32_e32 v20, v20, v34
	v_mul_f32_e32 v21, v21, v34
	v_mul_f32_e32 v6, v6, v34
	v_mul_f32_e32 v22, v22, v34
	v_mul_f32_e32 v7, v7, v34
	v_mul_f32_e32 v23, v23, v34
	s_nop 0
	s_nop 0
	v_cvt_pk_bf16_f32 v234, v38, v39
	v_cvt_pk_bf16_f32 v235, v6, v7
	v_cvt_pk_bf16_f32 v242, v20, v21
	v_cvt_pk_bf16_f32 v243, v22, v23
	v_mul_f32_e32 v8, v8, v34
	v_mul_f32_e32 v24, v24, v34
	v_mul_f32_e32 v9, v9, v34
	v_mul_f32_e32 v25, v25, v34
	v_mul_f32_e32 v10, v10, v34
	v_mul_f32_e32 v26, v26, v34
	v_mul_f32_e32 v11, v11, v34
	v_mul_f32_e32 v27, v27, v34
	v_and_b32_e32 v248, 32, v200
	v_lshrrev_b32_e32 v248, 2, v248
	v_mov_b32_e32 v249, 0
	v_lshl_add_u64 v[248:249], v[0:1], 0, v[248:249]
	v_permlane32_swap_b32_e32 v232, v234
	v_permlane32_swap_b32_e32 v233, v235
	global_store_dwordx4 v[248:249], v[232:235], off offset:1536
	v_permlane32_swap_b32_e32 v240, v242
	v_permlane32_swap_b32_e32 v241, v243
	global_store_dwordx4 v[248:249], v[240:243], off offset:1600
	v_cvt_pk_bf16_f32 v236, v8, v9
	v_cvt_pk_bf16_f32 v237, v10, v11
	v_cvt_pk_bf16_f32 v244, v24, v25
	v_cvt_pk_bf16_f32 v245, v26, v27
	v_mul_f32_e32 v12, v12, v34
	v_mul_f32_e32 v28, v28, v34
	v_mul_f32_e32 v13, v13, v34
	v_mul_f32_e32 v29, v29, v34
	v_mul_f32_e32 v14, v14, v34
	v_mul_f32_e32 v30, v30, v34
	v_mul_f32_e32 v15, v15, v34
	v_mul_f32_e32 v31, v31, v34
	s_nop 0
	s_nop 0
	v_cvt_pk_bf16_f32 v238, v12, v13
	v_cvt_pk_bf16_f32 v239, v14, v15
	v_cvt_pk_bf16_f32 v246, v28, v29
	v_cvt_pk_bf16_f32 v247, v30, v31
	v_permlane32_swap_b32_e32 v236, v238
	v_permlane32_swap_b32_e32 v237, v239
	global_store_dwordx4 v[248:249], v[236:239], off offset:1568
	s_nop 1
	v_permlane32_swap_b32_e32 v244, v246
	v_permlane32_swap_b32_e32 v245, v247
	global_store_dwordx4 v[248:249], v[244:247], off offset:1632
	s_cbranch_scc0 .LBB0_563

.LBB0_558:
	v_mul_f32_e32 v170, 0x3e38aa3b, v202
	v_cmp_ngt_f32_e32 vcc, s19, v202
	v_mul_f32_e32 v182, 0x3e38aa3b, v201
	s_and_b64 s[2:3], s[10:11], exec
	v_cndmask_b32_e32 v170, 0, v170, vcc
	v_cmp_ngt_f32_e32 vcc, s19, v201
	v_fma_f32 v112, v112, s20, -v170
	v_exp_f32_e32 v183, v112
	v_cndmask_b32_e32 v197, 0, v182, vcc
	v_fma_f32 v64, v64, s20, -v197
	v_exp_f32_e32 v182, v64
	v_fma_f32 v64, v113, s20, -v170
	v_fma_f32 v96, v96, s20, -v197
	v_exp_f32_e32 v113, v64
	v_fma_f32 v64, v97, s20, -v197
	v_exp_f32_e32 v184, v96
	v_exp_f32_e32 v96, v64
	v_fma_f32 v64, v81, s20, -v170
	v_exp_f32_e32 v97, v64
	v_fma_f32 v64, v65, s20, -v197
	v_exp_f32_e32 v112, v64
	v_fma_f32 v64, v114, s20, -v170
	v_exp_f32_e32 v65, v64
	v_fma_f32 v64, v98, s20, -v197
	v_exp_f32_e32 v186, v64
	v_fma_f32 v64, v82, s20, -v170
	v_exp_f32_e32 v187, v64
	v_fma_f32 v64, v66, s20, -v197
	v_fma_f32 v66, v115, s20, -v170
	v_exp_f32_e32 v81, v66
	v_fma_f32 v66, v99, s20, -v197
	v_exp_f32_e32 v98, v66
	v_fma_f32 v66, v83, s20, -v170
	v_fma_f32 v80, v80, s20, -v170
	v_exp_f32_e32 v99, v66
	v_fma_f32 v66, v67, s20, -v197
	v_exp_f32_e32 v185, v80
	v_exp_f32_e32 v80, v66
	v_fma_f32 v66, v116, s20, -v170
	v_exp_f32_e32 v83, v66
	v_fma_f32 v66, v100, s20, -v197
	v_exp_f32_e32 v114, v66
	v_fma_f32 v66, v84, s20, -v170
	v_exp_f32_e32 v115, v66
	v_fma_f32 v66, v68, s20, -v197
	v_exp_f32_e32 v82, v66
	v_fma_f32 v66, v117, s20, -v170
	v_exp_f32_e32 v67, v66
	v_fma_f32 v66, v101, s20, -v197
	v_exp_f32_e32 v116, v66
	v_fma_f32 v66, v85, s20, -v170
	v_fma_f32 v68, v118, s20, -v170
	v_exp_f32_e32 v117, v66
	v_fma_f32 v66, v69, s20, -v197
	v_exp_f32_e32 v69, v68
	v_fma_f32 v68, v102, s20, -v197
	v_exp_f32_e32 v188, v68
	v_fma_f32 v68, v86, s20, -v170
	v_exp_f32_e32 v189, v68
	v_fma_f32 v68, v70, s20, -v197
	v_fma_f32 v70, v119, s20, -v170
	v_exp_f32_e32 v85, v70
	v_fma_f32 v70, v103, s20, -v197
	v_exp_f32_e32 v118, v70
	v_fma_f32 v70, v87, s20, -v170
	v_exp_f32_e32 v119, v70
	v_fma_f32 v70, v71, s20, -v197
	v_exp_f32_e32 v84, v70
	v_add_f32_e32 v70, 0, v184
	v_add_f32_e32 v71, 0, v185
	s_cselect_b32 s2, s21, 0x7800
	v_add_f32_e32 v190, v96, v70
	v_add_f32_e32 v191, v97, v71
	v_fma_f32 v70, v120, s20, -v170
	v_exp_f32_e32 v71, v70
	v_fma_f32 v70, v104, s20, -v197
	v_exp_f32_e32 v86, v70
	v_fma_f32 v70, v121, s20, -v170
	v_exp_f32_e32 v101, v70
	v_fma_f32 v70, v105, s20, -v197
	v_exp_f32_e32 v102, v70
	v_fma_f32 v70, v122, s20, -v170
	v_exp_f32_e32 v105, v70
	v_fma_f32 v70, v106, s20, -v197
	v_exp_f32_e32 v106, v70
	v_add_u32_e32 v203, s2, v179
	v_fma_f32 v70, v123, s20, -v170
	v_cvt_pk_bf16_f32 v204, v183, v113
	v_cvt_pk_bf16_f32 v205, v65, v81
	v_cvt_pk_bf16_f32 v206, v83, v67
	v_cvt_pk_bf16_f32 v207, v69, v85
	v_cvt_pk_bf16_f32 v208, v184, v96
	v_cvt_pk_bf16_f32 v209, v186, v98
	v_cvt_pk_bf16_f32 v210, v114, v116
	v_cvt_pk_bf16_f32 v211, v188, v118
	ds_read_b64_tr_b16 v[212:213], v203
	ds_read_b64_tr_b16 v[214:215], v203 offset:1536
	v_exp_f32_e32 v217, v70
	v_fma_f32 v70, v107, s20, -v197
	ds_read_b64_tr_b16 v[122:123], v203 offset:1600
	ds_read_b64_tr_b16 v[120:121], v203 offset:64
	v_exp_f32_e32 v184, v70
	v_fma_f32 v70, v124, s20, -v170
	v_exp_f32_e32 v219, v70
	v_fma_f32 v70, v108, s20, -v197
	v_exp_f32_e32 v220, v70
	v_fma_f32 v70, v125, s20, -v170
	v_exp_f32_e32 v223, v70
	v_fma_f32 v70, v109, s20, -v197
	v_exp_f32_e32 v224, v70
	v_fma_f32 v70, v126, s20, -v170
	s_waitcnt lgkmcnt(0)
	v_mfma_f32_32x32x16_bf16 v[32:47], v[120:123], v[204:207], v[32:47]
	v_cvt_pk_bf16_f32 v108, v71, v101
	v_cvt_pk_bf16_f32 v109, v105, v217
	v_exp_f32_e32 v64, v64
	v_exp_f32_e32 v66, v66
	v_exp_f32_e32 v68, v68
	v_fma_f32 v76, v76, s20, -v197
	v_exp_f32_e32 v218, v76
	v_mfma_f32_32x32x16_bf16 v[16:31], v[120:123], v[208:211], v[16:31]
	v_add_f32_e64 v120, v186, v190
	v_add_f32_e64 v121, v187, v191
	v_fma_f32 v76, v93, s20, -v170
	v_add_f32_e64 v120, v98, v120
	v_add_f32_e64 v121, v99, v121
	v_exp_f32_e32 v225, v76
	v_add_f32_e32 v120, v114, v120
	v_add_f32_e32 v121, v115, v121
	v_fma_f32 v76, v77, s20, -v197
	v_add_f32_e32 v120, v116, v120
	v_add_f32_e32 v121, v117, v121
	v_mfma_f32_32x32x16_bf16 v[48:63], v[212:215], v[204:207], v[48:63]
	v_add_f32_e64 v190, v188, v120
	v_add_f32_e64 v191, v189, v121
	v_exp_f32_e32 v222, v76
	v_fma_f32 v76, v94, s20, -v170
	v_add_f32_e32 v190, v118, v190
	v_add_f32_e32 v191, v119, v191
	s_cselect_b32 s2, 0x7800, s21
	v_mfma_f32_32x32x16_bf16 v[0:15], v[212:215], v[208:211], v[0:15]
	v_exp_f32_e32 v213, v70
	v_fma_f32 v70, v110, s20, -v197
	v_exp_f32_e32 v214, v70
	v_fma_f32 v70, v127, s20, -v170
	v_exp_f32_e32 v227, v70
	v_fma_f32 v70, v111, s20, -v197
	v_exp_f32_e32 v228, v70
	v_cvt_pk_bf16_f32 v110, v219, v223
	v_cvt_pk_bf16_f32 v111, v213, v227
	v_cvt_pk_bf16_f32 v124, v86, v102
	v_cvt_pk_bf16_f32 v125, v106, v184
	v_cvt_pk_bf16_f32 v126, v220, v224
	v_cvt_pk_bf16_f32 v127, v214, v228
	ds_read_b64_tr_b16 v[204:205], v203 offset:3072
	ds_read_b64_tr_b16 v[206:207], v203 offset:4608
	ds_read_b64_tr_b16 v[122:123], v203 offset:4672
	ds_read_b64_tr_b16 v[120:121], v203 offset:3136
	v_fma_f32 v70, v88, s20, -v170
	v_exp_f32_e32 v87, v70
	v_fma_f32 v70, v72, s20, -v197
	v_fma_f32 v72, v89, s20, -v170
	v_exp_f32_e32 v103, v72
	v_fma_f32 v72, v73, s20, -v197
	v_exp_f32_e32 v100, v72
	v_fma_f32 v72, v90, s20, -v170
	v_exp_f32_e32 v107, v72
	v_fma_f32 v72, v74, s20, -v197
	v_exp_f32_e32 v104, v72
	v_fma_f32 v72, v91, s20, -v170
	s_waitcnt lgkmcnt(0)
	v_mfma_f32_32x32x16_bf16 v[32:47], v[120:123], v[108:111], v[32:47]
	v_cvt_pk_bf16_f32 v88, v185, v97
	v_exp_f32_e32 v185, v72
	v_fma_f32 v72, v75, s20, -v197
	v_exp_f32_e32 v216, v72
	v_fma_f32 v72, v92, s20, -v170
	v_cvt_pk_bf16_f32 v89, v187, v99
	v_cvt_pk_bf16_f32 v90, v115, v117
	v_mfma_f32_32x32x16_bf16 v[16:31], v[120:123], v[124:127], v[16:31]
	v_cvt_pk_bf16_f32 v91, v189, v119
	v_cvt_pk_bf16_f32 v96, v182, v112
	v_cvt_pk_bf16_f32 v97, v64, v80
	v_cvt_pk_bf16_f32 v98, v82, v66
	v_cvt_pk_bf16_f32 v99, v68, v84
	v_exp_f32_e32 v221, v72
	v_exp_f32_e32 v215, v76
	v_mfma_f32_32x32x16_bf16 v[48:63], v[204:207], v[108:111], v[48:63]
	ds_read_b64_tr_b16 v[108:109], v203 offset:6144
	ds_read_b64_tr_b16 v[110:111], v203 offset:7680
	ds_read_b64_tr_b16 v[74:75], v203 offset:7744
	ds_read_b64_tr_b16 v[72:73], v203 offset:6208
	v_fma_f32 v76, v78, s20, -v197
	v_exp_f32_e32 v70, v70
	v_exp_f32_e32 v212, v76
	v_fma_f32 v76, v95, s20, -v170
	v_exp_f32_e32 v229, v76
	v_mfma_f32_32x32x16_bf16 v[0:15], v[204:207], v[124:127], v[0:15]
	v_fma_f32 v76, v79, s20, -v197
	v_exp_f32_e32 v226, v76
	v_cvt_pk_bf16_f32 v76, v87, v103
	v_cvt_pk_bf16_f32 v77, v107, v185
	v_cvt_pk_bf16_f32 v78, v221, v225
	v_cvt_pk_bf16_f32 v79, v215, v229
	s_waitcnt lgkmcnt(0)
	v_mfma_f32_32x32x16_bf16 v[32:47], v[72:75], v[88:91], v[32:47]
	v_mfma_f32_32x32x16_bf16 v[16:31], v[72:75], v[96:99], v[16:31]
	v_add_f32_e64 v72, v182, 0
	v_add_f32_e64 v73, v183, 0
	v_add_f32_e64 v72, v112, v72
	v_add_f32_e64 v73, v113, v73
	v_add_f32_e64 v64, v64, v72
	v_add_f32_e64 v65, v65, v73
	v_add_f32_e32 v64, v80, v64
	v_add_f32_e32 v65, v81, v65
	v_mfma_f32_32x32x16_bf16 v[48:63], v[108:111], v[88:91], v[48:63]
	v_add_f32_e64 v64, v82, v64
	v_add_f32_e64 v65, v83, v65
	v_cvt_pk_bf16_f32 v88, v70, v100
	v_cvt_pk_bf16_f32 v89, v104, v216
	v_cvt_pk_bf16_f32 v90, v218, v222
	v_cvt_pk_bf16_f32 v91, v212, v226
	ds_read_b64_tr_b16 v[92:93], v203 offset:9216
	ds_read_b64_tr_b16 v[94:95], v203 offset:10752
	v_add_f32_e64 v64, v66, v64
	v_add_f32_e64 v65, v67, v65
	v_mfma_f32_32x32x16_bf16 v[0:15], v[108:111], v[96:99], v[0:15]
	ds_read_b64_tr_b16 v[74:75], v203 offset:10816
	ds_read_b64_tr_b16 v[72:73], v203 offset:9280
	v_add_f32_e64 v64, v68, v64
	v_add_f32_e64 v65, v69, v65
	v_add_f32_e64 v66, v86, v190
	v_add_f32_e64 v67, v87, v191
	v_add_f32_e32 v64, v84, v64
	v_add_f32_e32 v65, v85, v65
	v_add_f32_e32 v66, v102, v66
	v_add_f32_e32 v67, v103, v67
	v_add_f32_e32 v64, v70, v64
	v_add_f32_e32 v65, v71, v65
	v_add_f32_e32 v66, v106, v66
	v_add_f32_e32 v67, v107, v67
	v_add_f32_e32 v64, v100, v64
	v_add_f32_e32 v65, v101, v65
	s_waitcnt lgkmcnt(2)
	v_mfma_f32_32x32x16_bf16 v[48:63], v[92:95], v[76:79], v[48:63]
	v_add_f32_e64 v64, v104, v64
	v_add_f32_e64 v65, v105, v65
	v_add_f32_e64 v66, v184, v66
	v_add_f32_e64 v67, v185, v67
	v_add_f32_e64 v64, v216, v64
	v_add_f32_e64 v65, v217, v65
	v_add_f32_e32 v66, v220, v66
	v_add_f32_e32 v67, v221, v67
	v_add_f32_e32 v64, v218, v64
	v_add_f32_e32 v65, v219, v65
	v_add_f32_e32 v66, v224, v66
	v_add_f32_e32 v67, v225, v67
	v_add_f32_e32 v64, v222, v64
	v_add_f32_e32 v65, v223, v65
	v_mfma_f32_32x32x16_bf16 v[0:15], v[92:95], v[88:91], v[0:15]
	v_add_f32_e64 v66, v214, v66
	v_add_f32_e64 v67, v215, v67
	v_add_f32_e64 v64, v212, v64
	v_add_f32_e64 v65, v213, v65
	v_add_f32_e64 v66, v228, v66
	v_add_f32_e64 v67, v229, v67
	v_add_f32_e32 v64, v226, v64
	v_add_f32_e32 v65, v227, v65
	s_nop 0
	v_add_f32_e32 v64, v66, v64
	v_add_f32_e32 v65, v67, v65
	s_waitcnt lgkmcnt(0)
	v_mfma_f32_32x32x16_bf16 v[32:47], v[72:75], v[76:79], v[32:47]
	v_add_f32_e64 v174, v174, v64
	v_add_f32_e64 v175, v175, v65
	v_add_u32_e32 v64, s2, v178
	s_cselect_b32 s2, 0x2400, 0
	s_xor_b32 s1, s1, 1
	s_add_i32 s0, s0, 64
	v_add_u32_e32 v65, s2, v176
	s_cmpk_lg_i32 s0, 0x100
	v_mfma_f32_32x32x16_bf16 v[16:31], v[72:75], v[88:91], v[16:31]
	s_waitcnt vmcnt(1)
	ds_write_b128 v65, v[160:163]
	s_waitcnt vmcnt(0)
	ds_write_b128 v64, v[164:167]
	s_waitcnt lgkmcnt(0)
	s_barrier
	s_cbranch_scc0 .LBB0_561
.LBB0_559:
	s_cmp_eq_u32 s1, 0
	s_cselect_b64 s[10:11], -1, 0
	s_and_b64 s[2:3], s[10:11], exec
	s_cselect_b32 s2, 0, 0x2400
	v_add_u32_e32 v170, s2, v199
	ds_read_b128 v[64:67], v170
	ds_read_b128 v[160:163], v170 offset:32
	s_waitcnt lgkmcnt(1)
	v_mfma_f32_32x32x16_bf16 v[112:127], v[64:67], v[152:155], 0
	v_mfma_f32_32x32x16_bf16 v[96:111], v[64:67], v[156:159], 0
	ds_read_b128 v[64:67], v170 offset:4608
	ds_read_b128 v[164:167], v170 offset:4640
	ds_read_b128 v[182:185], v170 offset:64
	ds_read_b128 v[186:189], v170 offset:96
	ds_read_b128 v[204:207], v170 offset:4672
	ds_read_b128 v[208:211], v170 offset:4704
	s_waitcnt lgkmcnt(5)
	v_mfma_f32_32x32x16_bf16 v[80:95], v[64:67], v[152:155], 0
	v_mfma_f32_32x32x16_bf16 v[64:79], v[64:67], v[156:159], 0
	v_mfma_f32_32x32x16_bf16 v[112:127], v[160:163], v[144:147], v[112:127]
	v_mfma_f32_32x32x16_bf16 v[96:111], v[160:163], v[148:151], v[96:111]
	v_add_u32_e32 v160, s0, v198
	v_med3_i32 v160, v160, 0, v177
	v_lshlrev_b32_e32 v170, 11, v160
	s_waitcnt lgkmcnt(4)
	v_mfma_f32_32x32x16_bf16 v[80:95], v[164:167], v[144:147], v[80:95]
	v_mfma_f32_32x32x16_bf16 v[64:79], v[164:167], v[148:151], v[64:79]
	v_lshl_add_u64 v[164:165], v[180:181], 0, v[170:171]
	global_load_dwordx4 v[160:163], v[164:165], off
	s_nop 0
	global_load_dwordx4 v[164:167], v[164:165], off offset:512
	s_waitcnt lgkmcnt(3)
	v_mfma_f32_32x32x16_bf16 v[112:127], v[182:185], v[140:143], v[112:127]
	s_waitcnt lgkmcnt(1)
	v_mfma_f32_32x32x16_bf16 v[80:95], v[204:207], v[140:143], v[80:95]
	v_mfma_f32_32x32x16_bf16 v[96:111], v[182:185], v[132:135], v[96:111]
	v_mfma_f32_32x32x16_bf16 v[64:79], v[204:207], v[132:135], v[64:79]
	v_mfma_f32_32x32x16_bf16 v[112:127], v[186:189], v[136:139], v[112:127]
	s_waitcnt lgkmcnt(0)
	v_mfma_f32_32x32x16_bf16 v[80:95], v[208:211], v[136:139], v[80:95]
	s_nop 9
	v_max_f32_e32 v183, v113, v113
	v_max_f32_e32 v184, v115, v115
	v_max_f32_e32 v190, v112, v112
	v_mfma_f32_32x32x16_bf16 v[64:79], v[208:211], v[128:131], v[64:79]
	v_max_f32_e32 v182, v81, v81
	v_max_f32_e32 v182, v183, v182
	v_max_f32_e32 v183, v83, v83
	v_max_f32_e32 v170, v80, v80
	v_max_f32_e32 v183, v184, v183
	v_max_f32_e32 v170, v190, v170
	v_max3_f32 v184, v114, v82, v118
	v_mfma_f32_32x32x16_bf16 v[96:111], v[186:189], v[128:131], v[96:111]
	v_max3_f32 v183, v183, v119, v87
	v_max3_f32 v170, v170, v116, v84
	v_max3_f32 v182, v182, v117, v85
	v_max3_f32 v184, v184, v86, v122
	v_max3_f32 v183, v183, v123, v91
	v_max3_f32 v170, v170, v120, v88
	v_max3_f32 v182, v182, v121, v89
	v_max3_f32 v184, v184, v90, v126
	v_max3_f32 v183, v183, v127, v95
	v_max3_f32 v170, v170, v124, v92
	v_max3_f32 v182, v182, v125, v93
	v_max3_f32 v183, v184, v94, v183
	v_max3_f32 v170, v170, v182, v183
	v_max_f32_e32 v182, v64, v64
	v_max_f32_e32 v183, v96, v96
	v_max_f32_e32 v182, v183, v182
	v_max_f32_e32 v183, v65, v65
	v_max_f32_e32 v184, v97, v97
	v_max_f32_e32 v183, v184, v183
	v_max_f32_e32 v184, v67, v67
	v_max_f32_e32 v185, v99, v99
	v_max_f32_e32 v184, v185, v184
	v_max3_f32 v185, v98, v66, v102
	v_max3_f32 v184, v184, v103, v71
	v_max3_f32 v182, v182, v100, v68
	v_max3_f32 v183, v183, v101, v69
	v_max3_f32 v185, v185, v70, v106
	v_max3_f32 v184, v184, v107, v75
	v_max3_f32 v182, v182, v104, v72
	v_max3_f32 v183, v183, v105, v73
	v_max3_f32 v185, v185, v74, v110
	v_max3_f32 v184, v184, v111, v79
	v_max3_f32 v182, v182, v108, v76
	v_max3_f32 v183, v183, v109, v77
	v_max3_f32 v184, v185, v78, v184
	ds_bpermute_b32 v185, v196, v170
	v_max3_f32 v183, v182, v183, v184
	ds_bpermute_b32 v184, v196, v183
	s_waitcnt lgkmcnt(1)
	v_max_f32_e32 v182, v185, v185
	v_max_f32_e32 v182, v170, v182
	s_waitcnt lgkmcnt(0)
	v_max_f32_e32 v170, v184, v184
	v_max_f32_e32 v170, v183, v170
	v_add_f32_e32 v183, 0x42317218, v202
	v_cmp_gt_f32_e32 vcc, v182, v183
	v_add_f32_e32 v183, 0x42317218, v201
	v_cmp_gt_f32_e64 s[2:3], v170, v183
	s_or_b64 vcc, vcc, s[2:3]
	s_cbranch_vccz .LBB0_558
	v_max_f32_e32 v182, v182, v182
	v_max_f32_e32 v183, v202, v202
	v_max_f32_e32 v184, v183, v182
	v_max_f32_e32 v170, v170, v170
	v_max_f32_e32 v182, v201, v201
	v_cmp_ngt_f32_e32 vcc, s19, v184
	v_max_f32_e32 v185, v182, v170
	s_nop 0
	v_cndmask_b32_e32 v170, 0, v184, vcc
	v_sub_f32_e32 v170, v202, v170
	v_mul_f32_e32 v170, 0x3e38aa3b, v170
	v_cmp_ngt_f32_e32 vcc, s19, v185
	v_exp_f32_e32 v183, v170
	v_mov_b32_e32 v202, v184
	v_cndmask_b32_e32 v170, 0, v185, vcc
	v_sub_f32_e32 v170, v201, v170
	v_mul_f32_e32 v170, 0x3e38aa3b, v170
	v_exp_f32_e32 v182, v170
	v_mov_b32_e32 v170, v183
	v_mul_f32_e32 v62, v62, v170
	v_mul_f32_e32 v63, v63, v170
	v_mul_f32_e32 v60, v60, v170
	v_mul_f32_e32 v61, v61, v170
	v_mul_f32_e32 v174, v174, v182
	v_mul_f32_e32 v175, v175, v183
	v_mul_f32_e32 v58, v58, v170
	v_mul_f32_e32 v59, v59, v170
	v_mul_f32_e32 v56, v56, v170
	v_mul_f32_e32 v57, v57, v170
	v_mul_f32_e32 v54, v54, v170
	v_mul_f32_e32 v55, v55, v170
	v_mul_f32_e32 v52, v52, v170
	v_mul_f32_e32 v53, v53, v170
	v_mul_f32_e32 v50, v50, v170
	v_mul_f32_e32 v51, v51, v170
	v_mul_f32_e32 v48, v48, v170
	v_mul_f32_e32 v49, v49, v170
	v_mul_f32_e32 v14, v14, v182
	v_mul_f32_e32 v15, v15, v182
	v_mul_f32_e32 v12, v12, v182
	v_mul_f32_e32 v13, v13, v182
	v_mul_f32_e32 v10, v10, v182
	v_mul_f32_e32 v11, v11, v182
	v_mul_f32_e32 v8, v8, v182
	v_mul_f32_e32 v9, v9, v182
	v_mul_f32_e32 v6, v6, v182
	v_mul_f32_e32 v7, v7, v182
	v_mul_f32_e32 v4, v4, v182
	v_mul_f32_e32 v5, v5, v182
	v_mul_f32_e32 v2, v2, v182
	v_mul_f32_e32 v3, v3, v182
	v_mul_f32_e32 v0, v0, v182
	v_mul_f32_e32 v1, v1, v182
	v_mul_f32_e32 v46, v46, v170
	v_mul_f32_e32 v47, v47, v170
	v_mul_f32_e32 v44, v44, v170
	v_mul_f32_e32 v45, v45, v170
	v_mul_f32_e32 v42, v42, v170
	v_mul_f32_e32 v43, v43, v170
	v_mul_f32_e32 v40, v40, v170
	v_mul_f32_e32 v41, v41, v170
	v_mul_f32_e32 v38, v38, v170
	v_mul_f32_e32 v39, v39, v170
	v_mul_f32_e32 v36, v36, v170
	v_mul_f32_e32 v37, v37, v170
	v_mul_f32_e32 v34, v34, v170
	v_mul_f32_e32 v35, v35, v170
	v_mul_f32_e32 v32, v32, v170
	v_mul_f32_e32 v33, v33, v170
	v_mul_f32_e32 v30, v30, v182
	v_mul_f32_e32 v31, v31, v182
	v_mul_f32_e32 v28, v28, v182
	v_mul_f32_e32 v29, v29, v182
	v_mul_f32_e32 v26, v26, v182
	v_mul_f32_e32 v27, v27, v182
	v_mul_f32_e32 v24, v24, v182
	v_mul_f32_e32 v25, v25, v182
	v_mul_f32_e32 v22, v22, v182
	v_mul_f32_e32 v23, v23, v182
	v_mul_f32_e32 v20, v20, v182
	v_mul_f32_e32 v21, v21, v182
	v_mul_f32_e32 v18, v18, v182
	v_mul_f32_e32 v19, v19, v182
	v_mul_f32_e32 v16, v16, v182
	v_mul_f32_e32 v17, v17, v182
	v_mov_b32_e32 v201, v185
	s_branch .LBB0_558
.LBB0_561:
	ds_read_b128 v[64:67], v199 offset:9216
	ds_read_b128 v[160:163], v199 offset:9248
	s_waitcnt lgkmcnt(1)
	v_mfma_f32_32x32x16_bf16 v[112:127], v[64:67], v[152:155], 0
	v_mfma_f32_32x32x16_bf16 v[96:111], v[64:67], v[156:159], 0
	ds_read_b128 v[64:67], v199 offset:13824
	ds_read_b128 v[164:167], v199 offset:13856
	s_waitcnt lgkmcnt(1)
	v_mfma_f32_32x32x16_bf16 v[80:95], v[64:67], v[152:155], 0
	v_mfma_f32_32x32x16_bf16 v[64:79], v[64:67], v[156:159], 0
	v_mfma_f32_32x32x16_bf16 v[112:127], v[160:163], v[144:147], v[112:127]
	s_waitcnt lgkmcnt(0)
	v_mfma_f32_32x32x16_bf16 v[80:95], v[164:167], v[144:147], v[80:95]
	v_mfma_f32_32x32x16_bf16 v[96:111], v[160:163], v[148:151], v[96:111]
	v_mfma_f32_32x32x16_bf16 v[64:79], v[164:167], v[148:151], v[64:79]
	ds_read_b128 v[144:147], v199 offset:9280
	ds_read_b128 v[148:151], v199 offset:9312
	ds_read_b128 v[152:155], v199 offset:13888
	ds_read_b128 v[156:159], v199 offset:13920
	s_waitcnt lgkmcnt(3)
	v_mfma_f32_32x32x16_bf16 v[112:127], v[144:147], v[140:143], v[112:127]
	s_waitcnt lgkmcnt(1)
	v_mfma_f32_32x32x16_bf16 v[80:95], v[152:155], v[140:143], v[80:95]
	v_mfma_f32_32x32x16_bf16 v[96:111], v[144:147], v[132:135], v[96:111]
	v_mfma_f32_32x32x16_bf16 v[64:79], v[152:155], v[132:135], v[64:79]
	v_mfma_f32_32x32x16_bf16 v[112:127], v[148:151], v[136:139], v[112:127]
	s_waitcnt lgkmcnt(0)
	v_mfma_f32_32x32x16_bf16 v[80:95], v[156:159], v[136:139], v[80:95]
	s_nop 9
	v_max_f32_e32 v137, v112, v112
	v_max_f32_e32 v138, v113, v113
	v_max_f32_e32 v139, v115, v115
	v_mfma_f32_32x32x16_bf16 v[64:79], v[156:159], v[128:131], v[64:79]
	v_max_f32_e32 v136, v80, v80
	v_max_f32_e32 v136, v137, v136
	v_max_f32_e32 v137, v81, v81
	v_max_f32_e32 v137, v138, v137
	v_max_f32_e32 v138, v83, v83
	v_max_f32_e32 v138, v139, v138
	v_max3_f32 v133, v114, v82, v118
	v_mfma_f32_32x32x16_bf16 v[96:111], v[148:151], v[128:131], v[96:111]
	v_max3_f32 v134, v138, v119, v87
	v_max3_f32 v136, v136, v116, v84
	v_max3_f32 v132, v137, v117, v85
	v_max3_f32 v133, v133, v86, v122
	v_max3_f32 v134, v134, v123, v91
	v_max3_f32 v135, v136, v120, v88
	v_max3_f32 v132, v132, v121, v89
	v_max3_f32 v133, v133, v90, v126
	v_max3_f32 v134, v134, v127, v95
	v_max_f32_e32 v129, v65, v65
	s_nop 1
	v_max_f32_e32 v130, v97, v97
	v_max3_f32 v135, v135, v124, v92
	v_max3_f32 v132, v132, v125, v93
	v_max3_f32 v133, v133, v94, v134
	v_max_f32_e32 v129, v130, v129
	v_max_f32_e32 v130, v67, v67
	v_max_f32_e32 v131, v99, v99
	v_max3_f32 v132, v135, v132, v133
	v_max_f32_e32 v133, v64, v64
	v_max_f32_e32 v128, v96, v96
	v_max_f32_e32 v130, v131, v130
	v_max_f32_e32 v128, v128, v133
	v_max3_f32 v131, v98, v66, v102
	v_max3_f32 v130, v130, v103, v71
	v_max3_f32 v128, v128, v100, v68
	v_max3_f32 v129, v129, v101, v69
	v_max3_f32 v131, v131, v70, v106
	v_max3_f32 v130, v130, v107, v75
	v_max3_f32 v128, v128, v104, v72
	v_max3_f32 v129, v129, v105, v73
	v_max3_f32 v131, v131, v74, v110
	v_max3_f32 v130, v130, v111, v79
	v_max3_f32 v128, v128, v108, v76
	v_max3_f32 v129, v129, v109, v77
	v_max3_f32 v130, v131, v78, v130
	v_max3_f32 v128, v128, v129, v130
	ds_bpermute_b32 v131, v196, v132
	ds_bpermute_b32 v130, v196, v128
	s_waitcnt lgkmcnt(1)
	v_max_f32_e32 v129, v131, v131
	s_waitcnt lgkmcnt(0)
	v_max_f32_e32 v130, v130, v130
	v_max_f32_e32 v129, v132, v129
	v_max_f32_e32 v128, v128, v130
	v_add_f32_e32 v130, 0x42317218, v202
	v_cmp_gt_f32_e32 vcc, v129, v130
	v_add_f32_e32 v130, 0x42317218, v201
	v_cmp_gt_f32_e64 s[2:3], v128, v130
	s_or_b64 vcc, vcc, s[2:3]
	s_cbranch_vccz .LBB0_556
	v_max_f32_e32 v129, v129, v129
	v_max_f32_e32 v130, v202, v202
	v_max_f32_e32 v131, v130, v129
	v_max_f32_e32 v128, v128, v128
	v_max_f32_e32 v129, v201, v201
	v_cmp_gt_f32_e32 vcc, s19, v131
	v_max_f32_e32 v132, v129, v128
	v_cmp_gt_f32_e64 s[2:3], s19, v132
	v_cndmask_b32_e64 v128, v131, 0, vcc
	v_sub_f32_e32 v128, v202, v128
	v_mul_f32_e32 v128, 0x3e38aa3b, v128
	v_exp_f32_e32 v129, v128
	v_cndmask_b32_e64 v128, v132, 0, s[2:3]
	v_sub_f32_e32 v128, v201, v128
	v_mul_f32_e32 v128, 0x3e38aa3b, v128
	v_exp_f32_e32 v128, v128
	v_mov_b32_e32 v130, v129
	v_mul_f32_e32 v62, v62, v130
	v_mul_f32_e32 v63, v63, v130
	v_mul_f32_e32 v60, v60, v130
	v_mul_f32_e32 v61, v61, v130
	v_mul_f32_e32 v174, v174, v128
	v_mul_f32_e32 v175, v175, v129
	v_mul_f32_e32 v14, v14, v128
	v_mul_f32_e32 v15, v15, v128
	v_mul_f32_e32 v12, v12, v128
	v_mul_f32_e32 v13, v13, v128
	v_mul_f32_e32 v10, v10, v128
	v_mul_f32_e32 v11, v11, v128
	v_mul_f32_e32 v8, v8, v128
	v_mul_f32_e32 v9, v9, v128
	v_mul_f32_e32 v6, v6, v128
	v_mul_f32_e32 v7, v7, v128
	v_mul_f32_e32 v4, v4, v128
	v_mul_f32_e32 v5, v5, v128
	v_mul_f32_e32 v2, v2, v128
	v_mul_f32_e32 v3, v3, v128
	v_mul_f32_e32 v0, v0, v128
	v_mul_f32_e32 v1, v1, v128
	v_mul_f32_e32 v30, v30, v128
	v_mul_f32_e32 v31, v31, v128
	v_mul_f32_e32 v28, v28, v128
	v_mul_f32_e32 v29, v29, v128
	v_mul_f32_e32 v26, v26, v128
	v_mul_f32_e32 v27, v27, v128
	v_mul_f32_e32 v24, v24, v128
	v_mul_f32_e32 v25, v25, v128
	v_mul_f32_e32 v22, v22, v128
	v_mul_f32_e32 v23, v23, v128
	v_mul_f32_e32 v20, v20, v128
	v_mul_f32_e32 v21, v21, v128
	v_mul_f32_e32 v18, v18, v128
	v_mul_f32_e32 v19, v19, v128
	v_mul_f32_e32 v16, v16, v128
	v_mul_f32_e32 v17, v17, v128
	v_mul_f32_e32 v128, 0x3e38aa3b, v131
	v_cndmask_b32_e64 v170, v128, 0, vcc
	v_mul_f32_e32 v128, 0x3e38aa3b, v132
	v_mul_f32_e32 v58, v58, v130
	v_mul_f32_e32 v59, v59, v130
	v_mul_f32_e32 v56, v56, v130
	v_mul_f32_e32 v57, v57, v130
	v_mul_f32_e32 v54, v54, v130
	v_mul_f32_e32 v55, v55, v130
	v_mul_f32_e32 v52, v52, v130
	v_mul_f32_e32 v53, v53, v130
	v_mul_f32_e32 v50, v50, v130
	v_mul_f32_e32 v51, v51, v130
	v_mul_f32_e32 v48, v48, v130
	v_mul_f32_e32 v49, v49, v130
	v_mul_f32_e32 v46, v46, v130
	v_mul_f32_e32 v47, v47, v130
	v_mul_f32_e32 v44, v44, v130
	v_mul_f32_e32 v45, v45, v130
	v_mul_f32_e32 v42, v42, v130
	v_mul_f32_e32 v43, v43, v130
	v_mul_f32_e32 v40, v40, v130
	v_mul_f32_e32 v41, v41, v130
	v_mul_f32_e32 v38, v38, v130
	v_mul_f32_e32 v39, v39, v130
	v_mul_f32_e32 v36, v36, v130
	v_mul_f32_e32 v37, v37, v130
	v_mul_f32_e32 v34, v34, v130
	v_mul_f32_e32 v35, v35, v130
	v_mul_f32_e32 v32, v32, v130
	v_mul_f32_e32 v33, v33, v130
	v_cndmask_b32_e64 v197, v128, 0, s[2:3]
	s_branch .LBB0_556

.LBB0_634:
	s_lshl_b32 s0, 1, s0
	s_waitcnt vmcnt(0)
	v_and_b32_e32 v0, s0, v187
	v_and_b32_e32 v66, s0, v188
	v_cmp_ne_u32_e64 s[6:7], 0, v0
	v_cmp_ne_u32_e32 vcc, 0, v66
	v_cmp_le_u32_e64 s[8:9], s85, v143
	v_cmp_le_u32_e64 s[2:3], s85, v177
	s_and_b64 s[8:9], s[8:9], s[6:7]
	s_and_b64 s[2:3], s[2:3], vcc
	s_cmp_lg_u64 s[8:9], 0
	s_cselect_b64 s[8:9], -1, 0
	s_cmp_lg_u64 s[2:3], 0
	s_cselect_b64 s[2:3], -1, 0
	v_cndmask_b32_e64 v0, 0, 1, s[8:9]
	v_cndmask_b32_e64 v167, 0, 1, s[2:3]
	s_or_b64 s[0:1], s[8:9], s[2:3]
	s_and_saveexec_b64 s[54:55], s[0:1]
	s_cbranch_execz .LBB0_646
	s_cmp_eq_u32 s87, 0
	s_cselect_b64 s[58:59], -1, 0
	s_and_b64 s[0:1], s[58:59], exec
	s_cselect_b32 s0, 0, 0x2400
	v_add_u32_e32 v168, s0, v178
	ds_read_b128 v[158:161], v168
	ds_read_b128 v[162:165], v176 offset:53248
	v_cmp_gt_i32_e64 s[4:5], s85, v190
	s_waitcnt lgkmcnt(2)
	v_cndmask_b32_e64 v66, v173, v189, s[6:7]
	ds_read_b128 v[196:199], v168 offset:32
	ds_read_b128 v[202:205], v176 offset:54272
	ds_read_b128 v[206:209], v176 offset:57344
	ds_read_b128 v[210:213], v176 offset:58368
	v_cndmask_b32_e64 v166, 0, v171, s[4:5]
	v_cndmask_b32_e64 v66, v66, 0, s[4:5]
	v_cndmask_b32_e32 v67, v173, v189, vcc
	v_cmp_gt_i32_e64 s[4:5], s85, v191
	v_cndmask_b32_e64 v240, v173, v66, s[8:9]
	s_nop 0
	v_cndmask_b32_e64 v67, v67, 0, s[4:5]
	s_nop 1
	v_cndmask_b32_e64 v241, v173, v67, s[2:3]
	s_waitcnt lgkmcnt(4)
	v_mfma_f32_32x32x16_bf16 v[98:113], v[158:161], v[162:165], 0
	s_waitcnt lgkmcnt(1)
	v_mfma_f32_32x32x16_bf16 v[114:129], v[158:161], v[206:209], 0
	ds_read_b128 v[158:161], v168 offset:4608
	ds_read_b128 v[214:217], v168 offset:4640
	s_waitcnt lgkmcnt(1)
	v_mfma_f32_32x32x16_bf16 v[82:97], v[158:161], v[162:165], 0
	v_mfma_f32_32x32x16_bf16 v[66:81], v[158:161], v[206:209], 0
	v_mfma_f32_32x32x16_bf16 v[98:113], v[196:199], v[202:205], v[98:113]
	v_mfma_f32_32x32x16_bf16 v[114:129], v[196:199], v[210:213], v[114:129]
	ds_read_b128 v[158:161], v168 offset:64
	ds_read_b128 v[162:165], v176 offset:55296
	ds_read_b128 v[196:199], v168 offset:96
	ds_read_b128 v[206:209], v176 offset:56320
	s_waitcnt lgkmcnt(4)
	v_mfma_f32_32x32x16_bf16 v[82:97], v[214:217], v[202:205], v[82:97]
	v_mfma_f32_32x32x16_bf16 v[66:81], v[214:217], v[210:213], v[66:81]
	ds_read_b128 v[202:205], v176 offset:59392
	ds_read_b128 v[210:213], v176 offset:60416
	s_waitcnt lgkmcnt(4)
	v_mfma_f32_32x32x16_bf16 v[98:113], v[158:161], v[162:165], v[98:113]
	s_waitcnt lgkmcnt(1)
	v_mfma_f32_32x32x16_bf16 v[114:129], v[158:161], v[202:205], v[114:129]
	ds_read_b128 v[158:161], v168 offset:4672
	ds_read_b128 v[214:217], v168 offset:4704
	s_waitcnt lgkmcnt(1)
	v_mfma_f32_32x32x16_bf16 v[82:97], v[158:161], v[162:165], v[82:97]
	v_mfma_f32_32x32x16_bf16 v[66:81], v[158:161], v[202:205], v[66:81]
	v_cndmask_b32_e64 v158, 0, v172, s[6:7]
	v_or3_b32 v0, v158, v166, v0
	v_cndmask_b32_e64 v158, v158, v0, s[8:9]
	v_and_b32_e32 v0, 0x100, v158
	v_cmp_ne_u32_e64 s[6:7], 0, v0
	v_add_u32_e32 v0, s60, v192
	v_mfma_f32_32x32x16_bf16 v[98:113], v[196:199], v[206:209], v[98:113]
	v_mfma_f32_32x32x16_bf16 v[114:129], v[196:199], v[210:213], v[114:129]
	s_waitcnt lgkmcnt(0)
	v_mfma_f32_32x32x16_bf16 v[82:97], v[214:217], v[206:209], v[82:97]
	v_mfma_f32_32x32x16_bf16 v[66:81], v[214:217], v[210:213], v[66:81]
	s_and_saveexec_b64 s[8:9], s[6:7]
	s_cbranch_execz .LBB0_641
	v_lshl_add_u32 v206, v0, 2, s92
	v_and_b32_e32 v205, 0x10000, v158
	v_cmp_ne_u32_e64 s[6:7], 0, v205
	v_mov_b32_e32 v207, s93
	s_nop 1
	v_cndmask_b32_e64 v206, v207, v206, s[6:7]
	ds_read2_b32 v[208:209], v206 offset0:59 offset1:58
	ds_read2_b32 v[210:211], v206 offset0:57 offset1:56
	ds_read2_b32 v[212:213], v206 offset0:51 offset1:50
	ds_read2_b32 v[214:215], v206 offset0:49 offset1:48
	ds_read2_b32 v[216:217], v206 offset0:43 offset1:42
	ds_read2_b32 v[218:219], v206 offset0:41 offset1:40
	ds_read2_b32 v[220:221], v206 offset0:35 offset1:34
	ds_read2_b32 v[222:223], v206 offset0:33 offset1:32
	ds_read2_b32 v[224:225], v206 offset0:27 offset1:26
	ds_read2_b32 v[226:227], v206 offset0:25 offset1:24
	ds_read2_b32 v[228:229], v206 offset0:19 offset1:18
	ds_read2_b32 v[230:231], v206 offset0:17 offset1:16
	ds_read2_b32 v[232:233], v206 offset0:11 offset1:10
	ds_read2_b32 v[234:235], v206 offset0:9 offset1:8
	ds_read2_b32 v[236:237], v206 offset0:3 offset1:2
	ds_read2_b32 v[238:239], v206 offset0:1 offset1:0
	s_waitcnt lgkmcnt(8)
	v_add_f32_e32 v98, v98, v208
	v_add_f32_e32 v99, v99, v209
	v_add_f32_e32 v100, v100, v210
	v_add_f32_e32 v101, v101, v211
	v_add_f32_e32 v102, v102, v212
	v_add_f32_e32 v103, v103, v213
	v_add_f32_e32 v104, v104, v214
	v_add_f32_e32 v105, v105, v215
	v_add_f32_e32 v106, v106, v216
	v_add_f32_e32 v107, v107, v217
	v_add_f32_e32 v108, v108, v218
	v_add_f32_e32 v109, v109, v219
	v_add_f32_e32 v110, v110, v220
	v_add_f32_e32 v111, v111, v221
	v_add_f32_e32 v112, v112, v222
	v_add_f32_e32 v113, v113, v223
	s_waitcnt lgkmcnt(0)
	v_add_f32_e32 v82, v82, v224
	v_add_f32_e32 v83, v83, v225
	v_add_f32_e32 v84, v84, v226
	v_add_f32_e32 v85, v85, v227
	v_add_f32_e32 v86, v86, v228
	v_add_f32_e32 v87, v87, v229
	v_add_f32_e32 v88, v88, v230
	v_add_f32_e32 v89, v89, v231
	v_add_f32_e32 v90, v90, v232
	v_add_f32_e32 v91, v91, v233
	v_add_f32_e32 v92, v92, v234
	v_add_f32_e32 v93, v93, v235
	v_add_f32_e32 v94, v94, v236
	v_add_f32_e32 v95, v95, v237
	v_add_f32_e32 v96, v96, v238
	v_add_f32_e32 v97, v97, v239
.LBB0_641:
	s_or_b64 exec, exec, s[8:9]
	v_cndmask_b32_e32 v158, 0, v172, vcc
	v_cndmask_b32_e64 v159, 0, v171, s[4:5]
	v_or3_b32 v159, v158, v159, v167
	v_cndmask_b32_e64 v158, v158, v159, s[2:3]
	v_and_b32_e32 v159, 0x100, v158
	v_cmp_ne_u32_e32 vcc, 0, v159
	s_and_saveexec_b64 s[2:3], vcc
	s_cbranch_execz .LBB0_643
	v_lshl_add_u32 v206, v0, 2, s94
	v_and_b32_e32 v205, 0x10000, v158
	v_cmp_ne_u32_e32 vcc, 0, v205
	v_mov_b32_e32 v207, s93
	s_nop 1
	v_cndmask_b32_e32 v206, v207, v206, vcc
	ds_read2_b32 v[208:209], v206 offset0:59 offset1:58
	ds_read2_b32 v[210:211], v206 offset0:57 offset1:56
	ds_read2_b32 v[212:213], v206 offset0:51 offset1:50
	ds_read2_b32 v[214:215], v206 offset0:49 offset1:48
	ds_read2_b32 v[216:217], v206 offset0:43 offset1:42
	ds_read2_b32 v[218:219], v206 offset0:41 offset1:40
	ds_read2_b32 v[220:221], v206 offset0:35 offset1:34
	ds_read2_b32 v[222:223], v206 offset0:33 offset1:32
	ds_read2_b32 v[224:225], v206 offset0:27 offset1:26
	ds_read2_b32 v[226:227], v206 offset0:25 offset1:24
	ds_read2_b32 v[228:229], v206 offset0:19 offset1:18
	ds_read2_b32 v[230:231], v206 offset0:17 offset1:16
	ds_read2_b32 v[232:233], v206 offset0:11 offset1:10
	ds_read2_b32 v[234:235], v206 offset0:9 offset1:8
	ds_read2_b32 v[236:237], v206 offset0:3 offset1:2
	ds_read2_b32 v[238:239], v206 offset0:1 offset1:0
	s_waitcnt lgkmcnt(8)
	v_add_f32_e32 v114, v114, v208
	v_add_f32_e32 v115, v115, v209
	v_add_f32_e32 v116, v116, v210
	v_add_f32_e32 v117, v117, v211
	v_add_f32_e32 v118, v118, v212
	v_add_f32_e32 v119, v119, v213
	v_add_f32_e32 v120, v120, v214
	v_add_f32_e32 v121, v121, v215
	v_add_f32_e32 v122, v122, v216
	v_add_f32_e32 v123, v123, v217
	v_add_f32_e32 v124, v124, v218
	v_add_f32_e32 v125, v125, v219
	v_add_f32_e32 v126, v126, v220
	v_add_f32_e32 v127, v127, v221
	v_add_f32_e32 v128, v128, v222
	v_add_f32_e32 v129, v129, v223
	s_waitcnt lgkmcnt(0)
	v_add_f32_e32 v66, v66, v224
	v_add_f32_e32 v67, v67, v225
	v_add_f32_e32 v68, v68, v226
	v_add_f32_e32 v69, v69, v227
	v_add_f32_e32 v70, v70, v228
	v_add_f32_e32 v71, v71, v229
	v_add_f32_e32 v72, v72, v230
	v_add_f32_e32 v73, v73, v231
	v_add_f32_e32 v74, v74, v232
	v_add_f32_e32 v75, v75, v233
	v_add_f32_e32 v76, v76, v234
	v_add_f32_e32 v77, v77, v235
	v_add_f32_e32 v78, v78, v236
	v_add_f32_e32 v79, v79, v237
	v_add_f32_e32 v80, v80, v238
	v_add_f32_e32 v81, v81, v239
.LBB0_643:
	s_or_b64 exec, exec, s[2:3]
	v_max_f32_e32 v0, v98, v82
	v_max_f32_e32 v158, v99, v83
	v_max_f32_e32 v159, v101, v85
	v_max3_f32 v160, v100, v84, v104
	v_max3_f32 v159, v159, v105, v89
	v_max3_f32 v0, v0, v102, v86
	v_max3_f32 v158, v158, v103, v87
	v_max3_f32 v160, v160, v88, v108
	v_max3_f32 v159, v159, v109, v93
	v_max3_f32 v0, v0, v106, v90
	v_max3_f32 v158, v158, v107, v91
	v_max3_f32 v160, v160, v92, v112
	v_max3_f32 v159, v159, v113, v97
	v_max3_f32 v0, v0, v110, v94
	v_max3_f32 v158, v158, v111, v95
	v_max3_f32 v159, v160, v96, v159
	v_max3_f32 v0, v0, v158, v159
	v_max_f32_e32 v158, v114, v66
	v_max_f32_e32 v159, v115, v67
	v_max_f32_e32 v160, v117, v69
	v_max3_f32 v161, v116, v68, v120
	v_max3_f32 v160, v160, v121, v73
	v_max3_f32 v161, v161, v72, v124
	v_max3_f32 v160, v160, v125, v77
	v_max3_f32 v161, v161, v76, v128
	v_max3_f32 v160, v160, v129, v81
	v_max3_f32 v160, v161, v80, v160
	v_max3_f32 v158, v158, v118, v70
	v_max3_f32 v159, v159, v119, v71
	v_max3_f32 v158, v158, v122, v74
	v_max3_f32 v159, v159, v123, v75
	v_max3_f32 v158, v158, v126, v78
	v_max3_f32 v159, v159, v127, v79
	v_max3_f32 v159, v158, v159, v160
	v_mov_b32_e32 v162, v0
	v_mov_b32_e32 v160, v159
	s_nop 1
	v_permlane32_swap_b32_e32 v0, v162
	v_permlane32_swap_b32_e32 v159, v160
	v_max_f32_e32 v158, v0, v162
	v_max_f32_e32 v0, v159, v160
	v_add_f32_e32 v158, v158, v240
	v_add_f32_e32 v0, v0, v241
	v_add_f32_e32 v159, 0x42317218, v194
	v_cmp_gt_f32_e32 vcc, v158, v159
	v_add_f32_e32 v159, 0x42317218, v193
	v_cmp_gt_f32_e64 s[2:3], v0, v159
	s_or_b64 vcc, vcc, s[2:3]
	s_cbranch_vccz .LBB0_645
	v_max_f32_e32 v158, v158, v158
	v_max_f32_e32 v159, v194, v194
	v_max_f32_e32 v160, v159, v158
	v_max_f32_e32 v0, v0, v0
	v_max_f32_e32 v158, v193, v193
	v_cmp_ngt_f32_e32 vcc, s76, v160
	v_max_f32_e32 v161, v158, v0
	s_nop 0
	v_cndmask_b32_e32 v0, 0, v160, vcc
	v_sub_f32_e32 v0, v194, v0
	v_mul_f32_e32 v0, 0x3e38aa3b, v0
	v_cmp_ngt_f32_e32 vcc, s76, v161
	v_exp_f32_e32 v159, v0
	v_mov_b32_e32 v194, v160
	v_cndmask_b32_e32 v0, 0, v161, vcc
	v_sub_f32_e32 v0, v193, v0
	v_mul_f32_e32 v0, 0x3e38aa3b, v0
	v_exp_f32_e32 v158, v0
	v_mov_b32_e32 v0, v159
	v_mul_f32_e32 v64, v64, v0
	v_mul_f32_e32 v65, v65, v0
	v_mul_f32_e32 v62, v62, v0
	v_mul_f32_e32 v63, v63, v0
	v_mul_f32_e32 v156, v156, v158
	v_mul_f32_e32 v157, v157, v159
	v_mul_f32_e32 v60, v60, v0
	v_mul_f32_e32 v61, v61, v0
	v_mul_f32_e32 v58, v58, v0
	v_mul_f32_e32 v59, v59, v0
	v_mul_f32_e32 v56, v56, v0
	v_mul_f32_e32 v57, v57, v0
	v_mul_f32_e32 v54, v54, v0
	v_mul_f32_e32 v55, v55, v0
	v_mul_f32_e32 v52, v52, v0
	v_mul_f32_e32 v53, v53, v0
	v_mul_f32_e32 v50, v50, v0
	v_mul_f32_e32 v51, v51, v0
	v_mul_f32_e32 v16, v16, v158
	v_mul_f32_e32 v17, v17, v158
	v_mul_f32_e32 v14, v14, v158
	v_mul_f32_e32 v15, v15, v158
	v_mul_f32_e32 v12, v12, v158
	v_mul_f32_e32 v13, v13, v158
	v_mul_f32_e32 v10, v10, v158
	v_mul_f32_e32 v11, v11, v158
	v_mul_f32_e32 v8, v8, v158
	v_mul_f32_e32 v9, v9, v158
	v_mul_f32_e32 v6, v6, v158
	v_mul_f32_e32 v7, v7, v158
	v_mul_f32_e32 v4, v4, v158
	v_mul_f32_e32 v5, v5, v158
	v_mul_f32_e32 v2, v2, v158
	v_mul_f32_e32 v3, v3, v158
	v_mul_f32_e32 v48, v48, v0
	v_mul_f32_e32 v49, v49, v0
	v_mul_f32_e32 v46, v46, v0
	v_mul_f32_e32 v47, v47, v0
	v_mul_f32_e32 v44, v44, v0
	v_mul_f32_e32 v45, v45, v0
	v_mul_f32_e32 v42, v42, v0
	v_mul_f32_e32 v43, v43, v0
	v_mul_f32_e32 v40, v40, v0
	v_mul_f32_e32 v41, v41, v0
	v_mul_f32_e32 v38, v38, v0
	v_mul_f32_e32 v39, v39, v0
	v_mul_f32_e32 v36, v36, v0
	v_mul_f32_e32 v37, v37, v0
	v_mul_f32_e32 v34, v34, v0
	v_mul_f32_e32 v35, v35, v0
	v_mul_f32_e32 v32, v32, v158
	v_mul_f32_e32 v33, v33, v158
	v_mul_f32_e32 v30, v30, v158
	v_mul_f32_e32 v31, v31, v158
	v_mul_f32_e32 v28, v28, v158
	v_mul_f32_e32 v29, v29, v158
	v_mul_f32_e32 v26, v26, v158
	v_mul_f32_e32 v27, v27, v158
	v_mul_f32_e32 v24, v24, v158
	v_mul_f32_e32 v25, v25, v158
	v_mul_f32_e32 v22, v22, v158
	v_mul_f32_e32 v23, v23, v158
	v_mul_f32_e32 v20, v20, v158
	v_mul_f32_e32 v21, v21, v158
	v_mul_f32_e32 v18, v18, v158
	v_mul_f32_e32 v19, v19, v158
	v_mov_b32_e32 v193, v161
.LBB0_645:
	v_mul_f32_e32 v0, 0x3e38aa3b, v194
	v_cmp_ngt_f32_e32 vcc, s76, v194
	v_mul_f32_e32 v158, 0x3e38aa3b, v193
	s_and_b64 s[0:1], s[58:59], exec
	v_cndmask_b32_e32 v0, 0, v0, vcc
	v_fma_f32 v0, -v240, s77, v0
	v_cmp_ngt_f32_e32 vcc, s76, v193
	v_fma_f32 v98, v98, s77, -v0
	v_exp_f32_e32 v159, v98
	v_cndmask_b32_e32 v195, 0, v158, vcc
	v_fma_f32 v195, -v241, s77, v195
	v_fma_f32 v66, v66, s77, -v195
	v_exp_f32_e32 v158, v66
	v_fma_f32 v66, v99, s77, -v0
	v_exp_f32_e32 v99, v66
	v_fma_f32 v66, v115, s77, -v195
	v_fma_f32 v98, v114, s77, -v195
	v_exp_f32_e32 v114, v66
	v_fma_f32 v66, v83, s77, -v0
	v_exp_f32_e32 v115, v66
	v_fma_f32 v66, v67, s77, -v195
	v_exp_f32_e32 v160, v98
	v_exp_f32_e32 v98, v66
	v_fma_f32 v66, v100, s77, -v0
	v_exp_f32_e32 v67, v66
	v_fma_f32 v66, v116, s77, -v195
	v_exp_f32_e32 v162, v66
	v_fma_f32 v66, v84, s77, -v0
	v_exp_f32_e32 v163, v66
	v_fma_f32 v66, v68, s77, -v195
	v_fma_f32 v68, v101, s77, -v0
	v_exp_f32_e32 v83, v68
	v_fma_f32 v68, v117, s77, -v195
	v_exp_f32_e32 v100, v68
	v_fma_f32 v68, v85, s77, -v0
	v_fma_f32 v82, v82, s77, -v0
	v_exp_f32_e32 v101, v68
	v_fma_f32 v68, v69, s77, -v195
	v_exp_f32_e32 v161, v82
	v_exp_f32_e32 v82, v68
	v_fma_f32 v68, v102, s77, -v0
	v_exp_f32_e32 v69, v68
	v_fma_f32 v68, v118, s77, -v195
	v_exp_f32_e32 v116, v68
	v_fma_f32 v68, v86, s77, -v0
	v_exp_f32_e32 v117, v68
	v_fma_f32 v68, v70, s77, -v195
	v_fma_f32 v70, v103, s77, -v0
	v_exp_f32_e32 v85, v70
	v_fma_f32 v70, v119, s77, -v195
	v_exp_f32_e32 v164, v70
	v_fma_f32 v70, v87, s77, -v0
	v_add_f32_e32 v86, 0, v160
	v_add_f32_e32 v87, 0, v161
	v_exp_f32_e32 v165, v70
	v_fma_f32 v70, v71, s77, -v195
	v_add_f32_e32 v86, v114, v86
	v_add_f32_e32 v87, v115, v87
	v_exp_f32_e32 v84, v70
	v_fma_f32 v70, v104, s77, -v0
	v_add_f32_e32 v86, v162, v86
	v_add_f32_e32 v87, v163, v87
	v_exp_f32_e32 v71, v70
	v_fma_f32 v70, v120, s77, -v195
	v_add_f32_e32 v86, v100, v86
	v_add_f32_e32 v87, v101, v87
	v_exp_f32_e32 v166, v70
	v_fma_f32 v70, v88, s77, -v0
	v_add_f32_e32 v86, v116, v86
	v_add_f32_e32 v87, v117, v87
	v_exp_f32_e32 v167, v70
	v_fma_f32 v70, v72, s77, -v195
	v_add_f32_e32 v168, v164, v86
	v_add_f32_e32 v169, v165, v87
	v_fma_f32 v72, v105, s77, -v0
	v_fma_f32 v86, v107, s77, -v0
	v_exp_f32_e32 v87, v72
	v_fma_f32 v72, v121, s77, -v195
	v_exp_f32_e32 v105, v86
	v_fma_f32 v86, v123, s77, -v195
	v_exp_f32_e32 v88, v72
	v_fma_f32 v72, v106, s77, -v0
	v_exp_f32_e32 v106, v86
	v_fma_f32 v86, v108, s77, -v0
	v_exp_f32_e32 v119, v86
	v_fma_f32 v86, v124, s77, -v195
	s_cselect_b32 s0, s78, 0x7800
	v_exp_f32_e32 v108, v86
	v_fma_f32 v86, v109, s77, -v0
	v_add_u32_e32 v201, s0, v179
	v_exp_f32_e32 v211, v86
	v_fma_f32 v86, v125, s77, -v195
	v_exp_f32_e32 v103, v72
	v_fma_f32 v72, v122, s77, -v195
	v_cvt_pk_bf16_f32 v120, v159, v99
	v_cvt_pk_bf16_f32 v121, v67, v83
	v_cvt_pk_bf16_f32 v122, v69, v85
	v_cvt_pk_bf16_f32 v123, v71, v87
	v_cvt_pk_bf16_f32 v196, v160, v114
	v_cvt_pk_bf16_f32 v197, v162, v100
	v_cvt_pk_bf16_f32 v198, v116, v164
	v_cvt_pk_bf16_f32 v199, v166, v88
	ds_read_b64_tr_b16 v[202:203], v201
	ds_read_b64_tr_b16 v[204:205], v201 offset:1536
	v_exp_f32_e32 v100, v86
	v_fma_f32 v86, v110, s77, -v0
	ds_read_b64_tr_b16 v[208:209], v201 offset:1600
	ds_read_b64_tr_b16 v[206:207], v201 offset:64
	v_exp_f32_e32 v213, v86
	v_fma_f32 v86, v126, s77, -v195
	v_exp_f32_e32 v160, v86
	v_fma_f32 v86, v111, s77, -v0
	v_exp_f32_e32 v215, v86
	v_fma_f32 v86, v127, s77, -v195
	v_exp_f32_e32 v162, v86
	v_fma_f32 v86, v112, s77, -v0
	s_waitcnt lgkmcnt(2)
	v_mfma_f32_32x32x16_bf16 v[50:65], v[202:205], v[120:123], v[50:65]
	v_exp_f32_e32 v72, v72
	v_cvt_pk_bf16_f32 v110, v103, v105
	v_cvt_pk_bf16_f32 v111, v119, v211
	v_cvt_pk_bf16_f32 v112, v213, v215
	v_fma_f32 v74, v74, s77, -v195
	v_exp_f32_e32 v102, v74
	v_fma_f32 v74, v91, s77, -v0
	v_mfma_f32_32x32x16_bf16 v[2:17], v[202:205], v[196:199], v[2:17]
	v_exp_f32_e32 v203, v86
	v_fma_f32 v86, v128, s77, -v195
	v_exp_f32_e32 v128, v86
	v_fma_f32 v86, v113, s77, -v0
	v_exp_f32_e32 v205, v86
	v_fma_f32 v86, v129, s77, -v195
	v_exp_f32_e32 v164, v86
	s_waitcnt lgkmcnt(0)
	v_mfma_f32_32x32x16_bf16 v[34:49], v[206:209], v[120:123], v[34:49]
	v_cvt_pk_bf16_f32 v113, v203, v205
	v_cvt_pk_bf16_f32 v120, v72, v106
	v_cvt_pk_bf16_f32 v121, v108, v100
	v_cvt_pk_bf16_f32 v122, v160, v162
	v_cvt_pk_bf16_f32 v123, v128, v164
	ds_read_b64_tr_b16 v[124:125], v201 offset:3072
	ds_read_b64_tr_b16 v[126:127], v201 offset:4608
	v_exp_f32_e32 v107, v74
	v_mfma_f32_32x32x16_bf16 v[18:33], v[206:209], v[196:199], v[18:33]
	ds_read_b64_tr_b16 v[198:199], v201 offset:4672
	ds_read_b64_tr_b16 v[196:197], v201 offset:3136
	v_fma_f32 v74, v75, s77, -v195
	v_exp_f32_e32 v104, v74
	v_fma_f32 v74, v92, s77, -v0
	v_exp_f32_e32 v109, v74
	v_fma_f32 v74, v76, s77, -v195
	v_fma_f32 v86, v89, s77, -v0
	v_fma_f32 v73, v73, s77, -v195
	v_exp_f32_e32 v118, v74
	v_fma_f32 v74, v93, s77, -v0
	s_waitcnt lgkmcnt(0)
	v_mfma_f32_32x32x16_bf16 v[34:49], v[196:199], v[110:113], v[34:49]
	v_exp_f32_e32 v89, v86
	v_exp_f32_e32 v86, v73
	v_fma_f32 v73, v90, s77, -v0
	v_cvt_pk_bf16_f32 v90, v161, v115
	v_cvt_pk_bf16_f32 v91, v163, v101
	v_exp_f32_e32 v101, v74
	v_fma_f32 v74, v77, s77, -v195
	v_mfma_f32_32x32x16_bf16 v[18:33], v[196:199], v[120:123], v[18:33]
	v_exp_f32_e32 v210, v74
	v_fma_f32 v74, v94, s77, -v0
	v_exp_f32_e32 v66, v66
	v_exp_f32_e32 v68, v68
	v_exp_f32_e32 v70, v70
	v_cvt_pk_bf16_f32 v92, v117, v165
	v_cvt_pk_bf16_f32 v93, v167, v89
	v_mfma_f32_32x32x16_bf16 v[50:65], v[124:127], v[110:113], v[50:65]
	v_cvt_pk_bf16_f32 v110, v158, v98
	v_cvt_pk_bf16_f32 v111, v66, v82
	v_cvt_pk_bf16_f32 v112, v68, v84
	v_cvt_pk_bf16_f32 v113, v70, v86
	ds_read_b64_tr_b16 v[114:115], v201 offset:6144
	ds_read_b64_tr_b16 v[116:117], v201 offset:7680
	v_exp_f32_e32 v161, v74
	ds_read_b64_tr_b16 v[76:77], v201 offset:7744
	ds_read_b64_tr_b16 v[74:75], v201 offset:6208
	v_mfma_f32_32x32x16_bf16 v[2:17], v[124:127], v[120:123], v[2:17]
	v_add_f32_e64 v206, v158, 0
	v_add_f32_e64 v207, v159, 0
	v_fma_f32 v78, v78, s77, -v195
	v_exp_f32_e32 v212, v78
	v_fma_f32 v78, v95, s77, -v0
	v_exp_f32_e32 v163, v78
	v_fma_f32 v78, v79, s77, -v195
	v_exp_f32_e32 v214, v78
	s_waitcnt lgkmcnt(0)
	v_mfma_f32_32x32x16_bf16 v[34:49], v[74:77], v[90:93], v[34:49]
	v_fma_f32 v78, v96, s77, -v0
	v_fma_f32 v0, v97, s77, -v0
	v_exp_f32_e32 v73, v73
	v_exp_f32_e32 v129, v78
	v_fma_f32 v78, v80, s77, -v195
	v_exp_f32_e32 v165, v0
	v_fma_f32 v0, v81, s77, -v195
	v_mfma_f32_32x32x16_bf16 v[18:33], v[74:77], v[110:113], v[18:33]
	v_add_f32_e64 v74, v98, v206
	v_add_f32_e64 v75, v99, v207
	v_exp_f32_e32 v202, v78
	v_add_f32_e32 v66, v66, v74
	v_add_f32_e32 v67, v67, v75
	v_exp_f32_e32 v204, v0
	v_add_f32_e32 v66, v82, v66
	v_add_f32_e32 v67, v83, v67
	v_cvt_pk_bf16_f32 v78, v73, v107
	v_cvt_pk_bf16_f32 v79, v109, v101
	v_mfma_f32_32x32x16_bf16 v[50:65], v[114:117], v[90:93], v[50:65]
	v_add_f32_e64 v66, v68, v66
	v_add_f32_e64 v67, v69, v67
	v_cvt_pk_bf16_f32 v80, v161, v163
	v_cvt_pk_bf16_f32 v81, v129, v165
	v_cvt_pk_bf16_f32 v90, v102, v104
	v_cvt_pk_bf16_f32 v91, v118, v210
	v_cvt_pk_bf16_f32 v92, v212, v214
	v_cvt_pk_bf16_f32 v93, v202, v204
	v_mfma_f32_32x32x16_bf16 v[2:17], v[114:117], v[110:113], v[2:17]
	ds_read_b64_tr_b16 v[94:95], v201 offset:9216
	ds_read_b64_tr_b16 v[96:97], v201 offset:10752
	v_add_f32_e64 v74, v84, v66
	v_add_f32_e64 v75, v85, v67
	ds_read_b64_tr_b16 v[68:69], v201 offset:10816
	ds_read_b64_tr_b16 v[66:67], v201 offset:9280
	v_add_f32_e32 v168, v166, v168
	v_add_f32_e32 v169, v167, v169
	v_add_f32_e32 v70, v70, v74
	v_add_f32_e32 v71, v71, v75
	v_add_f32_e32 v74, v88, v168
	v_add_f32_e32 v75, v89, v169
	v_add_f32_e32 v70, v86, v70
	v_add_f32_e32 v71, v87, v71
	v_add_f32_e32 v72, v72, v74
	v_add_f32_e32 v73, v73, v75
	v_add_f32_e32 v70, v102, v70
	v_add_f32_e32 v71, v103, v71
	v_add_f32_e32 v72, v106, v72
	v_add_f32_e32 v73, v107, v73
	v_add_f32_e32 v70, v104, v70
	v_add_f32_e32 v71, v105, v71
	s_waitcnt lgkmcnt(2)
	v_mfma_f32_32x32x16_bf16 v[50:65], v[94:97], v[78:81], v[50:65]
	v_add_f32_e64 v72, v108, v72
	v_add_f32_e64 v73, v109, v73
	v_add_f32_e64 v70, v118, v70
	v_add_f32_e64 v71, v119, v71
	v_add_f32_e64 v72, v100, v72
	v_add_f32_e64 v73, v101, v73
	v_add_f32_e32 v70, v210, v70
	v_add_f32_e32 v71, v211, v71
	v_add_f32_e32 v72, v160, v72
	v_add_f32_e32 v73, v161, v73
	v_add_f32_e32 v70, v212, v70
	v_add_f32_e32 v71, v213, v71
	v_add_f32_e32 v72, v162, v72
	v_add_f32_e32 v73, v163, v73
	v_mfma_f32_32x32x16_bf16 v[2:17], v[94:97], v[90:93], v[2:17]
	v_add_f32_e64 v70, v214, v70
	v_add_f32_e64 v71, v215, v71
	v_add_f32_e64 v72, v128, v72
	v_add_f32_e64 v73, v129, v73
	v_add_f32_e64 v70, v202, v70
	v_add_f32_e64 v71, v203, v71
	v_add_f32_e32 v72, v164, v72
	v_add_f32_e32 v73, v165, v73
	v_add_f32_e32 v70, v204, v70
	v_add_f32_e32 v71, v205, v71
	s_nop 0
	v_add_f32_e32 v70, v72, v70
	v_add_f32_e32 v71, v73, v71
	s_waitcnt lgkmcnt(0)
	v_mfma_f32_32x32x16_bf16 v[34:49], v[66:69], v[78:81], v[34:49]
	v_add_f32_e64 v156, v156, v70
	v_add_f32_e64 v157, v157, v71
	v_mfma_f32_32x32x16_bf16 v[18:33], v[66:69], v[90:93], v[18:33]

.LBB0_655:
	s_add_i32 s0, s84, 63
	v_cmp_le_u32_e32 vcc, s84, v143
	v_cmp_ge_i32_e64 s[2:3], s0, v168
	s_and_b64 s[2:3], vcc, s[2:3]
	v_cmp_le_u32_e32 vcc, s84, v177
	v_cmp_ge_i32_e64 s[4:5], s0, v169
	s_and_b64 vcc, vcc, s[4:5]
	s_or_b64 s[4:5], s[2:3], vcc
	s_and_saveexec_b64 s[60:61], s[4:5]
	s_cbranch_execz .LBB0_663
	v_cmp_gt_i32_e64 s[4:5], s0, v182
	v_cmp_lt_i32_e64 s[6:7], s84, v183
	v_cmp_gt_i32_e64 s[8:9], s0, v167
	v_cmp_lt_i32_e64 s[10:11], s84, v185
	s_or_b64 s[6:7], s[4:5], s[6:7]
	s_or_b64 s[8:9], s[8:9], s[10:11]
	s_cmp_eq_u32 s86, 0
	s_cselect_b64 s[4:5], -1, 0
	s_and_b64 s[0:1], s[4:5], exec
	s_waitcnt lgkmcnt(0)
	v_cndmask_b32_e64 v0, v184, 0, s[6:7]
	v_cndmask_b32_e64 v66, v184, 0, s[8:9]
	s_cselect_b32 s0, 0, 0x2400
	v_cndmask_b32_e64 v244, v173, v66, s[2:3]
	v_cndmask_b32_e32 v245, v173, v0, vcc
	v_add_u32_e32 v0, s0, v178
	ds_read_b128 v[156:159], v0
	ds_read_b128 v[160:163], v176 offset:53248
	ds_read_b128 v[188:191], v0 offset:32
	ds_read_b128 v[192:195], v176 offset:54272
	ds_read_b128 v[196:199], v176 offset:57344
	ds_read_b128 v[202:205], v176 offset:58368
	s_waitcnt lgkmcnt(4)
	v_mfma_f32_32x32x16_bf16 v[98:113], v[156:159], v[160:163], 0
	s_and_b64 s[0:1], s[2:3], s[8:9]
	s_waitcnt lgkmcnt(1)
	v_mfma_f32_32x32x16_bf16 v[114:129], v[156:159], v[196:199], 0
	ds_read_b128 v[156:159], v0 offset:4608
	ds_read_b128 v[206:209], v0 offset:4640
	s_waitcnt lgkmcnt(1)
	v_mfma_f32_32x32x16_bf16 v[82:97], v[156:159], v[160:163], 0
	v_mfma_f32_32x32x16_bf16 v[66:81], v[156:159], v[196:199], 0
	ds_read_b128 v[156:159], v0 offset:64
	ds_read_b128 v[160:163], v176 offset:55296
	ds_read_b128 v[212:215], v0 offset:96
	ds_read_b128 v[216:219], v176 offset:56320
	v_mfma_f32_32x32x16_bf16 v[98:113], v[188:191], v[192:195], v[98:113]
	v_mfma_f32_32x32x16_bf16 v[114:129], v[188:191], v[202:205], v[114:129]
	ds_read_b128 v[188:191], v176 offset:59392
	ds_read_b128 v[220:223], v176 offset:60416
	s_waitcnt lgkmcnt(6)
	v_mfma_f32_32x32x16_bf16 v[82:97], v[206:209], v[192:195], v[82:97]
	v_mfma_f32_32x32x16_bf16 v[66:81], v[206:209], v[202:205], v[66:81]
	s_waitcnt lgkmcnt(4)
	v_mfma_f32_32x32x16_bf16 v[98:113], v[156:159], v[160:163], v[98:113]
	s_waitcnt lgkmcnt(1)
	v_mfma_f32_32x32x16_bf16 v[114:129], v[156:159], v[188:191], v[114:129]
	ds_read_b128 v[156:159], v0 offset:4672
	ds_read_b128 v[224:227], v0 offset:4704
	s_waitcnt lgkmcnt(1)
	v_mfma_f32_32x32x16_bf16 v[82:97], v[156:159], v[160:163], v[82:97]
	v_mfma_f32_32x32x16_bf16 v[66:81], v[156:159], v[188:191], v[66:81]
	v_mfma_f32_32x32x16_bf16 v[98:113], v[212:215], v[216:219], v[98:113]
	v_mfma_f32_32x32x16_bf16 v[114:129], v[212:215], v[220:223], v[114:129]
	s_waitcnt lgkmcnt(0)
	v_mfma_f32_32x32x16_bf16 v[82:97], v[224:227], v[216:219], v[82:97]
	v_mfma_f32_32x32x16_bf16 v[66:81], v[224:227], v[220:223], v[66:81]
	s_and_saveexec_b64 s[8:9], s[0:1]
	s_cbranch_execz .LBB0_658
	v_lshl_add_u32 v211, v181, 2, s95
	ds_read2_b32 v[212:213], v211 offset0:59 offset1:58
	ds_read2_b32 v[214:215], v211 offset0:57 offset1:56
	ds_read2_b32 v[216:217], v211 offset0:51 offset1:50
	ds_read2_b32 v[218:219], v211 offset0:49 offset1:48
	ds_read2_b32 v[220:221], v211 offset0:43 offset1:42
	ds_read2_b32 v[222:223], v211 offset0:41 offset1:40
	ds_read2_b32 v[224:225], v211 offset0:35 offset1:34
	ds_read2_b32 v[226:227], v211 offset0:33 offset1:32
	ds_read2_b32 v[228:229], v211 offset0:27 offset1:26
	ds_read2_b32 v[230:231], v211 offset0:25 offset1:24
	ds_read2_b32 v[232:233], v211 offset0:19 offset1:18
	ds_read2_b32 v[234:235], v211 offset0:17 offset1:16
	ds_read2_b32 v[236:237], v211 offset0:11 offset1:10
	ds_read2_b32 v[238:239], v211 offset0:9 offset1:8
	ds_read2_b32 v[240:241], v211 offset0:3 offset1:2
	ds_read2_b32 v[242:243], v211 offset0:1 offset1:0
	s_waitcnt lgkmcnt(8)
	v_add_f32_e32 v98, v98, v212
	v_add_f32_e32 v99, v99, v213
	v_add_f32_e32 v100, v100, v214
	v_add_f32_e32 v101, v101, v215
	v_add_f32_e32 v102, v102, v216
	v_add_f32_e32 v103, v103, v217
	v_add_f32_e32 v104, v104, v218
	v_add_f32_e32 v105, v105, v219
	v_add_f32_e32 v106, v106, v220
	v_add_f32_e32 v107, v107, v221
	v_add_f32_e32 v108, v108, v222
	v_add_f32_e32 v109, v109, v223
	v_add_f32_e32 v110, v110, v224
	v_add_f32_e32 v111, v111, v225
	v_add_f32_e32 v112, v112, v226
	v_add_f32_e32 v113, v113, v227
	s_waitcnt lgkmcnt(0)
	v_add_f32_e32 v82, v82, v228
	v_add_f32_e32 v83, v83, v229
	v_add_f32_e32 v84, v84, v230
	v_add_f32_e32 v85, v85, v231
	v_add_f32_e32 v86, v86, v232
	v_add_f32_e32 v87, v87, v233
	v_add_f32_e32 v88, v88, v234
	v_add_f32_e32 v89, v89, v235
	v_add_f32_e32 v90, v90, v236
	v_add_f32_e32 v91, v91, v237
	v_add_f32_e32 v92, v92, v238
	v_add_f32_e32 v93, v93, v239
	v_add_f32_e32 v94, v94, v240
	v_add_f32_e32 v95, v95, v241
	v_add_f32_e32 v96, v96, v242
	v_add_f32_e32 v97, v97, v243
.LBB0_658:
	s_or_b64 exec, exec, s[8:9]
	s_and_b64 s[0:1], vcc, s[6:7]
	s_and_saveexec_b64 s[2:3], s[0:1]
	s_cbranch_execz .LBB0_660
	v_lshl_add_u32 v211, v181, 2, s96
	ds_read2_b32 v[212:213], v211 offset0:59 offset1:58
	ds_read2_b32 v[214:215], v211 offset0:57 offset1:56
	ds_read2_b32 v[216:217], v211 offset0:51 offset1:50
	ds_read2_b32 v[218:219], v211 offset0:49 offset1:48
	ds_read2_b32 v[220:221], v211 offset0:43 offset1:42
	ds_read2_b32 v[222:223], v211 offset0:41 offset1:40
	ds_read2_b32 v[224:225], v211 offset0:35 offset1:34
	ds_read2_b32 v[226:227], v211 offset0:33 offset1:32
	ds_read2_b32 v[228:229], v211 offset0:27 offset1:26
	ds_read2_b32 v[230:231], v211 offset0:25 offset1:24
	ds_read2_b32 v[232:233], v211 offset0:19 offset1:18
	ds_read2_b32 v[234:235], v211 offset0:17 offset1:16
	ds_read2_b32 v[236:237], v211 offset0:11 offset1:10
	ds_read2_b32 v[238:239], v211 offset0:9 offset1:8
	ds_read2_b32 v[240:241], v211 offset0:3 offset1:2
	ds_read2_b32 v[242:243], v211 offset0:1 offset1:0
	s_waitcnt lgkmcnt(8)
	v_add_f32_e32 v114, v114, v212
	v_add_f32_e32 v115, v115, v213
	v_add_f32_e32 v116, v116, v214
	v_add_f32_e32 v117, v117, v215
	v_add_f32_e32 v118, v118, v216
	v_add_f32_e32 v119, v119, v217
	v_add_f32_e32 v120, v120, v218
	v_add_f32_e32 v121, v121, v219
	v_add_f32_e32 v122, v122, v220
	v_add_f32_e32 v123, v123, v221
	v_add_f32_e32 v124, v124, v222
	v_add_f32_e32 v125, v125, v223
	v_add_f32_e32 v126, v126, v224
	v_add_f32_e32 v127, v127, v225
	v_add_f32_e32 v128, v128, v226
	v_add_f32_e32 v129, v129, v227
	s_waitcnt lgkmcnt(0)
	v_add_f32_e32 v66, v66, v228
	v_add_f32_e32 v67, v67, v229
	v_add_f32_e32 v68, v68, v230
	v_add_f32_e32 v69, v69, v231
	v_add_f32_e32 v70, v70, v232
	v_add_f32_e32 v71, v71, v233
	v_add_f32_e32 v72, v72, v234
	v_add_f32_e32 v73, v73, v235
	v_add_f32_e32 v74, v74, v236
	v_add_f32_e32 v75, v75, v237
	v_add_f32_e32 v76, v76, v238
	v_add_f32_e32 v77, v77, v239
	v_add_f32_e32 v78, v78, v240
	v_add_f32_e32 v79, v79, v241
	v_add_f32_e32 v80, v80, v242
	v_add_f32_e32 v81, v81, v243
.LBB0_660:
	s_or_b64 exec, exec, s[2:3]
	s_nop 3
	v_max_f32_e32 v0, v98, v82
	v_max_f32_e32 v156, v99, v83
	v_max_f32_e32 v157, v101, v85
	v_max3_f32 v158, v100, v84, v104
	v_max3_f32 v157, v157, v105, v89
	v_max3_f32 v0, v0, v102, v86
	v_max3_f32 v156, v156, v103, v87
	v_max3_f32 v158, v158, v88, v108
	v_max3_f32 v157, v157, v109, v93
	v_max3_f32 v0, v0, v106, v90
	v_max3_f32 v156, v156, v107, v91
	v_max3_f32 v158, v158, v92, v112
	v_max3_f32 v157, v157, v113, v97
	v_max3_f32 v0, v0, v110, v94
	v_max3_f32 v156, v156, v111, v95
	v_max3_f32 v157, v158, v96, v157
	v_max3_f32 v0, v0, v156, v157
	v_max_f32_e32 v156, v114, v66
	v_max_f32_e32 v157, v115, v67
	v_max_f32_e32 v158, v117, v69
	v_max3_f32 v159, v116, v68, v120
	v_max3_f32 v158, v158, v121, v73
	v_max3_f32 v156, v156, v118, v70
	v_max3_f32 v157, v157, v119, v71
	v_max3_f32 v159, v159, v72, v124
	v_max3_f32 v158, v158, v125, v77
	v_max3_f32 v156, v156, v122, v74
	v_max3_f32 v157, v157, v123, v75
	v_max3_f32 v159, v159, v76, v128
	v_max3_f32 v158, v158, v129, v81
	v_max3_f32 v156, v156, v126, v78
	v_max3_f32 v157, v157, v127, v79
	v_max3_f32 v158, v159, v80, v158
	v_max3_f32 v157, v156, v157, v158
	v_mov_b32_e32 v159, v0
	v_mov_b32_e32 v158, v157
	s_nop 1
	v_permlane32_swap_b32_e32 v0, v159
	v_permlane32_swap_b32_e32 v157, v158
	v_max_f32_e32 v156, v0, v159
	v_max_f32_e32 v0, v157, v158
	v_add_f32_e32 v156, v156, v244
	v_add_f32_e32 v0, v0, v245
	v_add_f32_e32 v157, 0x42317218, v187
	v_cmp_gt_f32_e32 vcc, v156, v157
	v_add_f32_e32 v157, 0x42317218, v186
	v_cmp_gt_f32_e64 s[2:3], v0, v157
	s_or_b64 vcc, vcc, s[2:3]
	s_cbranch_vccz .LBB0_662
	v_max_f32_e32 v156, v156, v156
	v_max_f32_e32 v157, v187, v187
	v_max_f32_e32 v158, v157, v156
	v_max_f32_e32 v0, v0, v0
	v_max_f32_e32 v156, v186, v186
	v_cmp_ngt_f32_e32 vcc, s76, v158
	v_max_f32_e32 v159, v156, v0
	s_nop 0
	v_cndmask_b32_e32 v0, 0, v158, vcc
	v_sub_f32_e32 v0, v187, v0
	v_mul_f32_e32 v0, 0x3e38aa3b, v0
	v_cmp_ngt_f32_e32 vcc, s76, v159
	v_exp_f32_e32 v157, v0
	v_mov_b32_e32 v187, v158
	v_cndmask_b32_e32 v0, 0, v159, vcc
	v_sub_f32_e32 v0, v186, v0
	v_mul_f32_e32 v0, 0x3e38aa3b, v0
	v_exp_f32_e32 v156, v0
	v_mov_b32_e32 v0, v157
	v_mul_f32_e32 v64, v64, v0
	v_mul_f32_e32 v65, v65, v0
	v_mul_f32_e32 v62, v62, v0
	v_mul_f32_e32 v63, v63, v0
	v_mul_f32_e32 v150, v150, v156
	v_mul_f32_e32 v151, v151, v157
	v_mul_f32_e32 v60, v60, v0
	v_mul_f32_e32 v61, v61, v0
	v_mul_f32_e32 v58, v58, v0
	v_mul_f32_e32 v59, v59, v0
	v_mul_f32_e32 v56, v56, v0
	v_mul_f32_e32 v57, v57, v0
	v_mul_f32_e32 v54, v54, v0
	v_mul_f32_e32 v55, v55, v0
	v_mul_f32_e32 v52, v52, v0
	v_mul_f32_e32 v53, v53, v0
	v_mul_f32_e32 v50, v50, v0
	v_mul_f32_e32 v51, v51, v0
	v_mul_f32_e32 v16, v16, v156
	v_mul_f32_e32 v17, v17, v156
	v_mul_f32_e32 v14, v14, v156
	v_mul_f32_e32 v15, v15, v156
	v_mul_f32_e32 v12, v12, v156
	v_mul_f32_e32 v13, v13, v156
	v_mul_f32_e32 v10, v10, v156
	v_mul_f32_e32 v11, v11, v156
	v_mul_f32_e32 v8, v8, v156
	v_mul_f32_e32 v9, v9, v156
	v_mul_f32_e32 v6, v6, v156
	v_mul_f32_e32 v7, v7, v156
	v_mul_f32_e32 v4, v4, v156
	v_mul_f32_e32 v5, v5, v156
	v_mul_f32_e32 v2, v2, v156
	v_mul_f32_e32 v3, v3, v156
	v_mul_f32_e32 v48, v48, v0
	v_mul_f32_e32 v49, v49, v0
	v_mul_f32_e32 v46, v46, v0
	v_mul_f32_e32 v47, v47, v0
	v_mul_f32_e32 v44, v44, v0
	v_mul_f32_e32 v45, v45, v0
	v_mul_f32_e32 v42, v42, v0
	v_mul_f32_e32 v43, v43, v0
	v_mul_f32_e32 v40, v40, v0
	v_mul_f32_e32 v41, v41, v0
	v_mul_f32_e32 v38, v38, v0
	v_mul_f32_e32 v39, v39, v0
	v_mul_f32_e32 v36, v36, v0
	v_mul_f32_e32 v37, v37, v0
	v_mul_f32_e32 v34, v34, v0
	v_mul_f32_e32 v35, v35, v0
	v_mul_f32_e32 v32, v32, v156
	v_mul_f32_e32 v33, v33, v156
	v_mul_f32_e32 v30, v30, v156
	v_mul_f32_e32 v31, v31, v156
	v_mul_f32_e32 v28, v28, v156
	v_mul_f32_e32 v29, v29, v156
	v_mul_f32_e32 v26, v26, v156
	v_mul_f32_e32 v27, v27, v156
	v_mul_f32_e32 v24, v24, v156
	v_mul_f32_e32 v25, v25, v156
	v_mul_f32_e32 v22, v22, v156
	v_mul_f32_e32 v23, v23, v156
	v_mul_f32_e32 v20, v20, v156
	v_mul_f32_e32 v21, v21, v156
	v_mul_f32_e32 v18, v18, v156
	v_mul_f32_e32 v19, v19, v156
	v_mov_b32_e32 v186, v159
.LBB0_662:
	v_mul_f32_e32 v0, 0x3e38aa3b, v187
	v_cmp_ngt_f32_e32 vcc, s76, v187
	v_mul_f32_e32 v156, 0x3e38aa3b, v186
	s_and_b64 s[0:1], s[4:5], exec
	v_cndmask_b32_e32 v0, 0, v0, vcc
	v_fma_f32 v0, -v244, s77, v0
	v_cmp_ngt_f32_e32 vcc, s76, v186
	v_fma_f32 v98, v98, s77, -v0
	v_exp_f32_e32 v157, v98
	v_cndmask_b32_e32 v201, 0, v156, vcc
	v_fma_f32 v201, -v245, s77, v201
	v_fma_f32 v66, v66, s77, -v201
	v_exp_f32_e32 v156, v66
	v_fma_f32 v66, v99, s77, -v0
	v_exp_f32_e32 v99, v66
	v_fma_f32 v66, v115, s77, -v201
	v_fma_f32 v98, v114, s77, -v201
	v_exp_f32_e32 v114, v66
	v_fma_f32 v66, v83, s77, -v0
	v_exp_f32_e32 v115, v66
	v_fma_f32 v66, v67, s77, -v201
	v_exp_f32_e32 v158, v98
	v_exp_f32_e32 v98, v66
	v_fma_f32 v66, v100, s77, -v0
	v_exp_f32_e32 v67, v66
	v_fma_f32 v66, v116, s77, -v201
	v_exp_f32_e32 v160, v66
	v_fma_f32 v66, v84, s77, -v0
	v_exp_f32_e32 v161, v66
	v_fma_f32 v66, v68, s77, -v201
	v_fma_f32 v68, v101, s77, -v0
	v_exp_f32_e32 v83, v68
	v_fma_f32 v68, v117, s77, -v201
	v_exp_f32_e32 v100, v68
	v_fma_f32 v68, v85, s77, -v0
	v_fma_f32 v82, v82, s77, -v0
	v_exp_f32_e32 v101, v68
	v_fma_f32 v68, v69, s77, -v201
	v_exp_f32_e32 v159, v82
	v_exp_f32_e32 v82, v68
	v_fma_f32 v68, v102, s77, -v0
	v_exp_f32_e32 v85, v68
	v_fma_f32 v68, v118, s77, -v201
	v_exp_f32_e32 v116, v68
	v_fma_f32 v68, v86, s77, -v0
	v_exp_f32_e32 v117, v68
	v_fma_f32 v68, v70, s77, -v201
	v_exp_f32_e32 v84, v68
	v_fma_f32 v68, v103, s77, -v0
	v_exp_f32_e32 v69, v68
	v_fma_f32 v68, v119, s77, -v201
	v_exp_f32_e32 v118, v68
	v_fma_f32 v68, v87, s77, -v0
	v_fma_f32 v70, v104, s77, -v0
	v_exp_f32_e32 v119, v68
	v_fma_f32 v68, v71, s77, -v201
	v_exp_f32_e32 v71, v70
	v_fma_f32 v70, v120, s77, -v201
	v_exp_f32_e32 v162, v70
	v_fma_f32 v70, v88, s77, -v0
	v_exp_f32_e32 v163, v70
	v_fma_f32 v70, v72, s77, -v201
	v_fma_f32 v72, v105, s77, -v0
	v_exp_f32_e32 v87, v72
	v_fma_f32 v72, v121, s77, -v201
	v_exp_f32_e32 v120, v72
	v_fma_f32 v72, v89, s77, -v0
	v_exp_f32_e32 v121, v72
	v_fma_f32 v72, v73, s77, -v201
	v_exp_f32_e32 v86, v72
	v_add_f32_e32 v72, 0, v158
	v_add_f32_e32 v73, 0, v159
	s_cselect_b32 s0, s78, 0x7800
	v_add_f32_e32 v164, v114, v72
	v_add_f32_e32 v165, v115, v73
	v_fma_f32 v72, v106, s77, -v0
	v_exp_f32_e32 v73, v72
	v_fma_f32 v72, v122, s77, -v201
	v_exp_f32_e32 v88, v72
	v_fma_f32 v72, v107, s77, -v0
	v_exp_f32_e32 v103, v72
	v_fma_f32 v72, v123, s77, -v201
	v_exp_f32_e32 v104, v72
	v_fma_f32 v72, v108, s77, -v0
	v_exp_f32_e32 v107, v72
	v_fma_f32 v72, v124, s77, -v201
	v_exp_f32_e32 v108, v72
	v_add_u32_e32 v216, s0, v179
	v_fma_f32 v72, v109, s77, -v0
	v_cvt_pk_bf16_f32 v188, v157, v99
	v_cvt_pk_bf16_f32 v189, v67, v83
	v_cvt_pk_bf16_f32 v190, v85, v69
	v_cvt_pk_bf16_f32 v191, v71, v87
	v_cvt_pk_bf16_f32 v192, v158, v114
	v_cvt_pk_bf16_f32 v193, v160, v100
	v_cvt_pk_bf16_f32 v194, v116, v118
	v_cvt_pk_bf16_f32 v195, v162, v120
	ds_read_b64_tr_b16 v[196:197], v216
	ds_read_b64_tr_b16 v[198:199], v216 offset:1536
	v_exp_f32_e32 v203, v72
	v_fma_f32 v72, v125, s77, -v201
	ds_read_b64_tr_b16 v[124:125], v216 offset:1600
	ds_read_b64_tr_b16 v[122:123], v216 offset:64
	v_exp_f32_e32 v158, v72
	v_fma_f32 v72, v110, s77, -v0
	v_exp_f32_e32 v205, v72
	v_fma_f32 v72, v126, s77, -v201
	v_exp_f32_e32 v206, v72
	v_fma_f32 v72, v111, s77, -v0
	v_exp_f32_e32 v209, v72
	v_fma_f32 v72, v127, s77, -v201
	v_exp_f32_e32 v210, v72
	v_fma_f32 v72, v112, s77, -v0
	s_waitcnt lgkmcnt(0)
	v_mfma_f32_32x32x16_bf16 v[34:49], v[122:125], v[188:191], v[34:49]
	v_cvt_pk_bf16_f32 v110, v73, v103
	v_cvt_pk_bf16_f32 v111, v107, v203
	v_cvt_pk_bf16_f32 v112, v205, v209
	v_exp_f32_e32 v66, v66
	v_exp_f32_e32 v68, v68
	v_exp_f32_e32 v70, v70
	v_fma_f32 v78, v78, s77, -v201
	v_mfma_f32_32x32x16_bf16 v[18:33], v[122:125], v[192:195], v[18:33]
	v_add_f32_e64 v122, v160, v164
	v_add_f32_e64 v123, v161, v165
	v_exp_f32_e32 v204, v78
	v_add_f32_e32 v122, v100, v122
	v_add_f32_e32 v123, v101, v123
	v_fma_f32 v78, v95, s77, -v0
	v_add_f32_e32 v122, v116, v122
	v_add_f32_e32 v123, v117, v123
	v_exp_f32_e32 v211, v78
	v_add_f32_e32 v122, v118, v122
	v_add_f32_e32 v123, v119, v123
	v_mfma_f32_32x32x16_bf16 v[50:65], v[196:199], v[188:191], v[50:65]
	v_add_f32_e64 v164, v162, v122
	v_add_f32_e64 v165, v163, v123
	v_fma_f32 v78, v79, s77, -v201
	v_exp_f32_e32 v208, v78
	v_fma_f32 v78, v96, s77, -v0
	v_add_f32_e32 v164, v120, v164
	v_add_f32_e32 v165, v121, v165
	v_mfma_f32_32x32x16_bf16 v[2:17], v[196:199], v[192:195], v[2:17]
	v_exp_f32_e32 v197, v72
	v_fma_f32 v72, v128, s77, -v201
	v_exp_f32_e32 v198, v72
	v_fma_f32 v72, v113, s77, -v0
	v_exp_f32_e32 v213, v72
	v_fma_f32 v72, v129, s77, -v201
	v_exp_f32_e32 v214, v72
	v_cvt_pk_bf16_f32 v113, v197, v213
	v_cvt_pk_bf16_f32 v126, v88, v104
	v_cvt_pk_bf16_f32 v127, v108, v158
	v_cvt_pk_bf16_f32 v128, v206, v210
	v_cvt_pk_bf16_f32 v129, v198, v214
	ds_read_b64_tr_b16 v[188:189], v216 offset:3072
	ds_read_b64_tr_b16 v[190:191], v216 offset:4608
	ds_read_b64_tr_b16 v[124:125], v216 offset:4672
	ds_read_b64_tr_b16 v[122:123], v216 offset:3136
	v_fma_f32 v72, v90, s77, -v0
	v_exp_f32_e32 v89, v72
	v_fma_f32 v72, v74, s77, -v201
	v_fma_f32 v74, v91, s77, -v0
	v_exp_f32_e32 v105, v74
	v_fma_f32 v74, v75, s77, -v201
	v_exp_f32_e32 v102, v74
	v_fma_f32 v74, v92, s77, -v0
	v_exp_f32_e32 v109, v74
	v_fma_f32 v74, v76, s77, -v201
	v_exp_f32_e32 v106, v74
	v_fma_f32 v74, v93, s77, -v0
	s_waitcnt lgkmcnt(0)
	v_mfma_f32_32x32x16_bf16 v[34:49], v[122:125], v[110:113], v[34:49]
	v_cvt_pk_bf16_f32 v90, v159, v115
	v_exp_f32_e32 v159, v74
	v_fma_f32 v74, v77, s77, -v201
	v_exp_f32_e32 v202, v74
	v_fma_f32 v74, v94, s77, -v0
	v_cvt_pk_bf16_f32 v91, v161, v101
	v_cvt_pk_bf16_f32 v92, v117, v119
	v_mfma_f32_32x32x16_bf16 v[18:33], v[122:125], v[126:129], v[18:33]
	v_cvt_pk_bf16_f32 v93, v163, v121
	v_exp_f32_e32 v207, v74
	v_fma_f32 v0, v97, s77, -v0
	v_exp_f32_e32 v72, v72
	v_exp_f32_e32 v199, v78
	v_fma_f32 v78, v80, s77, -v201
	v_exp_f32_e32 v215, v0
	v_mfma_f32_32x32x16_bf16 v[50:65], v[188:191], v[110:113], v[50:65]
	v_cvt_pk_bf16_f32 v110, v156, v98
	v_cvt_pk_bf16_f32 v111, v66, v82
	v_cvt_pk_bf16_f32 v112, v84, v68
	v_cvt_pk_bf16_f32 v113, v70, v86
	ds_read_b64_tr_b16 v[114:115], v216 offset:6144
	ds_read_b64_tr_b16 v[116:117], v216 offset:7680
	ds_read_b64_tr_b16 v[76:77], v216 offset:7744
	ds_read_b64_tr_b16 v[74:75], v216 offset:6208
	v_fma_f32 v0, v81, s77, -v201
	v_mfma_f32_32x32x16_bf16 v[2:17], v[188:191], v[126:129], v[2:17]
	v_exp_f32_e32 v196, v78
	v_exp_f32_e32 v212, v0
	v_cvt_pk_bf16_f32 v78, v89, v105
	v_cvt_pk_bf16_f32 v79, v109, v159
	v_cvt_pk_bf16_f32 v80, v207, v211
	v_cvt_pk_bf16_f32 v81, v199, v215
	s_waitcnt lgkmcnt(0)
	v_mfma_f32_32x32x16_bf16 v[34:49], v[74:77], v[90:93], v[34:49]
	v_mfma_f32_32x32x16_bf16 v[18:33], v[74:77], v[110:113], v[18:33]
	v_add_f32_e64 v74, v156, 0
	v_add_f32_e64 v75, v157, 0
	v_add_f32_e64 v74, v98, v74
	v_add_f32_e64 v75, v99, v75
	v_add_f32_e64 v66, v66, v74
	v_add_f32_e64 v67, v67, v75
	v_add_f32_e32 v66, v82, v66
	v_add_f32_e32 v67, v83, v67
	v_mfma_f32_32x32x16_bf16 v[50:65], v[114:117], v[90:93], v[50:65]
	v_add_f32_e64 v66, v84, v66
	v_add_f32_e64 v67, v85, v67
	v_cvt_pk_bf16_f32 v90, v72, v102
	v_cvt_pk_bf16_f32 v91, v106, v202
	v_cvt_pk_bf16_f32 v92, v204, v208
	v_cvt_pk_bf16_f32 v93, v196, v212
	ds_read_b64_tr_b16 v[94:95], v216 offset:9216
	ds_read_b64_tr_b16 v[96:97], v216 offset:10752
	ds_read_b64_tr_b16 v[76:77], v216 offset:10816
	ds_read_b64_tr_b16 v[74:75], v216 offset:9280
	v_mfma_f32_32x32x16_bf16 v[2:17], v[114:117], v[110:113], v[2:17]
	v_add_f32_e64 v66, v68, v66
	v_add_f32_e64 v67, v69, v67
	v_add_f32_e64 v68, v88, v164
	v_add_f32_e64 v69, v89, v165
	v_add_f32_e64 v66, v70, v66
	v_add_f32_e64 v67, v71, v67
	v_add_f32_e32 v68, v104, v68
	v_add_f32_e32 v69, v105, v69
	v_add_f32_e32 v66, v86, v66
	v_add_f32_e32 v67, v87, v67
	v_add_f32_e32 v68, v108, v68
	v_add_f32_e32 v69, v109, v69
	v_add_f32_e32 v66, v72, v66
	v_add_f32_e32 v67, v73, v67
	s_waitcnt lgkmcnt(2)
	v_mfma_f32_32x32x16_bf16 v[50:65], v[94:97], v[78:81], v[50:65]
	v_add_f32_e64 v66, v102, v66
	v_add_f32_e64 v67, v103, v67
	v_add_f32_e64 v68, v158, v68
	v_add_f32_e64 v69, v159, v69
	v_add_f32_e64 v66, v106, v66
	v_add_f32_e64 v67, v107, v67
	v_add_f32_e32 v68, v206, v68
	v_add_f32_e32 v69, v207, v69
	v_add_f32_e32 v66, v202, v66
	v_add_f32_e32 v67, v203, v67
	v_add_f32_e32 v68, v210, v68
	v_add_f32_e32 v69, v211, v69
	v_add_f32_e32 v66, v204, v66
	v_add_f32_e32 v67, v205, v67
	v_mfma_f32_32x32x16_bf16 v[2:17], v[94:97], v[90:93], v[2:17]
	v_add_f32_e64 v66, v208, v66
	v_add_f32_e64 v67, v209, v67
	v_add_f32_e64 v68, v198, v68
	v_add_f32_e64 v69, v199, v69
	v_add_f32_e64 v66, v196, v66
	v_add_f32_e64 v67, v197, v67
	v_add_f32_e32 v68, v214, v68
	v_add_f32_e32 v69, v215, v69
	v_add_f32_e32 v66, v212, v66
	v_add_f32_e32 v67, v213, v67
	s_nop 0
	v_add_f32_e32 v66, v68, v66
	v_add_f32_e32 v67, v69, v67
	s_waitcnt lgkmcnt(0)
	v_mfma_f32_32x32x16_bf16 v[34:49], v[74:77], v[78:81], v[34:49]
	v_add_f32_e64 v150, v150, v66
	v_add_f32_e64 v151, v151, v67
	v_mfma_f32_32x32x16_bf16 v[18:33], v[74:77], v[90:93], v[18:33]

.Lmoba_skipfill:
	v_and_b32_e32 v253, 32, v200
	v_add_u32_e32 v253, 0x1e000, v253
	s_mov_b32 s91, 0x1d094
	s_mov_b32 s32, 0x1d114
	s_xor_b64 s[72:73], s[2:3], -1
	s_and_b64 s[0:1], s[2:3], exec
	s_cselect_b32 s97, s96, s95
	v_ashrrev_i32_e32 v80, 8, v78
	v_lshl_add_u32 v62, s97, 1, v80
	v_and_b32_e32 v81, 0xc0, v78
	v_and_b32_e32 v79, 31, v78
	v_lshl_or_b32 v83, v62, 8, v81
	v_or_b32_e32 v0, v83, v79
	v_ashrrev_i32_e32 v1, 31, v0
	v_lshl_add_u64 v[172:173], s[44:45], 0, v[0:1]
	v_bfe_u32 v82, v78, 5, 1
	v_mad_u64_u32 v[0:1], s[0:1], v172, s84, v[170:171]
	v_mad_i32_i24 v1, v173, s84, v1
	v_lshlrev_b32_e32 v168, 4, v82
	v_lshl_add_u64 v[0:1], v[0:1], 0, v[168:169]
	global_load_dwordx4 v[20:23], v[0:1], off offset:32
	global_load_dwordx4 v[28:31], v[0:1], off
	global_load_dwordx4 v[16:19], v[0:1], off offset:96
	global_load_dwordx4 v[24:27], v[0:1], off offset:64
	v_add_co_u32_e32 v144, vcc, 0x28000, v0
	s_nop 1
	v_addc_co_u32_e32 v145, vcc, 0, v1, vcc
	global_load_dwordx4 v[124:127], v[144:145], off offset:32
	global_load_dwordx4 v[132:135], v[144:145], off
	global_load_dwordx4 v[120:123], v[144:145], off offset:96
	global_load_dwordx4 v[128:131], v[144:145], off offset:64
	v_ashrrev_i32_e32 v146, 3, v200
	v_med3_i32 v146, v146, 0, v201
	v_mul_u32_u24_e32 v146, 0xa00, v146
	v_mov_b32_e32 v147, 0
	v_lshl_add_u64 v[146:147], v[146:147], 1, s[68:69]
	v_lshlrev_b32_e32 v144, 4, v200
	v_and_b32_e32 v144, 0x70, v144
	v_mov_b32_e32 v145, 0
	v_lshl_add_u64 v[146:147], v[146:147], 0, v[144:145]
	global_load_dwordx4 v[136:139], v[146:147], off
	global_load_dwordx4 v[140:143], v[146:147], off offset:1536
	v_and_b32_e32 v0, 32, v78
	v_mov_b32_e32 v1, v169
	v_lshl_add_u64 v[12:13], s[34:35], 0, v[0:1]
	v_mov_b32_e32 v63, 0
	v_lshl_add_u64 v[0:1], v[12:13], 0, s[50:51]
	v_cmp_lt_i32_e32 vcc, 0, v62
	v_mov_b32_e32 v64, 0
	s_waitcnt vmcnt(3)
	v_lshlrev_b32_e32 v15, 16, v20
	s_waitcnt vmcnt(2)
	v_lshlrev_b32_e32 v14, 16, v28
	v_and_b32_e32 v45, 0xffff0000, v20
	v_and_b32_e32 v44, 0xffff0000, v28
	v_lshlrev_b32_e32 v43, 16, v21
	v_lshlrev_b32_e32 v42, 16, v29
	v_and_b32_e32 v41, 0xffff0000, v21
	v_and_b32_e32 v40, 0xffff0000, v29
	v_lshlrev_b32_e32 v39, 16, v22
	v_lshlrev_b32_e32 v38, 16, v30
	v_and_b32_e32 v37, 0xffff0000, v22
	v_and_b32_e32 v36, 0xffff0000, v30
	v_lshlrev_b32_e32 v35, 16, v23
	v_lshlrev_b32_e32 v34, 16, v31
	v_and_b32_e32 v33, 0xffff0000, v23
	v_and_b32_e32 v32, 0xffff0000, v31
	s_waitcnt vmcnt(1)
	v_lshlrev_b32_e32 v49, 16, v16
	s_waitcnt vmcnt(0)
	v_lshlrev_b32_e32 v48, 16, v24
	v_and_b32_e32 v61, 0xffff0000, v16
	v_and_b32_e32 v60, 0xffff0000, v24
	v_lshlrev_b32_e32 v59, 16, v17
	v_lshlrev_b32_e32 v58, 16, v25
	v_and_b32_e32 v57, 0xffff0000, v17
	v_and_b32_e32 v56, 0xffff0000, v25
	v_lshlrev_b32_e32 v55, 16, v18
	v_lshlrev_b32_e32 v54, 16, v26
	v_and_b32_e32 v53, 0xffff0000, v18
	v_and_b32_e32 v52, 0xffff0000, v26
	v_lshlrev_b32_e32 v51, 16, v19
	v_lshlrev_b32_e32 v50, 16, v27
	v_and_b32_e32 v47, 0xffff0000, v19
	v_and_b32_e32 v46, 0xffff0000, v27
	s_and_saveexec_b64 s[2:3], vcc
	s_cbranch_execz .LBB0_1293
	ds_read_b128 v[2:5], v253 offset:0
	ds_read_b128 v[6:9], v253 offset:64
	ds_read_b128 v[64:67], v253 offset:16
	ds_read_b128 v[68:71], v253 offset:80
	ds_read_b128 v[72:75], v253 offset:128
	ds_read_b128 v[84:87], v253 offset:192
	ds_read_b128 v[88:91], v253 offset:144
	ds_read_b128 v[92:95], v253 offset:208
	s_waitcnt lgkmcnt(7)
	v_mov_b32_e32 v10, v2
	s_waitcnt lgkmcnt(6)
	v_mov_b32_e32 v11, v6
	v_mov_b32_e32 v6, v3
	v_mul_f32_e32 v6, v6, v44
	v_mul_f32_e32 v7, v7, v45
	v_mov_b32_e32 v2, v4
	v_mov_b32_e32 v3, v8
	v_mov_b32_e32 v8, v5
	s_waitcnt lgkmcnt(4)
	v_mov_b32_e32 v5, v68
	v_mov_b32_e32 v68, v65
	v_mov_b32_e32 v65, v70
	v_mov_b32_e32 v70, v67
	s_waitcnt lgkmcnt(2)
	v_mov_b32_e32 v67, v84
	v_mov_b32_e32 v84, v73
	v_fma_f32 v6, v10, v14, v6
	v_fma_f32 v7, v11, v15, v7
	v_mov_b32_e32 v4, v64
	v_mov_b32_e32 v64, v66
	v_mov_b32_e32 v66, v72
	v_mul_f32_e32 v84, v84, v60
	v_mul_f32_e32 v85, v85, v61
	v_fma_f32 v2, v2, v42, v6
	v_fma_f32 v3, v3, v43, v7
	v_mov_b32_e32 v72, v74
	v_mov_b32_e32 v73, v86
	v_fma_f32 v10, v66, v48, v84
	v_fma_f32 v11, v67, v49, v85
	v_fma_f32 v2, v8, v40, v2
	v_fma_f32 v3, v9, v41, v3
	v_mov_b32_e32 v86, v75
	v_fma_f32 v6, v72, v58, v10
	v_fma_f32 v7, v73, v59, v11
	v_fma_f32 v2, v4, v38, v2
	v_fma_f32 v3, v5, v39, v3
	s_waitcnt lgkmcnt(1)
	v_mov_b32_e32 v74, v88
	s_waitcnt lgkmcnt(0)
	v_mov_b32_e32 v75, v92
	v_fma_f32 v6, v86, v56, v6
	v_fma_f32 v7, v87, v57, v7
	v_fma_f32 v2, v68, v36, v2
	v_fma_f32 v3, v69, v37, v3
	v_mov_b32_e32 v92, v89
	v_fma_f32 v4, v74, v54, v6
	v_fma_f32 v5, v75, v55, v7
	v_fma_f32 v2, v64, v34, v2
	v_fma_f32 v3, v65, v35, v3
	v_mov_b32_e32 v76, v90
	v_mov_b32_e32 v77, v94
	v_fma_f32 v4, v92, v52, v4
	v_fma_f32 v5, v93, v53, v5
	v_fma_f32 v2, v70, v32, v2
	v_fma_f32 v3, v71, v33, v3
	v_mov_b32_e32 v94, v91
	v_fma_f32 v4, v76, v50, v4
	v_fma_f32 v5, v77, v51, v5
	v_add_f32_e32 v2, 0, v2
	v_add_f32_e32 v6, v2, v3
	v_fma_f32 v2, v94, v46, v4
	v_fma_f32 v3, v95, v47, v5
	s_nop 0
	v_add_f32_e32 v2, v6, v2
	v_add_f32_e32 v64, v2, v3
.LBB0_1293:
	s_or_b64 exec, exec, s[2:3]
	v_and_b32_e32 v3, 64, v181
	v_xor_b32_e32 v2, 32, v181
	v_add_u32_e32 v3, 64, v3
	v_cmp_lt_i32_e64 s[2:3], v2, v3
	s_nop 1
	v_cndmask_b32_e64 v2, v181, v2, s[2:3]
	v_lshlrev_b32_e32 v204, 2, v2
	ds_bpermute_b32 v65, v204, v64
	v_cmp_lt_i32_e64 s[2:3], 1, v62
	v_lshl_add_u64 v[2:3], v[12:13], 0, s[52:53]
	s_and_saveexec_b64 s[4:5], s[2:3]
	s_cbranch_execz .LBB0_1295
	ds_read_b128 v[4:7], v253 offset:256
	ds_read_b128 v[8:11], v253 offset:320
	ds_read_b128 v[66:69], v253 offset:272
	ds_read_b128 v[70:73], v253 offset:336
	ds_read_b128 v[74:77], v253 offset:384
	ds_read_b128 v[84:87], v253 offset:448
	ds_read_b128 v[88:91], v253 offset:400
	ds_read_b128 v[92:95], v253 offset:464
	s_waitcnt lgkmcnt(7)
	v_mov_b32_e32 v96, v4
	s_waitcnt lgkmcnt(6)
	v_mov_b32_e32 v97, v8
	v_mov_b32_e32 v8, v5
	v_mul_f32_e32 v8, v8, v44
	v_mul_f32_e32 v9, v9, v45
	v_mov_b32_e32 v4, v6
	v_mov_b32_e32 v5, v10
	v_mov_b32_e32 v10, v7
	s_waitcnt lgkmcnt(4)
	v_mov_b32_e32 v7, v70
	v_mov_b32_e32 v70, v67
	v_mov_b32_e32 v67, v72
	v_mov_b32_e32 v72, v69
	s_waitcnt lgkmcnt(2)
	v_mov_b32_e32 v69, v84
	v_mov_b32_e32 v84, v75
	v_fma_f32 v8, v96, v14, v8
	v_fma_f32 v9, v97, v15, v9
	v_mov_b32_e32 v6, v66
	v_mov_b32_e32 v66, v68
	v_mov_b32_e32 v68, v74
	v_mul_f32_e32 v84, v84, v60
	v_mul_f32_e32 v85, v85, v61
	v_fma_f32 v4, v4, v42, v8
	v_fma_f32 v5, v5, v43, v9
	v_mov_b32_e32 v74, v76
	v_mov_b32_e32 v75, v86
	v_fma_f32 v68, v68, v48, v84
	v_fma_f32 v69, v69, v49, v85
	v_fma_f32 v4, v10, v40, v4
	v_fma_f32 v5, v11, v41, v5
	v_mov_b32_e32 v86, v77
	v_fma_f32 v8, v74, v58, v68
	v_fma_f32 v9, v75, v59, v69
	v_fma_f32 v4, v6, v38, v4
	v_fma_f32 v5, v7, v39, v5
	s_waitcnt lgkmcnt(1)
	v_mov_b32_e32 v76, v88
	s_waitcnt lgkmcnt(0)
	v_mov_b32_e32 v77, v92
	v_fma_f32 v8, v86, v56, v8
	v_fma_f32 v9, v87, v57, v9
	v_fma_f32 v4, v70, v36, v4
	v_fma_f32 v5, v71, v37, v5
	v_mov_b32_e32 v92, v89
	v_fma_f32 v6, v76, v54, v8
	v_fma_f32 v7, v77, v55, v9
	v_fma_f32 v4, v66, v34, v4
	v_fma_f32 v5, v67, v35, v5
	v_mov_b32_e32 v88, v90
	v_mov_b32_e32 v89, v94
	v_fma_f32 v6, v92, v52, v6
	v_fma_f32 v7, v93, v53, v7
	v_fma_f32 v4, v72, v32, v4
	v_fma_f32 v5, v73, v33, v5
	v_mov_b32_e32 v94, v91
	v_fma_f32 v6, v88, v50, v6
	v_fma_f32 v7, v89, v51, v7
	v_add_f32_e32 v4, 0, v4
	v_add_f32_e32 v8, v4, v5
	v_fma_f32 v4, v94, v46, v6
	v_fma_f32 v5, v95, v47, v7
	s_nop 0
	v_add_f32_e32 v4, v8, v4
	v_add_f32_e32 v63, v4, v5
.LBB0_1295:
	s_or_b64 exec, exec, s[4:5]
	ds_bpermute_b32 v66, v204, v63
	v_cmp_lt_i32_e64 s[4:5], 2, v62
	v_mov_b32_e32 v67, 0
	v_lshl_add_u64 v[4:5], v[12:13], 0, s[54:55]
	v_mov_b32_e32 v68, 0
	s_and_saveexec_b64 s[6:7], s[4:5]
	s_cbranch_execz .LBB0_1297
	ds_read_b128 v[6:9], v253 offset:512
	ds_read_b128 v[68:71], v253 offset:576
	ds_read_b128 v[72:75], v253 offset:528
	ds_read_b128 v[84:87], v253 offset:592
	ds_read_b128 v[88:91], v253 offset:640
	ds_read_b128 v[92:95], v253 offset:704
	ds_read_b128 v[96:99], v253 offset:656
	ds_read_b128 v[100:103], v253 offset:720
	s_waitcnt lgkmcnt(7)
	v_mov_b32_e32 v10, v6
	s_waitcnt lgkmcnt(6)
	v_mov_b32_e32 v11, v68
	v_mov_b32_e32 v68, v7
	v_mul_f32_e32 v68, v68, v44
	v_mul_f32_e32 v69, v69, v45
	v_mov_b32_e32 v6, v8
	v_mov_b32_e32 v7, v70
	v_mov_b32_e32 v70, v9
	s_waitcnt lgkmcnt(4)
	v_mov_b32_e32 v9, v84
	v_mov_b32_e32 v84, v73
	v_mov_b32_e32 v73, v86
	v_mov_b32_e32 v86, v75
	s_waitcnt lgkmcnt(2)
	v_mov_b32_e32 v75, v92
	v_mov_b32_e32 v92, v89
	v_fma_f32 v10, v10, v14, v68
	v_fma_f32 v11, v11, v15, v69
	v_mov_b32_e32 v8, v72
	v_mov_b32_e32 v72, v74
	v_mov_b32_e32 v74, v88
	v_mul_f32_e32 v92, v92, v60
	v_mul_f32_e32 v93, v93, v61
	v_fma_f32 v6, v6, v42, v10
	v_fma_f32 v7, v7, v43, v11
	v_mov_b32_e32 v76, v90
	v_mov_b32_e32 v77, v94
	v_fma_f32 v68, v74, v48, v92
	v_fma_f32 v69, v75, v49, v93
	v_fma_f32 v6, v70, v40, v6
	v_fma_f32 v7, v71, v41, v7
	v_mov_b32_e32 v94, v91
	v_fma_f32 v10, v76, v58, v68
	v_fma_f32 v11, v77, v59, v69
	v_fma_f32 v6, v8, v38, v6
	v_fma_f32 v7, v9, v39, v7
	s_waitcnt lgkmcnt(1)
	v_mov_b32_e32 v88, v96
	s_waitcnt lgkmcnt(0)
	v_mov_b32_e32 v89, v100
	v_fma_f32 v10, v94, v56, v10
	v_fma_f32 v11, v95, v57, v11
	v_fma_f32 v6, v84, v36, v6
	v_fma_f32 v7, v85, v37, v7
	v_mov_b32_e32 v100, v97
	v_fma_f32 v8, v88, v54, v10
	v_fma_f32 v9, v89, v55, v11
	v_fma_f32 v6, v72, v34, v6
	v_fma_f32 v7, v73, v35, v7
	v_mov_b32_e32 v90, v98
	v_mov_b32_e32 v91, v102
	v_fma_f32 v8, v100, v52, v8
	v_fma_f32 v9, v101, v53, v9
	v_fma_f32 v6, v86, v32, v6
	v_fma_f32 v7, v87, v33, v7
	v_mov_b32_e32 v102, v99
	v_fma_f32 v8, v90, v50, v8
	v_fma_f32 v9, v91, v51, v9
	v_add_f32_e32 v6, 0, v6
	v_add_f32_e32 v10, v6, v7
	v_fma_f32 v6, v102, v46, v8
	v_fma_f32 v7, v103, v47, v9
	s_nop 0
	v_add_f32_e32 v6, v10, v6
	v_add_f32_e32 v68, v6, v7
.LBB0_1297:
	s_or_b64 exec, exec, s[6:7]
	ds_bpermute_b32 v69, v204, v68
	v_cmp_lt_i32_e64 s[6:7], 3, v62
	v_lshl_add_u64 v[6:7], v[12:13], 0, s[58:59]
	s_and_saveexec_b64 s[8:9], s[6:7]
	s_cbranch_execz .LBB0_1299
	ds_read_b128 v[8:11], v253 offset:768
	ds_read_b128 v[70:73], v253 offset:832
	ds_read_b128 v[74:77], v253 offset:784
	ds_read_b128 v[84:87], v253 offset:848
	ds_read_b128 v[88:91], v253 offset:896
	ds_read_b128 v[92:95], v253 offset:960
	ds_read_b128 v[96:99], v253 offset:912
	ds_read_b128 v[100:103], v253 offset:976
	s_waitcnt lgkmcnt(7)
	v_mov_b32_e32 v104, v8
	s_waitcnt lgkmcnt(6)
	v_mov_b32_e32 v105, v70
	v_mov_b32_e32 v70, v9
	v_mul_f32_e32 v70, v70, v44
	v_mul_f32_e32 v71, v71, v45
	v_mov_b32_e32 v8, v10
	v_mov_b32_e32 v9, v72
	v_mov_b32_e32 v72, v11
	s_waitcnt lgkmcnt(4)
	v_mov_b32_e32 v11, v84
	v_mov_b32_e32 v84, v75
	v_mov_b32_e32 v75, v86
	v_mov_b32_e32 v86, v77
	s_waitcnt lgkmcnt(2)
	v_mov_b32_e32 v77, v92
	v_mov_b32_e32 v92, v89
	v_fma_f32 v70, v104, v14, v70
	v_fma_f32 v71, v105, v15, v71
	v_mov_b32_e32 v10, v74
	v_mov_b32_e32 v74, v76
	v_mov_b32_e32 v76, v88
	v_mul_f32_e32 v92, v92, v60
	v_mul_f32_e32 v93, v93, v61
	v_fma_f32 v8, v8, v42, v70
	v_fma_f32 v9, v9, v43, v71
	v_mov_b32_e32 v88, v90
	v_mov_b32_e32 v89, v94
	v_fma_f32 v76, v76, v48, v92
	v_fma_f32 v77, v77, v49, v93
	v_fma_f32 v8, v72, v40, v8
	v_fma_f32 v9, v73, v41, v9
	v_mov_b32_e32 v94, v91
	v_fma_f32 v70, v88, v58, v76
	v_fma_f32 v71, v89, v59, v77
	v_fma_f32 v8, v10, v38, v8
	v_fma_f32 v9, v11, v39, v9
	s_waitcnt lgkmcnt(1)
	v_mov_b32_e32 v90, v96
	s_waitcnt lgkmcnt(0)
	v_mov_b32_e32 v91, v100
	v_fma_f32 v70, v94, v56, v70
	v_fma_f32 v71, v95, v57, v71
	v_fma_f32 v8, v84, v36, v8
	v_fma_f32 v9, v85, v37, v9
	v_mov_b32_e32 v100, v97
	v_fma_f32 v10, v90, v54, v70
	v_fma_f32 v11, v91, v55, v71
	v_fma_f32 v8, v74, v34, v8
	v_fma_f32 v9, v75, v35, v9
	v_mov_b32_e32 v96, v98
	v_mov_b32_e32 v97, v102
	v_fma_f32 v10, v100, v52, v10
	v_fma_f32 v11, v101, v53, v11
	v_fma_f32 v8, v86, v32, v8
	v_fma_f32 v9, v87, v33, v9
	v_mov_b32_e32 v102, v99
	v_fma_f32 v10, v96, v50, v10
	v_fma_f32 v11, v97, v51, v11
	v_add_f32_e32 v8, 0, v8
	v_add_f32_e32 v67, v8, v9
	v_fma_f32 v8, v102, v46, v10
	v_fma_f32 v9, v103, v47, v11
	s_nop 0
	v_add_f32_e32 v8, v67, v8
	v_add_f32_e32 v67, v8, v9
.LBB0_1299:
	s_or_b64 exec, exec, s[8:9]
	ds_bpermute_b32 v70, v204, v67
	v_cmp_lt_i32_e64 s[8:9], 4, v62
	v_mov_b32_e32 v71, 0
	v_lshl_add_u64 v[8:9], v[12:13], 0, s[60:61]
	v_mov_b32_e32 v72, 0
	s_and_saveexec_b64 s[10:11], s[8:9]
	s_cbranch_execz .LBB0_1301
	ds_read_b128 v[72:75], v253 offset:1024
	ds_read_b128 v[84:87], v253 offset:1088
	ds_read_b128 v[88:91], v253 offset:1040
	ds_read_b128 v[92:95], v253 offset:1104
	ds_read_b128 v[96:99], v253 offset:1152
	ds_read_b128 v[100:103], v253 offset:1216
	ds_read_b128 v[104:107], v253 offset:1168
	ds_read_b128 v[108:111], v253 offset:1232
	s_waitcnt lgkmcnt(7)
	v_mov_b32_e32 v10, v72
	s_waitcnt lgkmcnt(6)
	v_mov_b32_e32 v11, v84
	v_mov_b32_e32 v84, v73
	v_mul_f32_e32 v84, v84, v44
	v_mul_f32_e32 v85, v85, v45
	v_mov_b32_e32 v72, v74
	v_mov_b32_e32 v73, v86
	v_mov_b32_e32 v86, v75
	s_waitcnt lgkmcnt(4)
	v_mov_b32_e32 v75, v92
	v_mov_b32_e32 v92, v89
	s_waitcnt lgkmcnt(2)
	v_mov_b32_e32 v89, v100
	v_mov_b32_e32 v100, v97
	v_fma_f32 v10, v10, v14, v84
	v_fma_f32 v11, v11, v15, v85
	v_mov_b32_e32 v74, v88
	v_mov_b32_e32 v88, v96
	v_mul_f32_e32 v100, v100, v60
	v_mul_f32_e32 v101, v101, v61
	v_fma_f32 v10, v72, v42, v10
	v_fma_f32 v11, v73, v43, v11
	v_mov_b32_e32 v76, v90
	v_mov_b32_e32 v77, v94
	v_mov_b32_e32 v94, v91
	v_mov_b32_e32 v90, v98
	v_mov_b32_e32 v91, v102
	v_fma_f32 v84, v88, v48, v100
	v_fma_f32 v85, v89, v49, v101
	v_fma_f32 v10, v86, v40, v10
	v_fma_f32 v11, v87, v41, v11
	v_mov_b32_e32 v102, v99
	v_fma_f32 v72, v90, v58, v84
	v_fma_f32 v73, v91, v59, v85
	v_fma_f32 v10, v74, v38, v10
	v_fma_f32 v11, v75, v39, v11
	s_waitcnt lgkmcnt(1)
	v_mov_b32_e32 v96, v104
	s_waitcnt lgkmcnt(0)
	v_mov_b32_e32 v97, v108
	v_fma_f32 v72, v102, v56, v72
	v_fma_f32 v73, v103, v57, v73
	v_fma_f32 v10, v92, v36, v10
	v_fma_f32 v11, v93, v37, v11
	v_mov_b32_e32 v108, v105
	v_fma_f32 v72, v96, v54, v72
	v_fma_f32 v73, v97, v55, v73
	v_fma_f32 v10, v76, v34, v10
	v_fma_f32 v11, v77, v35, v11
	v_mov_b32_e32 v98, v106
	v_mov_b32_e32 v99, v110
	v_fma_f32 v72, v108, v52, v72
	v_fma_f32 v73, v109, v53, v73
	v_fma_f32 v10, v94, v32, v10
	v_fma_f32 v11, v95, v33, v11
	v_mov_b32_e32 v110, v107
	v_fma_f32 v72, v98, v50, v72
	v_fma_f32 v73, v99, v51, v73
	v_add_f32_e32 v10, 0, v10
	v_add_f32_e32 v74, v10, v11
	v_fma_f32 v10, v110, v46, v72
	v_fma_f32 v11, v111, v47, v73
	s_nop 0
	v_add_f32_e32 v10, v74, v10
	v_add_f32_e32 v72, v10, v11
.LBB0_1301:
	s_or_b64 exec, exec, s[10:11]
	ds_bpermute_b32 v73, v204, v72
	v_cmp_lt_i32_e64 s[10:11], 5, v62
	v_lshl_add_u64 v[10:11], v[12:13], 0, s[62:63]
	s_and_saveexec_b64 s[12:13], s[10:11]
	s_cbranch_execz .LBB0_1303
	ds_read_b128 v[74:77], v253 offset:1280
	ds_read_b128 v[84:87], v253 offset:1344
	ds_read_b128 v[88:91], v253 offset:1296
	ds_read_b128 v[92:95], v253 offset:1360
	ds_read_b128 v[96:99], v253 offset:1408
	ds_read_b128 v[100:103], v253 offset:1472
	ds_read_b128 v[104:107], v253 offset:1424
	ds_read_b128 v[108:111], v253 offset:1488
	s_waitcnt lgkmcnt(7)
	v_mov_b32_e32 v112, v74
	s_waitcnt lgkmcnt(6)
	v_mov_b32_e32 v113, v84
	v_mov_b32_e32 v84, v75
	v_mul_f32_e32 v84, v84, v44
	v_mul_f32_e32 v85, v85, v45
	v_mov_b32_e32 v74, v76
	v_mov_b32_e32 v75, v86
	v_mov_b32_e32 v86, v77
	s_waitcnt lgkmcnt(4)
	v_mov_b32_e32 v77, v92
	v_mov_b32_e32 v92, v89
	v_mov_b32_e32 v89, v94
	v_mov_b32_e32 v94, v91
	s_waitcnt lgkmcnt(2)
	v_mov_b32_e32 v91, v100
	v_mov_b32_e32 v100, v97
	v_fma_f32 v84, v112, v14, v84
	v_fma_f32 v85, v113, v15, v85
	v_mov_b32_e32 v76, v88
	v_mov_b32_e32 v88, v90
	v_mov_b32_e32 v90, v96
	v_mul_f32_e32 v100, v100, v60
	v_mul_f32_e32 v101, v101, v61
	v_fma_f32 v74, v74, v42, v84
	v_fma_f32 v75, v75, v43, v85
	v_mov_b32_e32 v96, v98
	v_mov_b32_e32 v97, v102
	v_fma_f32 v90, v90, v48, v100
	v_fma_f32 v91, v91, v49, v101
	v_fma_f32 v74, v86, v40, v74
	v_fma_f32 v75, v87, v41, v75
	v_mov_b32_e32 v102, v99
	v_fma_f32 v84, v96, v58, v90
	v_fma_f32 v85, v97, v59, v91
	v_fma_f32 v74, v76, v38, v74
	v_fma_f32 v75, v77, v39, v75
	s_waitcnt lgkmcnt(1)
	v_mov_b32_e32 v98, v104
	s_waitcnt lgkmcnt(0)
	v_mov_b32_e32 v99, v108
	v_fma_f32 v84, v102, v56, v84
	v_fma_f32 v85, v103, v57, v85
	v_fma_f32 v74, v92, v36, v74
	v_fma_f32 v75, v93, v37, v75
	v_mov_b32_e32 v108, v105
	v_fma_f32 v76, v98, v54, v84
	v_fma_f32 v77, v99, v55, v85
	v_fma_f32 v74, v88, v34, v74
	v_fma_f32 v75, v89, v35, v75
	v_mov_b32_e32 v104, v106
	v_mov_b32_e32 v105, v110
	v_fma_f32 v76, v108, v52, v76
	v_fma_f32 v77, v109, v53, v77
	v_fma_f32 v74, v94, v32, v74
	v_fma_f32 v75, v95, v33, v75
	v_mov_b32_e32 v110, v107
	v_fma_f32 v76, v104, v50, v76
	v_fma_f32 v77, v105, v51, v77
	v_add_f32_e32 v71, 0, v74
	v_add_f32_e32 v71, v71, v75
	v_fma_f32 v74, v110, v46, v76
	v_fma_f32 v75, v111, v47, v77
	s_nop 0
	v_add_f32_e32 v71, v71, v74
	v_add_f32_e32 v71, v71, v75
.LBB0_1303:
	s_or_b64 exec, exec, s[12:13]
	ds_bpermute_b32 v74, v204, v71
	v_cmp_lt_i32_e64 s[12:13], 6, v62
	v_mov_b32_e32 v75, 0
	v_lshl_add_u64 v[12:13], v[12:13], 0, s[64:65]
	s_and_saveexec_b64 s[14:15], s[12:13]
	s_cbranch_execz .LBB0_1305
	ds_read_b128 v[84:87], v253 offset:1536
	ds_read_b128 v[88:91], v253 offset:1600
	ds_read_b128 v[92:95], v253 offset:1552
	ds_read_b128 v[96:99], v253 offset:1616
	ds_read_b128 v[100:103], v253 offset:1664
	ds_read_b128 v[104:107], v253 offset:1728
	ds_read_b128 v[108:111], v253 offset:1680
	ds_read_b128 v[112:115], v253 offset:1744
	s_waitcnt lgkmcnt(7)
	v_mov_b32_e32 v76, v84
	s_waitcnt lgkmcnt(6)
	v_mov_b32_e32 v77, v88
	v_mov_b32_e32 v88, v85
	v_mul_f32_e32 v44, v88, v44
	v_mul_f32_e32 v45, v89, v45
	v_mov_b32_e32 v84, v86
	v_mov_b32_e32 v85, v90
	v_mov_b32_e32 v90, v87
	s_waitcnt lgkmcnt(4)
	v_mov_b32_e32 v87, v96
	v_mov_b32_e32 v96, v93
	v_mov_b32_e32 v93, v98
	v_mov_b32_e32 v98, v95
	s_waitcnt lgkmcnt(2)
	v_mov_b32_e32 v95, v104
	v_mov_b32_e32 v104, v101
	v_fma_f32 v14, v76, v14, v44
	v_fma_f32 v15, v77, v15, v45
	v_mov_b32_e32 v86, v92
	v_mov_b32_e32 v92, v94
	v_mov_b32_e32 v94, v100
	v_mul_f32_e32 v60, v104, v60
	v_mul_f32_e32 v61, v105, v61
	v_fma_f32 v14, v84, v42, v14
	v_fma_f32 v15, v85, v43, v15
	v_mov_b32_e32 v100, v102
	v_mov_b32_e32 v101, v106
	v_fma_f32 v44, v94, v48, v60
	v_fma_f32 v45, v95, v49, v61
	v_fma_f32 v14, v90, v40, v14
	v_fma_f32 v15, v91, v41, v15
	v_mov_b32_e32 v106, v103
	v_fma_f32 v42, v100, v58, v44
	v_fma_f32 v43, v101, v59, v45
	v_fma_f32 v14, v86, v38, v14
	v_fma_f32 v15, v87, v39, v15
	s_waitcnt lgkmcnt(1)
	v_mov_b32_e32 v102, v108
	s_waitcnt lgkmcnt(0)
	v_mov_b32_e32 v103, v112
	v_fma_f32 v40, v106, v56, v42
	v_fma_f32 v41, v107, v57, v43
	v_fma_f32 v14, v96, v36, v14
	v_fma_f32 v15, v97, v37, v15
	v_mov_b32_e32 v112, v109
	v_fma_f32 v38, v102, v54, v40
	v_fma_f32 v39, v103, v55, v41
	v_fma_f32 v14, v92, v34, v14
	v_fma_f32 v15, v93, v35, v15
	v_mov_b32_e32 v108, v110
	v_mov_b32_e32 v109, v114
	v_fma_f32 v36, v112, v52, v38
	v_fma_f32 v37, v113, v53, v39
	v_fma_f32 v14, v98, v32, v14
	v_fma_f32 v15, v99, v33, v15
	v_mov_b32_e32 v114, v111
	v_fma_f32 v34, v108, v50, v36
	v_fma_f32 v35, v109, v51, v37
	v_add_f32_e32 v14, 0, v14
	v_add_f32_e32 v32, v14, v15
	v_fma_f32 v14, v114, v46, v34
	v_fma_f32 v15, v115, v47, v35
	s_nop 0
	v_add_f32_e32 v14, v32, v14
	v_add_f32_e32 v75, v14, v15

.LBB0_1306:
	v_and_b32_e32 v38, 1, v37
	v_cmp_eq_u32_e64 s[18:19], 0, v38
	s_or_b64 s[18:19], s[18:19], s[14:15]
	v_and_b32_e32 v40, 2, v37
	v_cndmask_b32_e64 v39, v35, v199, s[18:19]
	v_cndmask_b32_e64 v38, 0, -1, s[18:19]
	v_cmp_ne_u32_e64 s[18:19], 0, v40
	v_cmp_gt_f32_e64 s[20:21], v34, v39
	s_and_b64 s[18:19], s[18:19], s[20:21]
	v_cndmask_b32_e64 v39, v39, v34, s[18:19]
	v_and_b32_e32 v40, 4, v37
	v_cndmask_b32_e64 v38, v38, 1, s[18:19]
	v_cmp_ne_u32_e64 s[18:19], 0, v40
	v_cmp_gt_f32_e64 s[20:21], v33, v39
	s_and_b64 s[18:19], s[18:19], s[20:21]
	v_cndmask_b32_e64 v39, v39, v33, s[18:19]
	v_and_b32_e32 v40, 8, v37
	v_cndmask_b32_e64 v38, v38, 2, s[18:19]
	v_cmp_ne_u32_e64 s[18:19], 0, v40
	v_cmp_gt_f32_e64 s[20:21], v32, v39
	s_and_b64 s[18:19], s[18:19], s[20:21]
	v_cndmask_b32_e64 v39, v39, v32, s[18:19]
	v_and_b32_e32 v40, 16, v37
	v_cndmask_b32_e64 v38, v38, 3, s[18:19]
	v_cmp_ne_u32_e64 s[18:19], 0, v40
	v_cmp_gt_f32_e64 s[20:21], v15, v39
	s_and_b64 s[18:19], s[18:19], s[20:21]
	v_cndmask_b32_e64 v39, v39, v15, s[18:19]
	v_and_b32_e32 v40, 32, v37
	v_cndmask_b32_e64 v38, v38, 4, s[18:19]
	v_cmp_ne_u32_e64 s[18:19], 0, v40
	v_cmp_gt_f32_e64 s[20:21], v14, v39
	s_and_b64 s[18:19], s[18:19], s[20:21]
	v_cndmask_b32_e64 v39, v39, v14, s[18:19]
	v_and_b32_e32 v40, 64, v37
	v_cndmask_b32_e64 v38, v38, 5, s[18:19]
	v_cmp_ne_u32_e64 s[18:19], 0, v40
	v_cmp_gt_f32_e64 s[20:21], v36, v39
	s_and_b64 s[18:19], s[18:19], s[20:21]
	v_cndmask_b32_e64 v38, v38, 6, s[18:19]
	v_lshlrev_b32_e64 v39, v38, 1
	v_cmp_lt_i32_e64 s[18:19], -1, v38
	v_not_b32_e32 v40, v39
	s_add_i32 s0, s0, -1
	v_cndmask_b32_e64 v38, 0, v39, s[18:19]
	v_or_b32_e32 v205, v38, v205
	v_cndmask_b32_e64 v38, -1, v40, s[18:19]
	s_cmp_lg_u32 s0, 0
	v_and_b32_e32 v37, v38, v37
	s_cbranch_scc1 .LBB0_1306
	v_or_b32_e32 v176, 32, v172
	v_mov_b64_e32 v[14:15], s[66:67]
	v_mad_u64_u32 v[14:15], s[0:1], v176, s84, v[14:15]
	v_mad_i32_i24 v15, v173, s84, v15
	v_lshlrev_b32_e32 v32, 1, v174
	v_mov_b32_e32 v33, v169
	v_lshl_add_u64 v[14:15], v[14:15], 0, v[32:33]
	v_mov_b64_e32 v[52:53], v[124:125]
	v_mov_b64_e32 v[54:55], v[126:127]
	v_mov_b64_e32 v[60:61], v[132:133]
	v_mov_b64_e32 v[62:63], v[134:135]
	v_mov_b64_e32 v[48:49], v[120:121]
	v_mov_b64_e32 v[50:51], v[122:123]
	v_mov_b64_e32 v[56:57], v[128:129]
	v_mov_b64_e32 v[58:59], v[130:131]
	v_mov_b32_e32 v86, 0
	v_mov_b32_e32 v87, 0
	s_waitcnt vmcnt(3)
	v_lshlrev_b32_e32 v15, 16, v52
	s_waitcnt vmcnt(2)
	v_lshlrev_b32_e32 v14, 16, v60
	v_and_b32_e32 v45, 0xffff0000, v52
	v_and_b32_e32 v44, 0xffff0000, v60
	v_lshlrev_b32_e32 v43, 16, v53
	v_lshlrev_b32_e32 v42, 16, v61
	v_and_b32_e32 v41, 0xffff0000, v53
	v_and_b32_e32 v40, 0xffff0000, v61
	v_lshlrev_b32_e32 v39, 16, v54
	v_lshlrev_b32_e32 v38, 16, v62
	v_and_b32_e32 v37, 0xffff0000, v54
	v_and_b32_e32 v36, 0xffff0000, v62
	v_lshlrev_b32_e32 v35, 16, v55
	v_lshlrev_b32_e32 v34, 16, v63
	v_and_b32_e32 v33, 0xffff0000, v55
	v_and_b32_e32 v32, 0xffff0000, v63
	s_waitcnt vmcnt(1)
	v_lshlrev_b32_e32 v65, 16, v48
	s_waitcnt vmcnt(0)
	v_lshlrev_b32_e32 v64, 16, v56
	v_and_b32_e32 v77, 0xffff0000, v48
	v_and_b32_e32 v76, 0xffff0000, v56
	v_lshlrev_b32_e32 v75, 16, v49
	v_lshlrev_b32_e32 v74, 16, v57
	v_and_b32_e32 v73, 0xffff0000, v49
	v_and_b32_e32 v72, 0xffff0000, v57
	v_lshlrev_b32_e32 v71, 16, v50
	v_lshlrev_b32_e32 v70, 16, v58
	v_and_b32_e32 v69, 0xffff0000, v50
	v_and_b32_e32 v68, 0xffff0000, v58
	v_lshlrev_b32_e32 v67, 16, v51
	v_lshlrev_b32_e32 v66, 16, v59
	v_and_b32_e32 v47, 0xffff0000, v51
	v_and_b32_e32 v46, 0xffff0000, v59
	s_and_saveexec_b64 s[14:15], vcc
	s_cbranch_execz .LBB0_1309
	ds_read_b128 v[88:91], v253 offset:0
	ds_read_b128 v[92:95], v253 offset:64
	ds_read_b128 v[96:99], v253 offset:16
	ds_read_b128 v[100:103], v253 offset:80
	ds_read_b128 v[104:107], v253 offset:128
	ds_read_b128 v[108:111], v253 offset:192
	ds_read_b128 v[112:115], v253 offset:144
	ds_read_b128 v[116:119], v253 offset:208
	s_waitcnt lgkmcnt(7)
	v_mov_b32_e32 v0, v88
	s_waitcnt lgkmcnt(6)
	v_mov_b32_e32 v1, v92
	v_mov_b32_e32 v92, v89
	v_mul_f32_e32 v92, v92, v44
	v_mul_f32_e32 v93, v93, v45
	v_mov_b32_e32 v88, v90
	v_mov_b32_e32 v89, v94
	v_mov_b32_e32 v94, v91
	s_waitcnt lgkmcnt(4)
	v_mov_b32_e32 v91, v100
	v_mov_b32_e32 v100, v97
	v_mov_b32_e32 v97, v102
	v_mov_b32_e32 v102, v99
	s_waitcnt lgkmcnt(2)
	v_mov_b32_e32 v99, v108
	v_mov_b32_e32 v108, v105
	v_fma_f32 v0, v0, v14, v92
	v_fma_f32 v1, v1, v15, v93
	v_mov_b32_e32 v90, v96
	v_mov_b32_e32 v96, v98
	v_mov_b32_e32 v98, v104
	v_mul_f32_e32 v108, v108, v76
	v_mul_f32_e32 v109, v109, v77
	v_fma_f32 v0, v88, v42, v0
	v_fma_f32 v1, v89, v43, v1
	v_mov_b32_e32 v104, v106
	v_mov_b32_e32 v105, v110
	v_fma_f32 v92, v98, v64, v108
	v_fma_f32 v93, v99, v65, v109
	v_fma_f32 v0, v94, v40, v0
	v_fma_f32 v1, v95, v41, v1
	v_mov_b32_e32 v110, v107
	v_fma_f32 v88, v104, v74, v92
	v_fma_f32 v89, v105, v75, v93
	v_fma_f32 v0, v90, v38, v0
	v_fma_f32 v1, v91, v39, v1
	s_waitcnt lgkmcnt(1)
	v_mov_b32_e32 v106, v112
	s_waitcnt lgkmcnt(0)
	v_mov_b32_e32 v107, v116
	v_fma_f32 v88, v110, v72, v88
	v_fma_f32 v89, v111, v73, v89
	v_fma_f32 v0, v100, v36, v0
	v_fma_f32 v1, v101, v37, v1
	v_mov_b32_e32 v116, v113
	v_fma_f32 v88, v106, v70, v88
	v_fma_f32 v89, v107, v71, v89
	v_fma_f32 v0, v96, v34, v0
	v_fma_f32 v1, v97, v35, v1
	v_mov_b32_e32 v112, v114
	v_mov_b32_e32 v113, v118
	v_fma_f32 v88, v116, v68, v88
	v_fma_f32 v89, v117, v69, v89
	v_fma_f32 v0, v102, v32, v0
	v_fma_f32 v1, v103, v33, v1
	v_mov_b32_e32 v118, v115
	v_fma_f32 v88, v112, v66, v88
	v_fma_f32 v89, v113, v67, v89
	v_add_f32_e32 v0, 0, v0
	v_add_f32_e32 v87, v0, v1
	v_fma_f32 v0, v118, v46, v88
	v_fma_f32 v1, v119, v47, v89
	s_nop 0
	v_add_f32_e32 v0, v87, v0
	v_add_f32_e32 v87, v0, v1
.LBB0_1309:
	s_or_b64 exec, exec, s[14:15]
	ds_bpermute_b32 v0, v204, v87
	s_and_saveexec_b64 s[14:15], s[2:3]
	s_cbranch_execz .LBB0_1311
	ds_read_b128 v[88:91], v253 offset:256
	ds_read_b128 v[92:95], v253 offset:320
	ds_read_b128 v[96:99], v253 offset:272
	ds_read_b128 v[100:103], v253 offset:336
	ds_read_b128 v[104:107], v253 offset:384
	ds_read_b128 v[108:111], v253 offset:448
	ds_read_b128 v[112:115], v253 offset:400
	ds_read_b128 v[116:119], v253 offset:464
	s_waitcnt lgkmcnt(7)
	v_mov_b32_e32 v2, v88
	s_waitcnt lgkmcnt(6)
	v_mov_b32_e32 v3, v92
	v_mov_b32_e32 v92, v89
	v_mul_f32_e32 v92, v92, v44
	v_mul_f32_e32 v93, v93, v45
	v_mov_b32_e32 v88, v90
	v_mov_b32_e32 v89, v94
	v_mov_b32_e32 v94, v91
	s_waitcnt lgkmcnt(4)
	v_mov_b32_e32 v91, v100
	v_mov_b32_e32 v100, v97
	v_mov_b32_e32 v97, v102
	v_mov_b32_e32 v102, v99
	s_waitcnt lgkmcnt(2)
	v_mov_b32_e32 v99, v108
	v_mov_b32_e32 v108, v105
	v_fma_f32 v2, v2, v14, v92
	v_fma_f32 v3, v3, v15, v93
	v_mov_b32_e32 v90, v96
	v_mov_b32_e32 v96, v98
	v_mov_b32_e32 v98, v104
	v_mul_f32_e32 v108, v108, v76
	v_mul_f32_e32 v109, v109, v77
	v_fma_f32 v2, v88, v42, v2
	v_fma_f32 v3, v89, v43, v3
	v_mov_b32_e32 v104, v106
	v_mov_b32_e32 v105, v110
	v_fma_f32 v92, v98, v64, v108
	v_fma_f32 v93, v99, v65, v109
	v_fma_f32 v2, v94, v40, v2
	v_fma_f32 v3, v95, v41, v3
	v_mov_b32_e32 v110, v107
	v_fma_f32 v88, v104, v74, v92
	v_fma_f32 v89, v105, v75, v93
	v_fma_f32 v2, v90, v38, v2
	v_fma_f32 v3, v91, v39, v3
	s_waitcnt lgkmcnt(1)
	v_mov_b32_e32 v106, v112
	s_waitcnt lgkmcnt(0)
	v_mov_b32_e32 v107, v116
	v_fma_f32 v88, v110, v72, v88
	v_fma_f32 v89, v111, v73, v89
	v_fma_f32 v2, v100, v36, v2
	v_fma_f32 v3, v101, v37, v3
	v_mov_b32_e32 v116, v113
	v_fma_f32 v88, v106, v70, v88
	v_fma_f32 v89, v107, v71, v89
	v_fma_f32 v2, v96, v34, v2
	v_fma_f32 v3, v97, v35, v3
	v_mov_b32_e32 v112, v114
	v_mov_b32_e32 v113, v118
	v_fma_f32 v88, v116, v68, v88
	v_fma_f32 v89, v117, v69, v89
	v_fma_f32 v2, v102, v32, v2
	v_fma_f32 v3, v103, v33, v3
	v_mov_b32_e32 v118, v115
	v_fma_f32 v88, v112, v66, v88
	v_fma_f32 v89, v113, v67, v89
	v_add_f32_e32 v1, 0, v2
	v_add_f32_e32 v1, v1, v3
	v_fma_f32 v2, v118, v46, v88
	v_fma_f32 v3, v119, v47, v89
	s_nop 0
	v_add_f32_e32 v1, v1, v2
	v_add_f32_e32 v86, v1, v3
.LBB0_1311:
	s_or_b64 exec, exec, s[14:15]
	ds_bpermute_b32 v1, v204, v86
	v_mov_b32_e32 v3, 0
	v_mov_b32_e32 v2, 0
	s_and_saveexec_b64 s[2:3], s[4:5]
	s_cbranch_execz .LBB0_1313
	ds_read_b128 v[88:91], v253 offset:512
	ds_read_b128 v[92:95], v253 offset:576
	ds_read_b128 v[96:99], v253 offset:528
	ds_read_b128 v[100:103], v253 offset:592
	ds_read_b128 v[104:107], v253 offset:640
	ds_read_b128 v[108:111], v253 offset:704
	ds_read_b128 v[112:115], v253 offset:656
	ds_read_b128 v[116:119], v253 offset:720
	s_waitcnt lgkmcnt(7)
	v_mov_b32_e32 v4, v88
	s_waitcnt lgkmcnt(6)
	v_mov_b32_e32 v5, v92
	v_mov_b32_e32 v92, v89
	v_mul_f32_e32 v92, v92, v44
	v_mul_f32_e32 v93, v93, v45
	v_mov_b32_e32 v88, v90
	v_mov_b32_e32 v89, v94
	v_mov_b32_e32 v94, v91
	s_waitcnt lgkmcnt(4)
	v_mov_b32_e32 v91, v100
	v_mov_b32_e32 v100, v97
	v_mov_b32_e32 v97, v102
	v_mov_b32_e32 v102, v99
	s_waitcnt lgkmcnt(2)
	v_mov_b32_e32 v99, v108
	v_mov_b32_e32 v108, v105
	v_fma_f32 v4, v4, v14, v92
	v_fma_f32 v5, v5, v15, v93
	v_mov_b32_e32 v90, v96
	v_mov_b32_e32 v96, v98
	v_mov_b32_e32 v98, v104
	v_mul_f32_e32 v108, v108, v76
	v_mul_f32_e32 v109, v109, v77
	v_fma_f32 v4, v88, v42, v4
	v_fma_f32 v5, v89, v43, v5
	v_mov_b32_e32 v104, v106
	v_mov_b32_e32 v105, v110
	v_fma_f32 v92, v98, v64, v108
	v_fma_f32 v93, v99, v65, v109
	v_fma_f32 v4, v94, v40, v4
	v_fma_f32 v5, v95, v41, v5
	v_mov_b32_e32 v110, v107
	v_fma_f32 v88, v104, v74, v92
	v_fma_f32 v89, v105, v75, v93
	v_fma_f32 v4, v90, v38, v4
	v_fma_f32 v5, v91, v39, v5
	s_waitcnt lgkmcnt(1)
	v_mov_b32_e32 v106, v112
	s_waitcnt lgkmcnt(0)
	v_mov_b32_e32 v107, v116
	v_fma_f32 v88, v110, v72, v88
	v_fma_f32 v89, v111, v73, v89
	v_fma_f32 v4, v100, v36, v4
	v_fma_f32 v5, v101, v37, v5
	v_mov_b32_e32 v116, v113
	v_fma_f32 v88, v106, v70, v88
	v_fma_f32 v89, v107, v71, v89
	v_fma_f32 v4, v96, v34, v4
	v_fma_f32 v5, v97, v35, v5
	v_mov_b32_e32 v112, v114
	v_mov_b32_e32 v113, v118
	v_fma_f32 v88, v116, v68, v88
	v_fma_f32 v89, v117, v69, v89
	v_fma_f32 v4, v102, v32, v4
	v_fma_f32 v5, v103, v33, v5
	v_mov_b32_e32 v118, v115
	v_fma_f32 v88, v112, v66, v88
	v_fma_f32 v89, v113, v67, v89
	v_add_f32_e32 v2, 0, v4
	v_add_f32_e32 v2, v2, v5
	v_fma_f32 v4, v118, v46, v88
	v_fma_f32 v5, v119, v47, v89
	s_nop 0
	v_add_f32_e32 v2, v2, v4
	v_add_f32_e32 v2, v2, v5
.LBB0_1313:
	s_or_b64 exec, exec, s[2:3]
	ds_bpermute_b32 v4, v204, v2
	s_and_saveexec_b64 s[2:3], s[6:7]
	s_cbranch_execz .LBB0_1315
	ds_read_b128 v[88:91], v253 offset:768
	ds_read_b128 v[92:95], v253 offset:832
	ds_read_b128 v[96:99], v253 offset:784
	ds_read_b128 v[100:103], v253 offset:848
	ds_read_b128 v[104:107], v253 offset:896
	ds_read_b128 v[108:111], v253 offset:960
	ds_read_b128 v[112:115], v253 offset:912
	ds_read_b128 v[116:119], v253 offset:976
	s_waitcnt lgkmcnt(7)
	v_mov_b32_e32 v6, v88
	s_waitcnt lgkmcnt(6)
	v_mov_b32_e32 v7, v92
	v_mov_b32_e32 v92, v89
	v_mul_f32_e32 v92, v92, v44
	v_mul_f32_e32 v93, v93, v45
	v_mov_b32_e32 v88, v90
	v_mov_b32_e32 v89, v94
	v_mov_b32_e32 v94, v91
	s_waitcnt lgkmcnt(4)
	v_mov_b32_e32 v91, v100
	v_mov_b32_e32 v100, v97
	v_mov_b32_e32 v97, v102
	v_mov_b32_e32 v102, v99
	s_waitcnt lgkmcnt(2)
	v_mov_b32_e32 v99, v108
	v_mov_b32_e32 v108, v105
	v_fma_f32 v6, v6, v14, v92
	v_fma_f32 v7, v7, v15, v93
	v_mov_b32_e32 v90, v96
	v_mov_b32_e32 v96, v98
	v_mov_b32_e32 v98, v104
	v_mul_f32_e32 v108, v108, v76
	v_mul_f32_e32 v109, v109, v77
	v_fma_f32 v6, v88, v42, v6
	v_fma_f32 v7, v89, v43, v7
	v_mov_b32_e32 v104, v106
	v_mov_b32_e32 v105, v110
	v_fma_f32 v92, v98, v64, v108
	v_fma_f32 v93, v99, v65, v109
	v_fma_f32 v6, v94, v40, v6
	v_fma_f32 v7, v95, v41, v7
	v_mov_b32_e32 v110, v107
	v_fma_f32 v88, v104, v74, v92
	v_fma_f32 v89, v105, v75, v93
	v_fma_f32 v6, v90, v38, v6
	v_fma_f32 v7, v91, v39, v7
	s_waitcnt lgkmcnt(1)
	v_mov_b32_e32 v106, v112
	s_waitcnt lgkmcnt(0)
	v_mov_b32_e32 v107, v116
	v_fma_f32 v88, v110, v72, v88
	v_fma_f32 v89, v111, v73, v89
	v_fma_f32 v6, v100, v36, v6
	v_fma_f32 v7, v101, v37, v7
	v_mov_b32_e32 v116, v113
	v_fma_f32 v88, v106, v70, v88
	v_fma_f32 v89, v107, v71, v89
	v_fma_f32 v6, v96, v34, v6
	v_fma_f32 v7, v97, v35, v7
	v_mov_b32_e32 v112, v114
	v_mov_b32_e32 v113, v118
	v_fma_f32 v88, v116, v68, v88
	v_fma_f32 v89, v117, v69, v89
	v_fma_f32 v6, v102, v32, v6
	v_fma_f32 v7, v103, v33, v7
	v_mov_b32_e32 v118, v115
	v_fma_f32 v88, v112, v66, v88
	v_fma_f32 v89, v113, v67, v89
	v_add_f32_e32 v3, 0, v6
	v_add_f32_e32 v3, v3, v7
	v_fma_f32 v6, v118, v46, v88
	v_fma_f32 v7, v119, v47, v89
	s_nop 0
	v_add_f32_e32 v3, v3, v6
	v_add_f32_e32 v3, v3, v7
.LBB0_1315:
	s_or_b64 exec, exec, s[2:3]
	ds_bpermute_b32 v5, v204, v3
	v_mov_b32_e32 v7, 0
	v_mov_b32_e32 v6, 0
	s_and_saveexec_b64 s[2:3], s[8:9]
	s_cbranch_execz .LBB0_1317
	ds_read_b128 v[88:91], v253 offset:1024
	ds_read_b128 v[92:95], v253 offset:1088
	ds_read_b128 v[96:99], v253 offset:1040
	ds_read_b128 v[100:103], v253 offset:1104
	ds_read_b128 v[104:107], v253 offset:1152
	ds_read_b128 v[108:111], v253 offset:1216
	ds_read_b128 v[112:115], v253 offset:1168
	ds_read_b128 v[116:119], v253 offset:1232
	s_waitcnt lgkmcnt(7)
	v_mov_b32_e32 v8, v88
	s_waitcnt lgkmcnt(6)
	v_mov_b32_e32 v9, v92
	v_mov_b32_e32 v92, v89
	v_mul_f32_e32 v92, v92, v44
	v_mul_f32_e32 v93, v93, v45
	v_mov_b32_e32 v88, v90
	v_mov_b32_e32 v89, v94
	v_mov_b32_e32 v94, v91
	s_waitcnt lgkmcnt(4)
	v_mov_b32_e32 v91, v100
	v_mov_b32_e32 v100, v97
	v_mov_b32_e32 v97, v102
	v_mov_b32_e32 v102, v99
	s_waitcnt lgkmcnt(2)
	v_mov_b32_e32 v99, v108
	v_mov_b32_e32 v108, v105
	v_fma_f32 v8, v8, v14, v92
	v_fma_f32 v9, v9, v15, v93
	v_mov_b32_e32 v90, v96
	v_mov_b32_e32 v96, v98
	v_mov_b32_e32 v98, v104
	v_mul_f32_e32 v108, v108, v76
	v_mul_f32_e32 v109, v109, v77
	v_fma_f32 v8, v88, v42, v8
	v_fma_f32 v9, v89, v43, v9
	v_mov_b32_e32 v104, v106
	v_mov_b32_e32 v105, v110
	v_fma_f32 v92, v98, v64, v108
	v_fma_f32 v93, v99, v65, v109
	v_fma_f32 v8, v94, v40, v8
	v_fma_f32 v9, v95, v41, v9
	v_mov_b32_e32 v110, v107
	v_fma_f32 v88, v104, v74, v92
	v_fma_f32 v89, v105, v75, v93
	v_fma_f32 v8, v90, v38, v8
	v_fma_f32 v9, v91, v39, v9
	s_waitcnt lgkmcnt(1)
	v_mov_b32_e32 v106, v112
	s_waitcnt lgkmcnt(0)
	v_mov_b32_e32 v107, v116
	v_fma_f32 v88, v110, v72, v88
	v_fma_f32 v89, v111, v73, v89
	v_fma_f32 v8, v100, v36, v8
	v_fma_f32 v9, v101, v37, v9
	v_mov_b32_e32 v116, v113
	v_fma_f32 v88, v106, v70, v88
	v_fma_f32 v89, v107, v71, v89
	v_fma_f32 v8, v96, v34, v8
	v_fma_f32 v9, v97, v35, v9
	v_mov_b32_e32 v112, v114
	v_mov_b32_e32 v113, v118
	v_fma_f32 v88, v116, v68, v88
	v_fma_f32 v89, v117, v69, v89
	v_fma_f32 v8, v102, v32, v8
	v_fma_f32 v9, v103, v33, v9
	v_mov_b32_e32 v118, v115
	v_fma_f32 v88, v112, v66, v88
	v_fma_f32 v89, v113, v67, v89
	v_add_f32_e32 v6, 0, v8
	v_add_f32_e32 v6, v6, v9
	v_fma_f32 v8, v118, v46, v88
	v_fma_f32 v9, v119, v47, v89
	s_nop 0
	v_add_f32_e32 v6, v6, v8
	v_add_f32_e32 v6, v6, v9
.LBB0_1317:
	s_or_b64 exec, exec, s[2:3]
	ds_bpermute_b32 v8, v204, v6
	s_and_saveexec_b64 s[2:3], s[10:11]
	s_cbranch_execz .LBB0_1319
	ds_read_b128 v[88:91], v253 offset:1280
	ds_read_b128 v[92:95], v253 offset:1344
	ds_read_b128 v[96:99], v253 offset:1296
	ds_read_b128 v[100:103], v253 offset:1360
	ds_read_b128 v[104:107], v253 offset:1408
	ds_read_b128 v[108:111], v253 offset:1472
	ds_read_b128 v[112:115], v253 offset:1424
	ds_read_b128 v[116:119], v253 offset:1488
	s_waitcnt lgkmcnt(7)
	v_mov_b32_e32 v10, v88
	s_waitcnt lgkmcnt(6)
	v_mov_b32_e32 v11, v92
	v_mov_b32_e32 v92, v89
	v_mul_f32_e32 v92, v92, v44
	v_mul_f32_e32 v93, v93, v45
	v_mov_b32_e32 v88, v90
	v_mov_b32_e32 v89, v94
	v_mov_b32_e32 v94, v91
	s_waitcnt lgkmcnt(4)
	v_mov_b32_e32 v91, v100
	v_mov_b32_e32 v100, v97
	v_mov_b32_e32 v97, v102
	v_mov_b32_e32 v102, v99
	s_waitcnt lgkmcnt(2)
	v_mov_b32_e32 v99, v108
	v_mov_b32_e32 v108, v105
	v_fma_f32 v10, v10, v14, v92
	v_fma_f32 v11, v11, v15, v93
	v_mov_b32_e32 v90, v96
	v_mov_b32_e32 v96, v98
	v_mov_b32_e32 v98, v104
	v_mul_f32_e32 v108, v108, v76
	v_mul_f32_e32 v109, v109, v77
	v_fma_f32 v10, v88, v42, v10
	v_fma_f32 v11, v89, v43, v11
	v_mov_b32_e32 v104, v106
	v_mov_b32_e32 v105, v110
	v_fma_f32 v92, v98, v64, v108
	v_fma_f32 v93, v99, v65, v109
	v_fma_f32 v10, v94, v40, v10
	v_fma_f32 v11, v95, v41, v11
	v_mov_b32_e32 v110, v107
	v_fma_f32 v88, v104, v74, v92
	v_fma_f32 v89, v105, v75, v93
	v_fma_f32 v10, v90, v38, v10
	v_fma_f32 v11, v91, v39, v11
	s_waitcnt lgkmcnt(1)
	v_mov_b32_e32 v106, v112
	s_waitcnt lgkmcnt(0)
	v_mov_b32_e32 v107, v116
	v_fma_f32 v88, v110, v72, v88
	v_fma_f32 v89, v111, v73, v89
	v_fma_f32 v10, v100, v36, v10
	v_fma_f32 v11, v101, v37, v11
	v_mov_b32_e32 v116, v113
	v_fma_f32 v88, v106, v70, v88
	v_fma_f32 v89, v107, v71, v89
	v_fma_f32 v10, v96, v34, v10
	v_fma_f32 v11, v97, v35, v11
	v_mov_b32_e32 v112, v114
	v_mov_b32_e32 v113, v118
	v_fma_f32 v88, v116, v68, v88
	v_fma_f32 v89, v117, v69, v89
	v_fma_f32 v10, v102, v32, v10
	v_fma_f32 v11, v103, v33, v11
	v_mov_b32_e32 v118, v115
	v_fma_f32 v88, v112, v66, v88
	v_fma_f32 v89, v113, v67, v89
	v_add_f32_e32 v7, 0, v10
	v_add_f32_e32 v7, v7, v11
	v_fma_f32 v10, v118, v46, v88
	v_fma_f32 v11, v119, v47, v89
	s_nop 0
	v_add_f32_e32 v7, v7, v10
	v_add_f32_e32 v7, v7, v11
.LBB0_1319:
	s_or_b64 exec, exec, s[2:3]
	ds_bpermute_b32 v9, v204, v7
	v_mov_b32_e32 v10, 0
	s_and_saveexec_b64 s[2:3], s[12:13]
	s_cbranch_execz .LBB0_1321
	ds_read_b128 v[88:91], v253 offset:1536
	ds_read_b128 v[92:95], v253 offset:1600
	ds_read_b128 v[96:99], v253 offset:1552
	ds_read_b128 v[100:103], v253 offset:1616
	ds_read_b128 v[104:107], v253 offset:1664
	ds_read_b128 v[108:111], v253 offset:1728
	ds_read_b128 v[112:115], v253 offset:1680
	s_nop 0
	ds_read_b128 v[10:13], v253 offset:1744
	s_waitcnt lgkmcnt(7)
	v_mov_b32_e32 v116, v88
	s_waitcnt lgkmcnt(6)
	v_mov_b32_e32 v117, v92
	v_mov_b32_e32 v92, v89
	v_mul_f32_e32 v44, v92, v44
	v_mul_f32_e32 v45, v93, v45
	v_mov_b32_e32 v88, v90
	v_mov_b32_e32 v89, v94
	v_mov_b32_e32 v94, v91
	s_waitcnt lgkmcnt(4)
	v_mov_b32_e32 v91, v100
	v_mov_b32_e32 v100, v97
	v_mov_b32_e32 v97, v102
	v_mov_b32_e32 v102, v99
	s_waitcnt lgkmcnt(2)
	v_mov_b32_e32 v99, v108
	v_mov_b32_e32 v108, v105
	v_fma_f32 v14, v116, v14, v44
	v_fma_f32 v15, v117, v15, v45
	v_mov_b32_e32 v90, v96
	v_mov_b32_e32 v96, v98
	v_mov_b32_e32 v98, v104
	v_mul_f32_e32 v76, v108, v76
	v_mul_f32_e32 v77, v109, v77
	v_fma_f32 v14, v88, v42, v14
	v_fma_f32 v15, v89, v43, v15
	v_mov_b32_e32 v104, v106
	v_mov_b32_e32 v105, v110
	v_fma_f32 v44, v98, v64, v76
	v_fma_f32 v45, v99, v65, v77
	v_fma_f32 v14, v94, v40, v14
	v_fma_f32 v15, v95, v41, v15
	v_mov_b32_e32 v110, v107
	v_fma_f32 v42, v104, v74, v44
	v_fma_f32 v43, v105, v75, v45
	v_fma_f32 v14, v90, v38, v14
	v_fma_f32 v15, v91, v39, v15
	s_waitcnt lgkmcnt(1)
	v_mov_b32_e32 v106, v112
	s_waitcnt lgkmcnt(0)
	v_mov_b32_e32 v107, v10
	v_fma_f32 v40, v110, v72, v42
	v_fma_f32 v41, v111, v73, v43
	v_fma_f32 v14, v100, v36, v14
	v_fma_f32 v15, v101, v37, v15
	v_mov_b32_e32 v10, v113
	v_fma_f32 v38, v106, v70, v40
	v_fma_f32 v39, v107, v71, v41
	v_fma_f32 v14, v96, v34, v14
	v_fma_f32 v15, v97, v35, v15
	v_mov_b32_e32 v112, v114
	v_mov_b32_e32 v113, v12
	v_fma_f32 v10, v10, v68, v38
	v_fma_f32 v11, v11, v69, v39
	v_fma_f32 v14, v102, v32, v14
	v_fma_f32 v15, v103, v33, v15
	v_mov_b32_e32 v12, v115
	v_fma_f32 v10, v112, v66, v10
	v_fma_f32 v11, v113, v67, v11
	v_add_f32_e32 v14, 0, v14
	v_add_f32_e32 v14, v14, v15
	v_fma_f32 v10, v12, v46, v10
	v_fma_f32 v11, v13, v47, v11
	s_nop 0
	v_add_f32_e32 v10, v14, v10
	v_add_f32_e32 v10, v10, v11

.LBB0_1326:
	s_lshr_b32 s0, s0, 2
	s_lshl_b32 s0, 1, s0
	v_and_b32_e32 v64, s0, v205
	v_and_b32_e32 v65, s0, v175
	v_cmp_ne_u32_e64 s[4:5], 0, v64
	v_cmp_ne_u32_e32 vcc, 0, v65
	v_cmp_le_i32_e64 s[6:7], s18, v206
	v_cmp_le_i32_e64 s[2:3], s18, v207
	s_and_b64 s[6:7], s[6:7], s[4:5]
	s_and_b64 s[2:3], s[2:3], vcc
	s_cmp_lg_u64 s[6:7], 0
	s_cselect_b64 s[6:7], -1, 0
	s_cmp_lg_u64 s[2:3], 0
	s_cselect_b64 s[2:3], -1, 0
	v_cndmask_b32_e64 v64, 0, 1, s[6:7]
	v_cndmask_b32_e64 v168, 0, 1, s[2:3]
	s_or_b64 s[0:1], s[6:7], s[2:3]
	s_and_saveexec_b64 s[12:13], s[0:1]
	s_cbranch_execz .LBB0_1338
	v_add_u32_e32 v65, s19, v208
	v_subrev_u32_e32 v66, 63, v65
	v_cmp_gt_i32_e64 s[8:9], s87, v66
	v_cndmask_b32_e64 v215, 0, v202, s[4:5]
	s_cmp_eq_u32 s97, 0
	v_cndmask_b32_e64 v66, 0, v198, s[8:9]
	v_or3_b32 v216, v215, v66, v64
	s_waitcnt lgkmcnt(8)
	v_cndmask_b32_e64 v64, v203, v212, s[4:5]
	v_cndmask_b32_e64 v64, v64, 0, s[8:9]
	s_cselect_b64 s[8:9], -1, 0
	s_and_b64 s[0:1], s[8:9], exec
	s_cselect_b32 s0, 0, 0x2400
	v_subrev_u32_e32 v65, 31, v65
	v_add_u32_e32 v217, s0, v209
	v_cmp_gt_i32_e64 s[4:5], s87, v65
	v_cndmask_b32_e32 v65, v203, v212, vcc
	ds_read_b128 v[186:189], v217 offset:4608
	ds_read_b128 v[190:193], v217
	ds_read_b128 v[194:197], v217 offset:32
	v_cndmask_b32_e64 v65, v65, 0, s[4:5]
	v_cndmask_b32_e64 v252, v203, v64, s[6:7]
	v_cndmask_b32_e64 v253, v203, v65, s[2:3]
	s_waitcnt lgkmcnt(1)
	v_mfma_f32_32x32x16_bf16 v[96:111], v[190:193], v[128:131], 0
	v_mfma_f32_32x32x16_bf16 v[112:127], v[190:193], v[148:151], 0
	v_mfma_f32_32x32x16_bf16 v[80:95], v[186:189], v[128:131], 0
	v_mfma_f32_32x32x16_bf16 v[64:79], v[186:189], v[148:151], 0
	ds_read_b128 v[186:189], v217 offset:4640
	s_waitcnt lgkmcnt(1)
	v_mfma_f32_32x32x16_bf16 v[96:111], v[194:197], v[132:135], v[96:111]
	v_mfma_f32_32x32x16_bf16 v[112:127], v[194:197], v[140:143], v[112:127]
	s_waitcnt lgkmcnt(0)
	v_mfma_f32_32x32x16_bf16 v[80:95], v[186:189], v[132:135], v[80:95]
	v_mfma_f32_32x32x16_bf16 v[64:79], v[186:189], v[140:143], v[64:79]
	ds_read_b128 v[186:189], v217 offset:64
	ds_read_b128 v[190:193], v217 offset:4672
	s_waitcnt lgkmcnt(1)
	v_mfma_f32_32x32x16_bf16 v[96:111], v[186:189], v[136:139], v[96:111]
	v_mfma_f32_32x32x16_bf16 v[112:127], v[186:189], v[144:147], v[112:127]
	s_waitcnt lgkmcnt(0)
	v_mfma_f32_32x32x16_bf16 v[80:95], v[190:193], v[136:139], v[80:95]
	v_mfma_f32_32x32x16_bf16 v[64:79], v[190:193], v[144:147], v[64:79]
	ds_read_b128 v[186:189], v217 offset:96
	ds_read_b128 v[190:193], v217 offset:4704
	s_waitcnt lgkmcnt(1)
	v_mfma_f32_32x32x16_bf16 v[96:111], v[186:189], v[152:155], v[96:111]
	v_mfma_f32_32x32x16_bf16 v[112:127], v[186:189], v[156:159], v[112:127]
	v_cndmask_b32_e64 v186, v215, v216, s[6:7]
	v_and_b32_e32 v187, 0x100, v186
	v_cmp_ne_u32_e64 s[6:7], 0, v187
	s_waitcnt lgkmcnt(0)
	v_mfma_f32_32x32x16_bf16 v[80:95], v[190:193], v[152:155], v[80:95]
	v_mfma_f32_32x32x16_bf16 v[64:79], v[190:193], v[156:159], v[64:79]
	v_add_u32_e32 v190, s19, v211
	s_and_saveexec_b64 s[14:15], s[6:7]
	s_cbranch_execz .LBB0_1333
	v_lshl_add_u32 v224, v190, 2, s91
	v_and_b32_e32 v186, 0x10000, v186
	v_cmp_ne_u32_e64 s[6:7], 0, v186
	v_mov_b32_e32 v225, 0x1d000
	s_nop 1
	v_cndmask_b32_e64 v224, v225, v224, s[6:7]
	ds_read2_b32 v[226:227], v224 offset0:59 offset1:58
	ds_read2_b32 v[228:229], v224 offset0:57 offset1:56
	ds_read2_b32 v[230:231], v224 offset0:51 offset1:50
	ds_read2_b32 v[232:233], v224 offset0:49 offset1:48
	ds_read2_b32 v[234:235], v224 offset0:43 offset1:42
	ds_read2_b32 v[236:237], v224 offset0:41 offset1:40
	ds_read2_b32 v[238:239], v224 offset0:35 offset1:34
	ds_read2_b32 v[240:241], v224 offset0:33 offset1:32
	ds_read2_b32 v[242:243], v224 offset0:27 offset1:26
	ds_read2_b32 v[244:245], v224 offset0:25 offset1:24
	ds_read2_b32 v[246:247], v224 offset0:19 offset1:18
	ds_read2_b32 v[248:249], v224 offset0:17 offset1:16
	ds_read2_b32 v[250:251], v224 offset0:11 offset1:10
	s_waitcnt lgkmcnt(5)
	v_add_f32_e32 v96, v96, v226
	v_add_f32_e32 v97, v97, v227
	v_add_f32_e32 v98, v98, v228
	v_add_f32_e32 v99, v99, v229
	v_add_f32_e32 v100, v100, v230
	v_add_f32_e32 v101, v101, v231
	v_add_f32_e32 v102, v102, v232
	v_add_f32_e32 v103, v103, v233
	v_add_f32_e32 v104, v104, v234
	v_add_f32_e32 v105, v105, v235
	v_add_f32_e32 v106, v106, v236
	v_add_f32_e32 v107, v107, v237
	v_add_f32_e32 v108, v108, v238
	v_add_f32_e32 v109, v109, v239
	v_add_f32_e32 v110, v110, v240
	v_add_f32_e32 v111, v111, v241
	ds_read2_b32 v[226:227], v224 offset0:9 offset1:8
	ds_read2_b32 v[228:229], v224 offset0:3 offset1:2
	ds_read2_b32 v[230:231], v224 offset0:1 offset1:0
	s_waitcnt lgkmcnt(3)
	v_add_f32_e32 v80, v80, v242
	v_add_f32_e32 v81, v81, v243
	v_add_f32_e32 v82, v82, v244
	v_add_f32_e32 v83, v83, v245
	v_add_f32_e32 v84, v84, v246
	v_add_f32_e32 v85, v85, v247
	v_add_f32_e32 v86, v86, v248
	v_add_f32_e32 v87, v87, v249
	v_add_f32_e32 v88, v88, v250
	v_add_f32_e32 v89, v89, v251
	s_waitcnt lgkmcnt(0)
	v_add_f32_e32 v90, v90, v226
	v_add_f32_e32 v91, v91, v227
	v_add_f32_e32 v92, v92, v228
	v_add_f32_e32 v93, v93, v229
	v_add_f32_e32 v94, v94, v230
	v_add_f32_e32 v95, v95, v231
.LBB0_1333:
	s_or_b64 exec, exec, s[14:15]
	v_cndmask_b32_e32 v186, 0, v202, vcc
	v_cndmask_b32_e64 v187, 0, v198, s[4:5]
	v_or3_b32 v168, v186, v187, v168
	v_cndmask_b32_e64 v168, v186, v168, s[2:3]
	v_and_b32_e32 v186, 0x100, v168
	v_cmp_ne_u32_e32 vcc, 0, v186
	s_and_saveexec_b64 s[2:3], vcc
	s_cbranch_execz .LBB0_1335
	v_lshl_add_u32 v224, v190, 2, s32
	v_and_b32_e32 v187, 0x10000, v168
	v_cmp_ne_u32_e32 vcc, 0, v187
	v_mov_b32_e32 v225, 0x1d000
	s_nop 1
	v_cndmask_b32_e32 v224, v225, v224, vcc
	ds_read2_b32 v[226:227], v224 offset0:59 offset1:58
	ds_read2_b32 v[228:229], v224 offset0:57 offset1:56
	ds_read2_b32 v[230:231], v224 offset0:51 offset1:50
	ds_read2_b32 v[232:233], v224 offset0:49 offset1:48
	ds_read2_b32 v[234:235], v224 offset0:43 offset1:42
	ds_read2_b32 v[236:237], v224 offset0:41 offset1:40
	ds_read2_b32 v[238:239], v224 offset0:35 offset1:34
	ds_read2_b32 v[240:241], v224 offset0:33 offset1:32
	ds_read2_b32 v[242:243], v224 offset0:27 offset1:26
	ds_read2_b32 v[244:245], v224 offset0:25 offset1:24
	ds_read2_b32 v[246:247], v224 offset0:19 offset1:18
	ds_read2_b32 v[248:249], v224 offset0:17 offset1:16
	ds_read2_b32 v[250:251], v224 offset0:11 offset1:10
	s_waitcnt lgkmcnt(5)
	v_add_f32_e32 v112, v112, v226
	v_add_f32_e32 v113, v113, v227
	v_add_f32_e32 v114, v114, v228
	v_add_f32_e32 v115, v115, v229
	v_add_f32_e32 v116, v116, v230
	v_add_f32_e32 v117, v117, v231
	v_add_f32_e32 v118, v118, v232
	v_add_f32_e32 v119, v119, v233
	v_add_f32_e32 v120, v120, v234
	v_add_f32_e32 v121, v121, v235
	v_add_f32_e32 v122, v122, v236
	v_add_f32_e32 v123, v123, v237
	v_add_f32_e32 v124, v124, v238
	v_add_f32_e32 v125, v125, v239
	v_add_f32_e32 v126, v126, v240
	v_add_f32_e32 v127, v127, v241
	ds_read2_b32 v[226:227], v224 offset0:9 offset1:8
	ds_read2_b32 v[228:229], v224 offset0:3 offset1:2
	ds_read2_b32 v[230:231], v224 offset0:1 offset1:0
	s_waitcnt lgkmcnt(3)
	v_add_f32_e32 v64, v64, v242
	v_add_f32_e32 v65, v65, v243
	v_add_f32_e32 v66, v66, v244
	v_add_f32_e32 v67, v67, v245
	v_add_f32_e32 v68, v68, v246
	v_add_f32_e32 v69, v69, v247
	v_add_f32_e32 v70, v70, v248
	v_add_f32_e32 v71, v71, v249
	v_add_f32_e32 v72, v72, v250
	v_add_f32_e32 v73, v73, v251
	s_waitcnt lgkmcnt(0)
	v_add_f32_e32 v74, v74, v226
	v_add_f32_e32 v75, v75, v227
	v_add_f32_e32 v76, v76, v228
	v_add_f32_e32 v77, v77, v229
	v_add_f32_e32 v78, v78, v230
	v_add_f32_e32 v79, v79, v231
.LBB0_1335:
	s_or_b64 exec, exec, s[2:3]
	v_max_f32_e32 v168, v96, v80
	v_max_f32_e32 v186, v97, v81
	v_max_f32_e32 v187, v99, v83
	v_max3_f32 v188, v98, v82, v102
	v_max3_f32 v187, v187, v103, v87
	v_max3_f32 v168, v168, v100, v84
	v_max3_f32 v186, v186, v101, v85
	v_max3_f32 v188, v188, v86, v106
	v_max3_f32 v187, v187, v107, v91
	v_max3_f32 v168, v168, v104, v88
	v_max3_f32 v186, v186, v105, v89
	v_max3_f32 v188, v188, v90, v110
	v_max3_f32 v187, v187, v111, v95
	v_max3_f32 v168, v168, v108, v92
	v_max3_f32 v186, v186, v109, v93
	v_max3_f32 v187, v188, v94, v187
	v_max3_f32 v168, v168, v186, v187
	v_max_f32_e32 v186, v112, v64
	v_max_f32_e32 v187, v113, v65
	v_max_f32_e32 v188, v115, v67
	v_max3_f32 v189, v114, v66, v118
	v_max3_f32 v188, v188, v119, v71
	v_max3_f32 v186, v186, v116, v68
	v_max3_f32 v187, v187, v117, v69
	v_max3_f32 v189, v189, v70, v122
	v_max3_f32 v188, v188, v123, v75
	v_max3_f32 v186, v186, v120, v72
	v_max3_f32 v187, v187, v121, v73
	v_max3_f32 v189, v189, v74, v126
	v_max3_f32 v188, v188, v127, v79
	v_max3_f32 v186, v186, v124, v76
	v_max3_f32 v187, v187, v125, v77
	v_max3_f32 v188, v189, v78, v188
	v_max3_f32 v187, v186, v187, v188
	v_mov_b32_e32 v189, v168
	v_mov_b32_e32 v188, v187
	s_nop 1
	v_permlane32_swap_b32_e32 v168, v189
	v_permlane32_swap_b32_e32 v187, v188
	v_max_f32_e32 v186, v168, v189
	v_max_f32_e32 v168, v187, v188
	v_add_f32_e32 v186, v186, v252
	v_add_f32_e32 v168, v168, v253
	v_add_f32_e32 v187, 0x42317218, v214
	v_cmp_gt_f32_e32 vcc, v186, v187
	v_add_f32_e32 v187, 0x42317218, v213
	v_cmp_gt_f32_e64 s[2:3], v168, v187
	s_or_b64 vcc, vcc, s[2:3]
	s_cbranch_vccz .LBB0_1337
	v_max_f32_e32 v186, v186, v186
	v_max_f32_e32 v187, v214, v214
	v_max_f32_e32 v188, v187, v186
	v_max_f32_e32 v168, v168, v168
	v_max_f32_e32 v186, v213, v213
	v_cmp_ngt_f32_e32 vcc, s88, v188
	v_max_f32_e32 v189, v186, v168
	s_nop 0
	v_cndmask_b32_e32 v168, 0, v188, vcc
	v_sub_f32_e32 v168, v214, v168
	v_mul_f32_e32 v168, 0x3e38aa3b, v168
	v_cmp_ngt_f32_e32 vcc, s88, v189
	v_exp_f32_e32 v187, v168
	v_mov_b32_e32 v214, v188
	v_cndmask_b32_e32 v168, 0, v189, vcc
	v_sub_f32_e32 v168, v213, v168
	v_mul_f32_e32 v168, 0x3e38aa3b, v168
	v_exp_f32_e32 v186, v168
	v_mov_b32_e32 v168, v187
	v_mul_f32_e32 v62, v62, v168
	v_mul_f32_e32 v63, v63, v168
	v_mul_f32_e32 v60, v60, v168
	v_mul_f32_e32 v61, v61, v168
	v_mul_f32_e32 v178, v178, v186
	v_mul_f32_e32 v179, v179, v187
	v_mul_f32_e32 v58, v58, v168
	v_mul_f32_e32 v59, v59, v168
	v_mul_f32_e32 v56, v56, v168
	v_mul_f32_e32 v57, v57, v168
	v_mul_f32_e32 v54, v54, v168
	v_mul_f32_e32 v55, v55, v168
	v_mul_f32_e32 v52, v52, v168
	v_mul_f32_e32 v53, v53, v168
	v_mul_f32_e32 v50, v50, v168
	v_mul_f32_e32 v51, v51, v168
	v_mul_f32_e32 v48, v48, v168
	v_mul_f32_e32 v49, v49, v168
	v_mul_f32_e32 v14, v14, v186
	v_mul_f32_e32 v15, v15, v186
	v_mul_f32_e32 v12, v12, v186
	v_mul_f32_e32 v13, v13, v186
	v_mul_f32_e32 v10, v10, v186
	v_mul_f32_e32 v11, v11, v186
	v_mul_f32_e32 v8, v8, v186
	v_mul_f32_e32 v9, v9, v186
	v_mul_f32_e32 v6, v6, v186
	v_mul_f32_e32 v7, v7, v186
	v_mul_f32_e32 v4, v4, v186
	v_mul_f32_e32 v5, v5, v186
	v_mul_f32_e32 v2, v2, v186
	v_mul_f32_e32 v3, v3, v186
	v_mul_f32_e32 v0, v0, v186
	v_mul_f32_e32 v1, v1, v186
	v_mul_f32_e32 v46, v46, v168
	v_mul_f32_e32 v47, v47, v168
	v_mul_f32_e32 v44, v44, v168
	v_mul_f32_e32 v45, v45, v168
	v_mul_f32_e32 v42, v42, v168
	v_mul_f32_e32 v43, v43, v168
	v_mul_f32_e32 v40, v40, v168
	v_mul_f32_e32 v41, v41, v168
	v_mul_f32_e32 v38, v38, v168
	v_mul_f32_e32 v39, v39, v168
	v_mul_f32_e32 v36, v36, v168
	v_mul_f32_e32 v37, v37, v168
	v_mul_f32_e32 v34, v34, v168
	v_mul_f32_e32 v35, v35, v168
	v_mul_f32_e32 v32, v32, v168
	v_mul_f32_e32 v33, v33, v168
	v_mul_f32_e32 v30, v30, v186
	v_mul_f32_e32 v31, v31, v186
	v_mul_f32_e32 v28, v28, v186
	v_mul_f32_e32 v29, v29, v186
	v_mul_f32_e32 v26, v26, v186
	v_mul_f32_e32 v27, v27, v186
	v_mul_f32_e32 v24, v24, v186
	v_mul_f32_e32 v25, v25, v186
	v_mul_f32_e32 v22, v22, v186
	v_mul_f32_e32 v23, v23, v186
	v_mul_f32_e32 v20, v20, v186
	v_mul_f32_e32 v21, v21, v186
	v_mul_f32_e32 v18, v18, v186
	v_mul_f32_e32 v19, v19, v186
	v_mul_f32_e32 v16, v16, v186
	v_mul_f32_e32 v17, v17, v186
	v_mov_b32_e32 v213, v189
.LBB0_1337:
	v_mul_f32_e32 v168, 0x3e38aa3b, v214
	v_cmp_ngt_f32_e32 vcc, s88, v214
	v_mul_f32_e32 v186, 0x3e38aa3b, v213
	s_and_b64 s[0:1], s[8:9], exec
	v_cndmask_b32_e32 v168, 0, v168, vcc
	v_fma_f32 v168, -v252, s89, v168
	v_cmp_ngt_f32_e32 vcc, s88, v213
	v_fma_f32 v96, v96, s89, -v168
	v_exp_f32_e32 v187, v96
	v_cndmask_b32_e32 v215, 0, v186, vcc
	v_fma_f32 v215, -v253, s89, v215
	v_fma_f32 v64, v64, s89, -v215
	v_exp_f32_e32 v186, v64
	v_fma_f32 v64, v97, s89, -v168
	v_exp_f32_e32 v97, v64
	v_fma_f32 v64, v113, s89, -v215
	v_fma_f32 v96, v112, s89, -v215
	v_exp_f32_e32 v112, v64
	v_fma_f32 v64, v81, s89, -v168
	v_exp_f32_e32 v113, v64
	v_fma_f32 v64, v65, s89, -v215
	v_exp_f32_e32 v188, v96
	v_exp_f32_e32 v96, v64
	v_fma_f32 v64, v98, s89, -v168
	v_exp_f32_e32 v65, v64
	v_fma_f32 v64, v114, s89, -v215
	v_exp_f32_e32 v190, v64
	v_fma_f32 v64, v82, s89, -v168
	v_exp_f32_e32 v191, v64
	v_fma_f32 v64, v66, s89, -v215
	v_fma_f32 v66, v99, s89, -v168
	v_exp_f32_e32 v81, v66
	v_fma_f32 v66, v115, s89, -v215
	v_exp_f32_e32 v98, v66
	v_fma_f32 v66, v83, s89, -v168
	v_fma_f32 v80, v80, s89, -v168
	v_exp_f32_e32 v99, v66
	v_fma_f32 v66, v67, s89, -v215
	v_exp_f32_e32 v189, v80
	v_exp_f32_e32 v80, v66
	v_fma_f32 v66, v100, s89, -v168
	v_exp_f32_e32 v67, v66
	v_fma_f32 v66, v116, s89, -v215
	v_exp_f32_e32 v114, v66
	v_fma_f32 v66, v84, s89, -v168
	v_exp_f32_e32 v115, v66
	v_fma_f32 v66, v68, s89, -v215
	v_fma_f32 v68, v101, s89, -v168
	v_exp_f32_e32 v83, v68
	v_fma_f32 v68, v117, s89, -v215
	v_exp_f32_e32 v192, v68
	v_fma_f32 v68, v85, s89, -v168
	v_add_f32_e32 v84, 0, v188
	v_add_f32_e32 v85, 0, v189
	v_exp_f32_e32 v193, v68
	v_fma_f32 v68, v69, s89, -v215
	v_add_f32_e32 v84, v112, v84
	v_add_f32_e32 v85, v113, v85
	v_exp_f32_e32 v82, v68
	v_fma_f32 v68, v102, s89, -v168
	v_add_f32_e32 v84, v190, v84
	v_add_f32_e32 v85, v191, v85
	v_exp_f32_e32 v69, v68
	v_fma_f32 v68, v118, s89, -v215
	v_add_f32_e32 v84, v98, v84
	v_add_f32_e32 v85, v99, v85
	v_exp_f32_e32 v194, v68
	v_fma_f32 v68, v86, s89, -v168
	v_add_f32_e32 v84, v114, v84
	v_add_f32_e32 v85, v115, v85
	v_exp_f32_e32 v195, v68
	v_fma_f32 v68, v70, s89, -v215
	v_add_f32_e32 v196, v192, v84
	v_add_f32_e32 v197, v193, v85
	v_fma_f32 v70, v103, s89, -v168
	v_fma_f32 v84, v105, s89, -v168
	v_exp_f32_e32 v85, v70
	v_fma_f32 v70, v119, s89, -v215
	v_exp_f32_e32 v103, v84
	v_fma_f32 v84, v121, s89, -v215
	v_exp_f32_e32 v86, v70
	v_fma_f32 v70, v104, s89, -v168
	v_exp_f32_e32 v104, v84
	v_fma_f32 v84, v106, s89, -v168
	v_exp_f32_e32 v117, v84
	v_fma_f32 v84, v122, s89, -v215
	s_cselect_b32 s0, s92, 0x7800
	v_exp_f32_e32 v106, v84
	v_fma_f32 v84, v107, s89, -v168
	v_add_u32_e32 v234, s0, v185
	v_exp_f32_e32 v229, v84
	v_fma_f32 v84, v123, s89, -v215
	v_exp_f32_e32 v101, v70
	v_fma_f32 v70, v120, s89, -v215
	v_cvt_pk_bf16_f32 v118, v187, v97
	v_cvt_pk_bf16_f32 v119, v65, v81
	v_cvt_pk_bf16_f32 v120, v67, v83
	v_cvt_pk_bf16_f32 v121, v69, v85
	v_cvt_pk_bf16_f32 v216, v188, v112
	v_cvt_pk_bf16_f32 v217, v190, v98
	v_cvt_pk_bf16_f32 v218, v114, v192
	v_cvt_pk_bf16_f32 v219, v194, v86
	ds_read_b64_tr_b16 v[220:221], v234
	ds_read_b64_tr_b16 v[222:223], v234 offset:1536
	v_exp_f32_e32 v98, v84
	v_fma_f32 v84, v108, s89, -v168
	ds_read_b64_tr_b16 v[226:227], v234 offset:1600
	ds_read_b64_tr_b16 v[224:225], v234 offset:64
	v_exp_f32_e32 v231, v84
	v_fma_f32 v84, v124, s89, -v215
	v_exp_f32_e32 v188, v84
	v_fma_f32 v84, v109, s89, -v168
	v_exp_f32_e32 v233, v84
	v_fma_f32 v84, v125, s89, -v215
	v_exp_f32_e32 v190, v84
	v_fma_f32 v84, v110, s89, -v168
	s_waitcnt lgkmcnt(2)
	v_mfma_f32_32x32x16_bf16 v[48:63], v[220:223], v[118:121], v[48:63]
	v_exp_f32_e32 v70, v70
	v_cvt_pk_bf16_f32 v108, v101, v103
	v_cvt_pk_bf16_f32 v109, v117, v229
	v_cvt_pk_bf16_f32 v110, v231, v233
	v_fma_f32 v72, v72, s89, -v215
	v_exp_f32_e32 v100, v72
	v_fma_f32 v72, v89, s89, -v168
	v_mfma_f32_32x32x16_bf16 v[0:15], v[220:223], v[216:219], v[0:15]
	v_exp_f32_e32 v221, v84
	v_fma_f32 v84, v126, s89, -v215
	v_exp_f32_e32 v126, v84
	v_fma_f32 v84, v111, s89, -v168
	v_exp_f32_e32 v223, v84
	v_fma_f32 v84, v127, s89, -v215
	v_exp_f32_e32 v192, v84
	s_waitcnt lgkmcnt(0)
	v_mfma_f32_32x32x16_bf16 v[32:47], v[224:227], v[118:121], v[32:47]
	v_cvt_pk_bf16_f32 v111, v221, v223
	v_cvt_pk_bf16_f32 v118, v70, v104
	v_cvt_pk_bf16_f32 v119, v106, v98
	v_cvt_pk_bf16_f32 v120, v188, v190
	v_cvt_pk_bf16_f32 v121, v126, v192
	ds_read_b64_tr_b16 v[122:123], v234 offset:3072
	ds_read_b64_tr_b16 v[124:125], v234 offset:4608
	v_exp_f32_e32 v105, v72
	v_mfma_f32_32x32x16_bf16 v[16:31], v[224:227], v[216:219], v[16:31]
	ds_read_b64_tr_b16 v[218:219], v234 offset:4672
	ds_read_b64_tr_b16 v[216:217], v234 offset:3136
	v_fma_f32 v72, v73, s89, -v215
	v_exp_f32_e32 v102, v72
	v_fma_f32 v72, v90, s89, -v168
	v_exp_f32_e32 v107, v72
	v_fma_f32 v72, v74, s89, -v215
	v_fma_f32 v84, v87, s89, -v168
	v_fma_f32 v71, v71, s89, -v215
	v_exp_f32_e32 v116, v72
	v_fma_f32 v72, v91, s89, -v168
	s_waitcnt lgkmcnt(0)
	v_mfma_f32_32x32x16_bf16 v[32:47], v[216:219], v[108:111], v[32:47]
	v_exp_f32_e32 v87, v84
	v_exp_f32_e32 v84, v71
	v_fma_f32 v71, v88, s89, -v168
	v_cvt_pk_bf16_f32 v88, v189, v113
	v_cvt_pk_bf16_f32 v89, v191, v99
	v_exp_f32_e32 v99, v72
	v_fma_f32 v72, v75, s89, -v215
	v_mfma_f32_32x32x16_bf16 v[16:31], v[216:219], v[118:121], v[16:31]
	v_exp_f32_e32 v228, v72
	v_fma_f32 v72, v92, s89, -v168
	v_exp_f32_e32 v64, v64
	v_exp_f32_e32 v66, v66
	v_exp_f32_e32 v68, v68
	v_cvt_pk_bf16_f32 v90, v115, v193
	v_cvt_pk_bf16_f32 v91, v195, v87
	v_mfma_f32_32x32x16_bf16 v[48:63], v[122:125], v[108:111], v[48:63]
	v_cvt_pk_bf16_f32 v108, v186, v96
	v_cvt_pk_bf16_f32 v109, v64, v80
	v_cvt_pk_bf16_f32 v110, v66, v82
	v_cvt_pk_bf16_f32 v111, v68, v84
	ds_read_b64_tr_b16 v[112:113], v234 offset:6144
	ds_read_b64_tr_b16 v[114:115], v234 offset:7680
	v_exp_f32_e32 v189, v72
	ds_read_b64_tr_b16 v[74:75], v234 offset:7744
	ds_read_b64_tr_b16 v[72:73], v234 offset:6208
	v_mfma_f32_32x32x16_bf16 v[0:15], v[122:125], v[118:121], v[0:15]
	v_fma_f32 v76, v76, s89, -v215
	v_exp_f32_e32 v230, v76
	v_fma_f32 v76, v93, s89, -v168
	v_add_f32_e32 v224, 0, v186
	v_add_f32_e32 v225, 0, v187
	v_exp_f32_e32 v191, v76
	v_fma_f32 v76, v77, s89, -v215
	v_exp_f32_e32 v232, v76
	v_fma_f32 v76, v94, s89, -v168
	s_waitcnt lgkmcnt(0)
	v_mfma_f32_32x32x16_bf16 v[32:47], v[72:75], v[88:91], v[32:47]
	v_exp_f32_e32 v127, v76
	v_fma_f32 v76, v78, s89, -v215
	v_exp_f32_e32 v220, v76
	v_fma_f32 v76, v95, s89, -v168
	v_exp_f32_e32 v71, v71
	v_exp_f32_e32 v193, v76
	v_fma_f32 v76, v79, s89, -v215
	v_mfma_f32_32x32x16_bf16 v[16:31], v[72:75], v[108:111], v[16:31]
	v_add_f32_e64 v72, v96, v224
	v_add_f32_e64 v73, v97, v225
	v_exp_f32_e32 v222, v76
	v_add_f32_e32 v64, v64, v72
	v_add_f32_e32 v65, v65, v73
	v_cvt_pk_bf16_f32 v76, v71, v105
	v_cvt_pk_bf16_f32 v77, v107, v99
	v_cvt_pk_bf16_f32 v78, v189, v191
	v_cvt_pk_bf16_f32 v79, v127, v193
	v_mfma_f32_32x32x16_bf16 v[48:63], v[112:115], v[88:91], v[48:63]
	v_add_f32_e64 v64, v80, v64
	v_add_f32_e64 v65, v81, v65
	v_cvt_pk_bf16_f32 v88, v100, v102
	v_cvt_pk_bf16_f32 v89, v116, v228
	v_cvt_pk_bf16_f32 v90, v230, v232
	v_cvt_pk_bf16_f32 v91, v220, v222
	ds_read_b64_tr_b16 v[92:93], v234 offset:9216
	ds_read_b64_tr_b16 v[94:95], v234 offset:10752
	v_add_f32_e64 v64, v66, v64
	v_add_f32_e64 v65, v67, v65
	v_mfma_f32_32x32x16_bf16 v[0:15], v[112:115], v[108:111], v[0:15]
	v_add_f32_e64 v72, v82, v64
	v_add_f32_e64 v73, v83, v65
	ds_read_b64_tr_b16 v[66:67], v234 offset:10816
	ds_read_b64_tr_b16 v[64:65], v234 offset:9280
	v_add_f32_e64 v196, v194, v196
	v_add_f32_e64 v197, v195, v197
	v_add_f32_e32 v68, v68, v72
	v_add_f32_e32 v69, v69, v73
	v_add_f32_e32 v72, v86, v196
	v_add_f32_e32 v73, v87, v197
	v_add_f32_e32 v68, v84, v68
	v_add_f32_e32 v69, v85, v69
	v_add_f32_e32 v70, v70, v72
	v_add_f32_e32 v71, v71, v73
	v_add_f32_e32 v68, v100, v68
	v_add_f32_e32 v69, v101, v69
	v_add_f32_e32 v70, v104, v70
	v_add_f32_e32 v71, v105, v71
	v_add_f32_e32 v68, v102, v68
	v_add_f32_e32 v69, v103, v69
	s_waitcnt lgkmcnt(2)
	v_mfma_f32_32x32x16_bf16 v[48:63], v[92:95], v[76:79], v[48:63]
	v_add_f32_e64 v70, v106, v70
	v_add_f32_e64 v71, v107, v71
	v_add_f32_e64 v68, v116, v68
	v_add_f32_e64 v69, v117, v69
	v_add_f32_e64 v70, v98, v70
	v_add_f32_e64 v71, v99, v71
	v_add_f32_e32 v68, v228, v68
	v_add_f32_e32 v69, v229, v69
	v_add_f32_e32 v70, v188, v70
	v_add_f32_e32 v71, v189, v71
	v_add_f32_e32 v68, v230, v68
	v_add_f32_e32 v69, v231, v69
	v_add_f32_e32 v70, v190, v70
	v_add_f32_e32 v71, v191, v71
	v_mfma_f32_32x32x16_bf16 v[0:15], v[92:95], v[88:91], v[0:15]
	v_add_f32_e64 v68, v232, v68
	v_add_f32_e64 v69, v233, v69
	v_add_f32_e64 v70, v126, v70
	v_add_f32_e64 v71, v127, v71
	v_add_f32_e64 v68, v220, v68
	v_add_f32_e64 v69, v221, v69
	v_add_f32_e32 v70, v192, v70
	v_add_f32_e32 v71, v193, v71
	v_add_f32_e32 v68, v222, v68
	v_add_f32_e32 v69, v223, v69
	s_nop 0
	v_add_f32_e32 v68, v70, v68
	v_add_f32_e32 v69, v71, v69
	s_waitcnt lgkmcnt(0)
	v_mfma_f32_32x32x16_bf16 v[32:47], v[64:67], v[76:79], v[32:47]
	v_add_f32_e64 v178, v178, v68
	v_add_f32_e64 v179, v179, v69
	v_mfma_f32_32x32x16_bf16 v[16:31], v[64:67], v[88:91], v[16:31]

.LBB0_1344:
	v_fma_f32 v64, v64, s18, -v197
	v_exp_f32_e32 v131, v64
	v_fma_f32 v64, v113, s18, -v170
	v_fma_f32 v96, v96, s18, -v197
	v_exp_f32_e32 v113, v64
	v_fma_f32 v64, v97, s18, -v197
	v_fma_f32 v112, v112, s18, -v170
	v_exp_f32_e32 v130, v96
	v_exp_f32_e32 v96, v64
	v_fma_f32 v64, v81, s18, -v170
	v_fma_f32 v66, v66, s18, -v197
	v_exp_f32_e32 v129, v112
	v_exp_f32_e32 v112, v64
	v_fma_f32 v64, v65, s18, -v197
	v_exp_f32_e32 v133, v66
	v_fma_f32 v66, v115, s18, -v170
	v_exp_f32_e32 v97, v64
	v_fma_f32 v64, v114, s18, -v170
	v_exp_f32_e32 v81, v66
	v_fma_f32 v66, v99, s18, -v197
	v_fma_f32 v80, v80, s18, -v170
	v_exp_f32_e32 v65, v64
	v_fma_f32 v64, v98, s18, -v197
	v_exp_f32_e32 v98, v66
	v_fma_f32 v66, v83, s18, -v170
	v_fma_f32 v68, v68, s18, -v197
	v_exp_f32_e32 v128, v80
	v_exp_f32_e32 v80, v66
	v_fma_f32 v66, v67, s18, -v197
	v_exp_f32_e32 v115, v68
	v_fma_f32 v68, v117, s18, -v170
	v_exp_f32_e32 v99, v66
	v_fma_f32 v66, v116, s18, -v170
	v_exp_f32_e32 v83, v68
	v_fma_f32 v68, v101, s18, -v197
	v_exp_f32_e32 v67, v66
	v_fma_f32 v66, v100, s18, -v197
	v_exp_f32_e32 v100, v68
	v_fma_f32 v68, v85, s18, -v170
	v_exp_f32_e32 v132, v64
	v_fma_f32 v64, v82, s18, -v170
	v_exp_f32_e32 v82, v68
	v_fma_f32 v68, v69, s18, -v197
	v_exp_f32_e32 v114, v66
	v_fma_f32 v66, v84, s18, -v170
	v_exp_f32_e32 v101, v68
	v_fma_f32 v68, v118, s18, -v170
	v_fma_f32 v84, v119, s18, -v170
	v_exp_f32_e32 v69, v68
	v_fma_f32 v68, v102, s18, -v197
	v_exp_f32_e32 v85, v84
	v_fma_f32 v84, v103, s18, -v197
	v_exp_f32_e32 v116, v68
	v_fma_f32 v68, v86, s18, -v170
	v_exp_f32_e32 v86, v84
	v_fma_f32 v84, v120, s18, -v170
	v_exp_f32_e32 v103, v84
	v_fma_f32 v84, v104, s18, -v197
	v_exp_f32_e32 v120, v84
	v_fma_f32 v84, v121, s18, -v170
	v_exp_f32_e32 v119, v84
	v_fma_f32 v84, v105, s18, -v197
	v_exp_f32_e32 v134, v84
	v_fma_f32 v84, v122, s18, -v170
	v_exp_f32_e32 v105, v84
	v_fma_f32 v84, v106, s18, -v197
	v_exp_f32_e32 v106, v84
	v_fma_f32 v84, v123, s18, -v170
	v_exp_f32_e32 v153, v84
	v_fma_f32 v84, v107, s18, -v197
	v_cvt_pk_bf16_f32 v136, v129, v113
	v_cvt_pk_bf16_f32 v137, v65, v81
	v_cvt_pk_bf16_f32 v138, v67, v83
	v_cvt_pk_bf16_f32 v139, v69, v85
	v_cvt_pk_bf16_f32 v140, v130, v96
	v_cvt_pk_bf16_f32 v141, v132, v98
	v_cvt_pk_bf16_f32 v142, v114, v100
	v_cvt_pk_bf16_f32 v143, v116, v86
	ds_read_b64_tr_b16 v[144:145], v179 offset:30720
	ds_read_b64_tr_b16 v[146:147], v179 offset:32256
	v_exp_f32_e32 v154, v84
	v_fma_f32 v84, v124, s18, -v170
	v_exp_f32_e32 v157, v84
	v_fma_f32 v84, v108, s18, -v197
	v_exp_f32_e32 v158, v84
	v_fma_f32 v84, v125, s18, -v170
	v_exp_f32_e32 v161, v84
	v_fma_f32 v84, v109, s18, -v197
	v_exp_f32_e32 v162, v84
	v_fma_f32 v84, v126, s18, -v170
	s_waitcnt lgkmcnt(0)
	v_mfma_f32_32x32x16_bf16 v[48:63], v[144:147], v[136:139], v[48:63]
	v_fma_f32 v70, v70, s18, -v197
	v_exp_f32_e32 v117, v70
	v_fma_f32 v70, v87, s18, -v170
	ds_read_b64_tr_b16 v[150:151], v179 offset:32320
	ds_read_b64_tr_b16 v[148:149], v179 offset:30784
	v_exp_f32_e32 v64, v64
	v_exp_f32_e32 v66, v66
	v_exp_f32_e32 v68, v68
	v_mfma_f32_32x32x16_bf16 v[0:15], v[144:147], v[140:143], v[0:15]
	v_exp_f32_e32 v145, v84
	v_fma_f32 v84, v110, s18, -v197
	v_exp_f32_e32 v126, v84
	v_fma_f32 v84, v127, s18, -v170
	v_exp_f32_e32 v147, v84
	v_fma_f32 v84, v111, s18, -v197
	v_exp_f32_e32 v164, v84
	v_exp_f32_e32 v84, v70
	v_fma_f32 v70, v71, s18, -v197
	v_exp_f32_e32 v87, v70
	v_fma_f32 v70, v88, s18, -v170
	v_exp_f32_e32 v102, v70
	v_fma_f32 v70, v72, s18, -v197
	v_exp_f32_e32 v121, v70
	v_fma_f32 v70, v89, s18, -v170
	v_exp_f32_e32 v118, v70
	v_fma_f32 v70, v73, s18, -v197
	v_exp_f32_e32 v135, v70
	v_fma_f32 v70, v90, s18, -v170
	v_exp_f32_e32 v104, v70
	v_fma_f32 v70, v74, s18, -v197
	v_fma_f32 v74, v91, s18, -v170
	v_exp_f32_e32 v152, v74
	v_fma_f32 v74, v75, s18, -v197
	v_exp_f32_e32 v155, v74
	v_fma_f32 v74, v92, s18, -v170
	v_exp_f32_e32 v156, v74
	v_fma_f32 v74, v76, s18, -v197
	v_exp_f32_e32 v159, v74
	v_fma_f32 v74, v93, s18, -v170
	v_exp_f32_e32 v160, v74
	v_fma_f32 v74, v77, s18, -v197
	v_exp_f32_e32 v163, v74
	v_fma_f32 v74, v94, s18, -v170
	v_exp_f32_e32 v144, v74
	v_fma_f32 v74, v78, s18, -v197
	v_exp_f32_e32 v127, v74
	v_fma_f32 v74, v95, s18, -v170
	v_exp_f32_e32 v146, v74
	v_fma_f32 v74, v79, s18, -v197
	v_add_f32_e32 v78, 0, v130
	v_add_f32_e32 v79, 0, v131
	s_waitcnt lgkmcnt(0)
	v_mfma_f32_32x32x16_bf16 v[32:47], v[148:151], v[136:139], v[32:47]
	v_add_f32_e64 v78, v96, v78
	v_add_f32_e64 v79, v97, v79
	v_cvt_pk_bf16_f32 v108, v103, v119
	v_cvt_pk_bf16_f32 v109, v105, v153
	v_cvt_pk_bf16_f32 v110, v157, v161
	v_cvt_pk_bf16_f32 v111, v145, v147
	v_cvt_pk_bf16_f32 v122, v120, v134
	v_add_f32_e64 v78, v132, v78
	v_add_f32_e64 v79, v133, v79
	v_cvt_pk_bf16_f32 v123, v106, v154
	v_cvt_pk_bf16_f32 v124, v158, v162
	v_cvt_pk_bf16_f32 v125, v126, v164
	ds_read_b64_tr_b16 v[136:137], v179 offset:33792
	ds_read_b64_tr_b16 v[138:139], v179 offset:35328
	v_add_f32_e32 v78, v98, v78
	v_add_f32_e32 v79, v99, v79
	v_mfma_f32_32x32x16_bf16 v[16:31], v[148:151], v[140:143], v[16:31]
	v_add_f32_e64 v78, v114, v78
	v_add_f32_e64 v79, v115, v79
	ds_read_b64_tr_b16 v[142:143], v179 offset:35392
	ds_read_b64_tr_b16 v[140:141], v179 offset:33856
	v_add_f32_e64 v78, v100, v78
	v_add_f32_e64 v79, v101, v79
	v_exp_f32_e32 v107, v70
	v_add_f32_e32 v78, v116, v78
	v_add_f32_e32 v79, v117, v79
	v_cvt_pk_bf16_f32 v70, v128, v112
	v_cvt_pk_bf16_f32 v71, v64, v80
	v_cvt_pk_bf16_f32 v72, v66, v82
	v_cvt_pk_bf16_f32 v73, v68, v84
	v_cvt_pk_bf16_f32 v88, v131, v97
	v_cvt_pk_bf16_f32 v89, v133, v99
	v_cvt_pk_bf16_f32 v90, v115, v101
	v_cvt_pk_bf16_f32 v91, v117, v87
	s_nop 0
	v_add_f32_e32 v78, v86, v78
	v_add_f32_e32 v79, v87, v79
	v_add_f32_e32 v86, 0, v128
	v_add_f32_e32 v87, 0, v129
	s_waitcnt lgkmcnt(0)
	v_mfma_f32_32x32x16_bf16 v[32:47], v[140:143], v[108:111], v[32:47]
	v_add_f32_e64 v86, v112, v86
	v_add_f32_e64 v87, v113, v87
	v_add_f32_e64 v78, v120, v78
	v_add_f32_e64 v79, v121, v79
	v_add_f32_e64 v64, v64, v86
	v_add_f32_e64 v65, v65, v87
	v_add_f32_e32 v78, v134, v78
	v_add_f32_e32 v79, v135, v79
	v_add_f32_e32 v64, v80, v64
	v_add_f32_e32 v65, v81, v65
	v_add_f32_e32 v78, v106, v78
	v_add_f32_e32 v79, v107, v79
	v_add_f32_e32 v64, v66, v64
	v_add_f32_e32 v65, v67, v65
	v_mfma_f32_32x32x16_bf16 v[48:63], v[136:139], v[108:111], v[48:63]
	v_add_f32_e64 v64, v82, v64
	v_add_f32_e64 v65, v83, v65
	ds_read_b64_tr_b16 v[108:109], v179 offset:36864
	ds_read_b64_tr_b16 v[110:111], v179 offset:38400
	v_add_f32_e64 v64, v68, v64
	v_add_f32_e64 v65, v69, v65
	v_exp_f32_e32 v165, v74
	v_add_f32_e32 v64, v84, v64
	v_add_f32_e32 v65, v85, v65
	v_add_f32_e32 v78, v154, v78
	v_add_f32_e32 v79, v155, v79
	v_add_f32_e32 v64, v102, v64
	v_add_f32_e32 v65, v103, v65
	v_mfma_f32_32x32x16_bf16 v[0:15], v[136:139], v[122:125], v[0:15]
	v_add_f32_e64 v64, v118, v64
	v_add_f32_e64 v65, v119, v65
	v_add_f32_e64 v78, v158, v78
	v_add_f32_e64 v79, v159, v79
	v_add_f32_e64 v64, v104, v64
	v_add_f32_e64 v65, v105, v65
	v_add_f32_e32 v78, v162, v78
	v_add_f32_e32 v79, v163, v79
	v_add_f32_e32 v64, v152, v64
	v_add_f32_e32 v65, v153, v65
	v_add_f32_e32 v78, v126, v78
	v_add_f32_e32 v79, v127, v79
	v_add_f32_e32 v64, v156, v64
	v_add_f32_e32 v65, v157, v65
	v_mfma_f32_32x32x16_bf16 v[16:31], v[140:143], v[122:125], v[16:31]
	v_add_f32_e64 v64, v160, v64
	v_add_f32_e64 v65, v161, v65
	ds_read_b64_tr_b16 v[124:125], v179 offset:38464
	ds_read_b64_tr_b16 v[122:123], v179 offset:36928
	v_add_f32_e64 v64, v144, v64
	v_add_f32_e64 v65, v145, v65
	s_lshl_b32 s6, s20, 1
	v_add_f32_e32 v64, v146, v64
	v_add_f32_e32 v65, v147, v65
	v_lshlrev_b32_e32 v170, 3, v195
	v_add_f32_e32 v64, v64, v65
	v_add_f32_e32 v66, v175, v64
	ds_bpermute_b32 v67, v196, v66
	s_waitcnt lgkmcnt(1)
	v_mfma_f32_32x32x16_bf16 v[32:47], v[122:125], v[70:73], v[32:47]
	v_add_f32_e64 v64, v164, v78
	v_add_f32_e64 v65, v165, v79
	s_add_i32 s17, s17, s30
	v_add_f32_e32 v64, v64, v65
	s_waitcnt lgkmcnt(0)
	v_add_f32_e32 v65, v66, v67
	v_max_f32_e32 v65, 0xda24260, v65
	v_div_scale_f32 v66, s[0:1], v65, v65, 1.0
	v_mfma_f32_32x32x16_bf16 v[48:63], v[108:111], v[70:73], v[48:63]
	v_cvt_pk_bf16_f32 v70, v102, v118
	v_cvt_pk_bf16_f32 v71, v104, v152
	v_cvt_pk_bf16_f32 v72, v156, v160
	v_cvt_pk_bf16_f32 v73, v144, v146
	v_cvt_pk_bf16_f32 v74, v121, v135
	v_cvt_pk_bf16_f32 v75, v107, v155
	v_cvt_pk_bf16_f32 v76, v159, v163
	v_mfma_f32_32x32x16_bf16 v[0:15], v[108:111], v[88:91], v[0:15]
	v_cvt_pk_bf16_f32 v77, v127, v165
	ds_read_b64_tr_b16 v[92:93], v179 offset:39936
	ds_read_b64_tr_b16 v[94:95], v179 offset:41472
	v_rcp_f32_e32 v67, v66
	v_add_f32_e32 v64, v174, v64
	s_cmpk_lt_i32 s17, 0x200
	v_fma_f32 v68, -v66, v67, 1.0
	v_mfma_f32_32x32x16_bf16 v[16:31], v[122:125], v[88:91], v[16:31]
	ds_read_b64_tr_b16 v[90:91], v179 offset:41536
	ds_read_b64_tr_b16 v[88:89], v179 offset:40000
	v_fmac_f32_e32 v67, v68, v67
	v_div_scale_f32 v68, vcc, 1.0, v65, 1.0
	v_mul_f32_e32 v69, v68, v67
	s_waitcnt lgkmcnt(0)
	s_barrier
	v_mfma_f32_32x32x16_bf16 v[32:47], v[88:91], v[70:73], v[32:47]
	v_mfma_f32_32x32x16_bf16 v[48:63], v[92:95], v[70:73], v[48:63]
	v_fma_f32 v70, -v66, v69, v68
	v_fmac_f32_e32 v69, v70, v67
	v_fma_f32 v66, -v66, v69, v68
	v_div_fmas_f32 v66, v66, v67, v69
	v_div_fixup_f32 v65, v66, v65, 1.0
	s_nop 5
	v_mul_f32_e32 v66, v32, v65
	v_mul_f32_e32 v67, v33, v65
	v_lshlrev_b64 v[32:33], 11, v[172:173]
	v_mul_f32_e32 v68, v34, v65
	v_mul_f32_e32 v69, v35, v65
	v_lshl_add_u64 v[34:35], s[4:5], 0, v[32:33]
	v_lshl_add_u64 v[34:35], v[34:35], 0, s[6:7]
	v_mul_f32_e32 v48, v48, v65
	v_mul_f32_e32 v49, v49, v65
	v_mul_f32_e32 v50, v50, v65
	v_mul_f32_e32 v51, v51, v65
	v_mul_f32_e32 v70, v36, v65
	v_mul_f32_e32 v71, v37, v65
	v_mul_f32_e32 v72, v38, v65
	v_lshl_add_u64 v[34:35], v[34:35], 0, v[170:171]
	v_cvt_pk_bf16_f32 v232, v48, v49
	v_cvt_pk_bf16_f32 v233, v50, v51
	v_cvt_pk_bf16_f32 v240, v66, v67
	v_mul_f32_e32 v52, v52, v65
	v_mul_f32_e32 v53, v53, v65
	v_mul_f32_e32 v54, v54, v65
	v_mul_f32_e32 v55, v55, v65
	v_mul_f32_e32 v73, v39, v65
	v_mul_f32_e32 v40, v40, v65
	v_cvt_pk_bf16_f32 v241, v68, v69
	s_nop 0
	s_nop 0
	v_cvt_pk_bf16_f32 v234, v52, v53
	v_cvt_pk_bf16_f32 v235, v54, v55
	v_cvt_pk_bf16_f32 v242, v70, v71
	v_mul_f32_e32 v56, v56, v65
	v_mul_f32_e32 v57, v57, v65
	v_mul_f32_e32 v41, v41, v65
	v_mul_f32_e32 v58, v58, v65
	v_mul_f32_e32 v59, v59, v65
	v_cvt_pk_bf16_f32 v243, v72, v73
	v_and_b32_e32 v248, 32, v200
	v_lshrrev_b32_e32 v248, 2, v248
	v_mov_b32_e32 v249, 0
	v_lshl_add_u64 v[248:249], v[34:35], 0, v[248:249]
	v_permlane32_swap_b32_e32 v232, v234
	v_permlane32_swap_b32_e32 v233, v235
	global_store_dwordx4 v[248:249], v[232:235], off offset:1536
	s_nop 1
	v_permlane32_swap_b32_e32 v240, v242
	v_permlane32_swap_b32_e32 v241, v243
	global_store_dwordx4 v[248:249], v[240:243], off offset:1600
	v_cvt_pk_bf16_f32 v236, v56, v57
	v_cvt_pk_bf16_f32 v237, v58, v59
	v_cvt_pk_bf16_f32 v244, v40, v41
	ds_bpermute_b32 v40, v196, v64
	v_mul_f32_e32 v42, v42, v65
	v_mul_f32_e32 v43, v43, v65
	v_cvt_pk_bf16_f32 v245, v42, v43
	s_nop 0
	s_waitcnt lgkmcnt(0)
	v_add_f32_e32 v39, v64, v40
	v_max_f32_e32 v40, 0xda24260, v39
	v_div_scale_f32 v41, s[0:1], v40, v40, 1.0
	v_rcp_f32_e32 v42, v41
	v_mul_f32_e32 v60, v60, v65
	v_mul_f32_e32 v61, v61, v65
	v_mul_f32_e32 v62, v62, v65
	v_mul_f32_e32 v63, v63, v65
	s_nop 0
	v_cvt_pk_bf16_f32 v238, v60, v61
	v_cvt_pk_bf16_f32 v239, v62, v63
	v_mfma_f32_32x32x16_bf16 v[0:15], v[92:95], v[74:77], v[0:15]
	v_mul_f32_e32 v44, v44, v65
	v_mul_f32_e32 v45, v45, v65
	v_mul_f32_e32 v46, v46, v65
	v_mul_f32_e32 v47, v47, v65
	v_cvt_pk_bf16_f32 v246, v44, v45
	v_cvt_pk_bf16_f32 v247, v46, v47
	v_permlane32_swap_b32_e32 v236, v238
	v_permlane32_swap_b32_e32 v237, v239
	global_store_dwordx4 v[248:249], v[236:239], off offset:1568
	s_nop 1
	v_permlane32_swap_b32_e32 v244, v246
	v_permlane32_swap_b32_e32 v245, v247
	global_store_dwordx4 v[248:249], v[244:247], off offset:1632
	v_fma_f32 v34, -v41, v42, 1.0
	v_fmac_f32_e32 v42, v34, v42
	v_div_scale_f32 v34, vcc, 1.0, v40, 1.0
	v_mfma_f32_32x32x16_bf16 v[16:31], v[88:91], v[74:77], v[16:31]
	v_mul_f32_e32 v35, v34, v42
	v_fma_f32 v36, -v41, v35, v34
	v_fmac_f32_e32 v35, v36, v42
	v_fma_f32 v34, -v41, v35, v34
	v_div_fmas_f32 v34, v34, v42, v35
	v_div_fixup_f32 v34, v34, v40, 1.0
	v_or_b32_e32 v32, 0x10000, v32
	v_mul_f32_e32 v35, v0, v34
	v_mul_f32_e32 v36, v1, v34
	v_lshl_add_u64 v[0:1], s[4:5], 0, v[32:33]
	v_mul_f32_e32 v3, v3, v34
	v_lshl_add_u64 v[0:1], v[0:1], 0, s[6:7]
	v_mul_f32_e32 v16, v16, v34
	v_mul_f32_e32 v17, v17, v34
	v_mul_f32_e32 v37, v2, v34
	v_mul_f32_e32 v18, v18, v34
	v_mul_f32_e32 v19, v19, v34
	v_mul_f32_e32 v38, v4, v34
	v_mul_f32_e32 v39, v5, v34
	v_lshl_add_u64 v[0:1], v[0:1], 0, v[170:171]
	v_cvt_pk_bf16_f32 v232, v35, v36
	v_cvt_pk_bf16_f32 v233, v37, v3
	v_cvt_pk_bf16_f32 v240, v16, v17
	v_cvt_pk_bf16_f32 v241, v18, v19
	v_mul_f32_e32 v20, v20, v34
	v_mul_f32_e32 v21, v21, v34
	v_mul_f32_e32 v6, v6, v34
	v_mul_f32_e32 v22, v22, v34
	v_mul_f32_e32 v7, v7, v34
	v_mul_f32_e32 v23, v23, v34
	s_nop 0
	s_nop 0
	v_cvt_pk_bf16_f32 v234, v38, v39
	v_cvt_pk_bf16_f32 v235, v6, v7
	v_cvt_pk_bf16_f32 v242, v20, v21
	v_cvt_pk_bf16_f32 v243, v22, v23
	v_mul_f32_e32 v8, v8, v34
	v_mul_f32_e32 v24, v24, v34
	v_mul_f32_e32 v9, v9, v34
	v_mul_f32_e32 v25, v25, v34
	v_mul_f32_e32 v10, v10, v34
	v_mul_f32_e32 v26, v26, v34
	v_mul_f32_e32 v11, v11, v34
	v_mul_f32_e32 v27, v27, v34
	v_and_b32_e32 v248, 32, v200
	v_lshrrev_b32_e32 v248, 2, v248
	v_mov_b32_e32 v249, 0
	v_lshl_add_u64 v[248:249], v[0:1], 0, v[248:249]
	v_permlane32_swap_b32_e32 v232, v234
	v_permlane32_swap_b32_e32 v233, v235
	global_store_dwordx4 v[248:249], v[232:235], off offset:1536
	v_permlane32_swap_b32_e32 v240, v242
	v_permlane32_swap_b32_e32 v241, v243
	global_store_dwordx4 v[248:249], v[240:243], off offset:1600
	v_cvt_pk_bf16_f32 v236, v8, v9
	v_cvt_pk_bf16_f32 v237, v10, v11
	v_cvt_pk_bf16_f32 v244, v24, v25
	v_cvt_pk_bf16_f32 v245, v26, v27
	v_mul_f32_e32 v12, v12, v34
	v_mul_f32_e32 v28, v28, v34
	v_mul_f32_e32 v13, v13, v34
	v_mul_f32_e32 v29, v29, v34
	v_mul_f32_e32 v14, v14, v34
	v_mul_f32_e32 v30, v30, v34
	v_mul_f32_e32 v15, v15, v34
	v_mul_f32_e32 v31, v31, v34
	s_nop 0
	s_nop 0
	v_cvt_pk_bf16_f32 v238, v12, v13
	v_cvt_pk_bf16_f32 v239, v14, v15
	v_cvt_pk_bf16_f32 v246, v28, v29
	v_cvt_pk_bf16_f32 v247, v30, v31
	v_permlane32_swap_b32_e32 v236, v238
	v_permlane32_swap_b32_e32 v237, v239
	global_store_dwordx4 v[248:249], v[236:239], off offset:1568
	s_nop 1
	v_permlane32_swap_b32_e32 v244, v246
	v_permlane32_swap_b32_e32 v245, v247
	global_store_dwordx4 v[248:249], v[244:247], off offset:1632
	s_cbranch_scc0 .LBB0_1351

.LBB0_1346:
	v_mul_f32_e32 v170, 0x3e38aa3b, v202
	v_cmp_ngt_f32_e32 vcc, s15, v202
	v_mul_f32_e32 v182, 0x3e38aa3b, v201
	s_and_b64 s[2:3], s[10:11], exec
	v_cndmask_b32_e32 v170, 0, v170, vcc
	v_cmp_ngt_f32_e32 vcc, s15, v201
	v_fma_f32 v112, v112, s18, -v170
	v_exp_f32_e32 v183, v112
	v_cndmask_b32_e32 v197, 0, v182, vcc
	v_fma_f32 v64, v64, s18, -v197
	v_exp_f32_e32 v182, v64
	v_fma_f32 v64, v113, s18, -v170
	v_fma_f32 v96, v96, s18, -v197
	v_exp_f32_e32 v113, v64
	v_fma_f32 v64, v97, s18, -v197
	v_exp_f32_e32 v184, v96
	v_exp_f32_e32 v96, v64
	v_fma_f32 v64, v81, s18, -v170
	v_exp_f32_e32 v97, v64
	v_fma_f32 v64, v65, s18, -v197
	v_exp_f32_e32 v112, v64
	v_fma_f32 v64, v114, s18, -v170
	v_exp_f32_e32 v65, v64
	v_fma_f32 v64, v98, s18, -v197
	v_exp_f32_e32 v186, v64
	v_fma_f32 v64, v82, s18, -v170
	v_exp_f32_e32 v187, v64
	v_fma_f32 v64, v66, s18, -v197
	v_fma_f32 v66, v115, s18, -v170
	v_exp_f32_e32 v81, v66
	v_fma_f32 v66, v99, s18, -v197
	v_exp_f32_e32 v98, v66
	v_fma_f32 v66, v83, s18, -v170
	v_fma_f32 v80, v80, s18, -v170
	v_exp_f32_e32 v99, v66
	v_fma_f32 v66, v67, s18, -v197
	v_exp_f32_e32 v185, v80
	v_exp_f32_e32 v80, v66
	v_fma_f32 v66, v116, s18, -v170
	v_exp_f32_e32 v83, v66
	v_fma_f32 v66, v100, s18, -v197
	v_exp_f32_e32 v114, v66
	v_fma_f32 v66, v84, s18, -v170
	v_exp_f32_e32 v115, v66
	v_fma_f32 v66, v68, s18, -v197
	v_exp_f32_e32 v82, v66
	v_fma_f32 v66, v117, s18, -v170
	v_exp_f32_e32 v67, v66
	v_fma_f32 v66, v101, s18, -v197
	v_exp_f32_e32 v116, v66
	v_fma_f32 v66, v85, s18, -v170
	v_fma_f32 v68, v118, s18, -v170
	v_exp_f32_e32 v117, v66
	v_fma_f32 v66, v69, s18, -v197
	v_exp_f32_e32 v69, v68
	v_fma_f32 v68, v102, s18, -v197
	v_exp_f32_e32 v188, v68
	v_fma_f32 v68, v86, s18, -v170
	v_exp_f32_e32 v189, v68
	v_fma_f32 v68, v70, s18, -v197
	v_fma_f32 v70, v119, s18, -v170
	v_exp_f32_e32 v85, v70
	v_fma_f32 v70, v103, s18, -v197
	v_exp_f32_e32 v118, v70
	v_fma_f32 v70, v87, s18, -v170
	v_exp_f32_e32 v119, v70
	v_fma_f32 v70, v71, s18, -v197
	v_exp_f32_e32 v84, v70
	v_add_f32_e32 v70, 0, v184
	v_add_f32_e32 v71, 0, v185
	s_cselect_b32 s2, s19, 0x7800
	v_add_f32_e32 v190, v96, v70
	v_add_f32_e32 v191, v97, v71
	v_fma_f32 v70, v120, s18, -v170
	v_exp_f32_e32 v71, v70
	v_fma_f32 v70, v104, s18, -v197
	v_exp_f32_e32 v86, v70
	v_fma_f32 v70, v121, s18, -v170
	v_exp_f32_e32 v101, v70
	v_fma_f32 v70, v105, s18, -v197
	v_exp_f32_e32 v102, v70
	v_fma_f32 v70, v122, s18, -v170
	v_exp_f32_e32 v105, v70
	v_fma_f32 v70, v106, s18, -v197
	v_exp_f32_e32 v106, v70
	v_add_u32_e32 v203, s2, v179
	v_fma_f32 v70, v123, s18, -v170
	v_cvt_pk_bf16_f32 v204, v183, v113
	v_cvt_pk_bf16_f32 v205, v65, v81
	v_cvt_pk_bf16_f32 v206, v83, v67
	v_cvt_pk_bf16_f32 v207, v69, v85
	v_cvt_pk_bf16_f32 v208, v184, v96
	v_cvt_pk_bf16_f32 v209, v186, v98
	v_cvt_pk_bf16_f32 v210, v114, v116
	v_cvt_pk_bf16_f32 v211, v188, v118
	ds_read_b64_tr_b16 v[212:213], v203
	ds_read_b64_tr_b16 v[214:215], v203 offset:1536
	v_exp_f32_e32 v217, v70
	v_fma_f32 v70, v107, s18, -v197
	ds_read_b64_tr_b16 v[122:123], v203 offset:1600
	ds_read_b64_tr_b16 v[120:121], v203 offset:64
	v_exp_f32_e32 v184, v70
	v_fma_f32 v70, v124, s18, -v170
	v_exp_f32_e32 v219, v70
	v_fma_f32 v70, v108, s18, -v197
	v_exp_f32_e32 v220, v70
	v_fma_f32 v70, v125, s18, -v170
	v_exp_f32_e32 v223, v70
	v_fma_f32 v70, v109, s18, -v197
	v_exp_f32_e32 v224, v70
	v_fma_f32 v70, v126, s18, -v170
	s_waitcnt lgkmcnt(0)
	v_mfma_f32_32x32x16_bf16 v[32:47], v[120:123], v[204:207], v[32:47]
	v_cvt_pk_bf16_f32 v108, v71, v101
	v_cvt_pk_bf16_f32 v109, v105, v217
	v_exp_f32_e32 v64, v64
	v_exp_f32_e32 v66, v66
	v_exp_f32_e32 v68, v68
	v_fma_f32 v76, v76, s18, -v197
	v_exp_f32_e32 v218, v76
	v_mfma_f32_32x32x16_bf16 v[16:31], v[120:123], v[208:211], v[16:31]
	v_add_f32_e64 v120, v186, v190
	v_add_f32_e64 v121, v187, v191
	v_fma_f32 v76, v93, s18, -v170
	v_add_f32_e64 v120, v98, v120
	v_add_f32_e64 v121, v99, v121
	v_exp_f32_e32 v225, v76
	v_add_f32_e32 v120, v114, v120
	v_add_f32_e32 v121, v115, v121
	v_fma_f32 v76, v77, s18, -v197
	v_add_f32_e32 v120, v116, v120
	v_add_f32_e32 v121, v117, v121
	v_mfma_f32_32x32x16_bf16 v[48:63], v[212:215], v[204:207], v[48:63]
	v_add_f32_e64 v190, v188, v120
	v_add_f32_e64 v191, v189, v121
	v_exp_f32_e32 v222, v76
	v_fma_f32 v76, v94, s18, -v170
	v_add_f32_e32 v190, v118, v190
	v_add_f32_e32 v191, v119, v191
	s_cselect_b32 s2, 0x7800, s19
	v_mfma_f32_32x32x16_bf16 v[0:15], v[212:215], v[208:211], v[0:15]
	v_exp_f32_e32 v213, v70
	v_fma_f32 v70, v110, s18, -v197
	v_exp_f32_e32 v214, v70
	v_fma_f32 v70, v127, s18, -v170
	v_exp_f32_e32 v227, v70
	v_fma_f32 v70, v111, s18, -v197
	v_exp_f32_e32 v228, v70
	v_cvt_pk_bf16_f32 v110, v219, v223
	v_cvt_pk_bf16_f32 v111, v213, v227
	v_cvt_pk_bf16_f32 v124, v86, v102
	v_cvt_pk_bf16_f32 v125, v106, v184
	v_cvt_pk_bf16_f32 v126, v220, v224
	v_cvt_pk_bf16_f32 v127, v214, v228
	ds_read_b64_tr_b16 v[204:205], v203 offset:3072
	ds_read_b64_tr_b16 v[206:207], v203 offset:4608
	ds_read_b64_tr_b16 v[122:123], v203 offset:4672
	ds_read_b64_tr_b16 v[120:121], v203 offset:3136
	v_fma_f32 v70, v88, s18, -v170
	v_exp_f32_e32 v87, v70
	v_fma_f32 v70, v72, s18, -v197
	v_fma_f32 v72, v89, s18, -v170
	v_exp_f32_e32 v103, v72
	v_fma_f32 v72, v73, s18, -v197
	v_exp_f32_e32 v100, v72
	v_fma_f32 v72, v90, s18, -v170
	v_exp_f32_e32 v107, v72
	v_fma_f32 v72, v74, s18, -v197
	v_exp_f32_e32 v104, v72
	v_fma_f32 v72, v91, s18, -v170
	s_waitcnt lgkmcnt(0)
	v_mfma_f32_32x32x16_bf16 v[32:47], v[120:123], v[108:111], v[32:47]
	v_cvt_pk_bf16_f32 v88, v185, v97
	v_exp_f32_e32 v185, v72
	v_fma_f32 v72, v75, s18, -v197
	v_exp_f32_e32 v216, v72
	v_fma_f32 v72, v92, s18, -v170
	v_cvt_pk_bf16_f32 v89, v187, v99
	v_cvt_pk_bf16_f32 v90, v115, v117
	v_mfma_f32_32x32x16_bf16 v[16:31], v[120:123], v[124:127], v[16:31]
	v_cvt_pk_bf16_f32 v91, v189, v119
	v_cvt_pk_bf16_f32 v96, v182, v112
	v_cvt_pk_bf16_f32 v97, v64, v80
	v_cvt_pk_bf16_f32 v98, v82, v66
	v_cvt_pk_bf16_f32 v99, v68, v84
	v_exp_f32_e32 v221, v72
	v_exp_f32_e32 v215, v76
	v_mfma_f32_32x32x16_bf16 v[48:63], v[204:207], v[108:111], v[48:63]
	ds_read_b64_tr_b16 v[108:109], v203 offset:6144
	ds_read_b64_tr_b16 v[110:111], v203 offset:7680
	ds_read_b64_tr_b16 v[74:75], v203 offset:7744
	ds_read_b64_tr_b16 v[72:73], v203 offset:6208
	v_fma_f32 v76, v78, s18, -v197
	v_exp_f32_e32 v70, v70
	v_exp_f32_e32 v212, v76
	v_fma_f32 v76, v95, s18, -v170
	v_exp_f32_e32 v229, v76
	v_mfma_f32_32x32x16_bf16 v[0:15], v[204:207], v[124:127], v[0:15]
	v_fma_f32 v76, v79, s18, -v197
	v_exp_f32_e32 v226, v76
	v_cvt_pk_bf16_f32 v76, v87, v103
	v_cvt_pk_bf16_f32 v77, v107, v185
	v_cvt_pk_bf16_f32 v78, v221, v225
	v_cvt_pk_bf16_f32 v79, v215, v229
	s_waitcnt lgkmcnt(0)
	v_mfma_f32_32x32x16_bf16 v[32:47], v[72:75], v[88:91], v[32:47]
	v_mfma_f32_32x32x16_bf16 v[16:31], v[72:75], v[96:99], v[16:31]
	v_add_f32_e64 v72, v182, 0
	v_add_f32_e64 v73, v183, 0
	v_add_f32_e64 v72, v112, v72
	v_add_f32_e64 v73, v113, v73
	v_add_f32_e64 v64, v64, v72
	v_add_f32_e64 v65, v65, v73
	v_add_f32_e32 v64, v80, v64
	v_add_f32_e32 v65, v81, v65
	v_mfma_f32_32x32x16_bf16 v[48:63], v[108:111], v[88:91], v[48:63]
	v_add_f32_e64 v64, v82, v64
	v_add_f32_e64 v65, v83, v65
	v_cvt_pk_bf16_f32 v88, v70, v100
	v_cvt_pk_bf16_f32 v89, v104, v216
	v_cvt_pk_bf16_f32 v90, v218, v222
	v_cvt_pk_bf16_f32 v91, v212, v226
	ds_read_b64_tr_b16 v[92:93], v203 offset:9216
	ds_read_b64_tr_b16 v[94:95], v203 offset:10752
	v_add_f32_e64 v64, v66, v64
	v_add_f32_e64 v65, v67, v65
	v_mfma_f32_32x32x16_bf16 v[0:15], v[108:111], v[96:99], v[0:15]
	ds_read_b64_tr_b16 v[74:75], v203 offset:10816
	ds_read_b64_tr_b16 v[72:73], v203 offset:9280
	v_add_f32_e64 v64, v68, v64
	v_add_f32_e64 v65, v69, v65
	v_add_f32_e64 v66, v86, v190
	v_add_f32_e64 v67, v87, v191
	v_add_f32_e32 v64, v84, v64
	v_add_f32_e32 v65, v85, v65
	v_add_f32_e32 v66, v102, v66
	v_add_f32_e32 v67, v103, v67
	v_add_f32_e32 v64, v70, v64
	v_add_f32_e32 v65, v71, v65
	v_add_f32_e32 v66, v106, v66
	v_add_f32_e32 v67, v107, v67
	v_add_f32_e32 v64, v100, v64
	v_add_f32_e32 v65, v101, v65
	s_waitcnt lgkmcnt(2)
	v_mfma_f32_32x32x16_bf16 v[48:63], v[92:95], v[76:79], v[48:63]
	v_add_f32_e64 v64, v104, v64
	v_add_f32_e64 v65, v105, v65
	v_add_f32_e64 v66, v184, v66
	v_add_f32_e64 v67, v185, v67
	v_add_f32_e64 v64, v216, v64
	v_add_f32_e64 v65, v217, v65
	v_add_f32_e32 v66, v220, v66
	v_add_f32_e32 v67, v221, v67
	v_add_f32_e32 v64, v218, v64
	v_add_f32_e32 v65, v219, v65
	v_add_f32_e32 v66, v224, v66
	v_add_f32_e32 v67, v225, v67
	v_add_f32_e32 v64, v222, v64
	v_add_f32_e32 v65, v223, v65
	v_mfma_f32_32x32x16_bf16 v[0:15], v[92:95], v[88:91], v[0:15]
	v_add_f32_e64 v66, v214, v66
	v_add_f32_e64 v67, v215, v67
	v_add_f32_e64 v64, v212, v64
	v_add_f32_e64 v65, v213, v65
	v_add_f32_e64 v66, v228, v66
	v_add_f32_e64 v67, v229, v67
	v_add_f32_e32 v64, v226, v64
	v_add_f32_e32 v65, v227, v65
	s_nop 0
	v_add_f32_e32 v64, v66, v64
	v_add_f32_e32 v65, v67, v65
	s_waitcnt lgkmcnt(0)
	v_mfma_f32_32x32x16_bf16 v[32:47], v[72:75], v[76:79], v[32:47]
	v_add_f32_e64 v174, v174, v64
	v_add_f32_e64 v175, v175, v65
	v_add_u32_e32 v64, s2, v178
	s_cselect_b32 s2, 0x2400, 0
	s_xor_b32 s1, s1, 1
	s_add_i32 s0, s0, 64
	v_add_u32_e32 v65, s2, v176
	s_cmpk_lg_i32 s0, 0x100
	v_mfma_f32_32x32x16_bf16 v[16:31], v[72:75], v[88:91], v[16:31]
	s_waitcnt vmcnt(1)
	ds_write_b128 v65, v[160:163]
	s_waitcnt vmcnt(0)
	ds_write_b128 v64, v[164:167]
	s_waitcnt lgkmcnt(0)
	s_barrier
	s_cbranch_scc0 .LBB0_1349
.LBB0_1347:
	s_cmp_eq_u32 s1, 0
	s_cselect_b64 s[10:11], -1, 0
	s_and_b64 s[2:3], s[10:11], exec
	s_cselect_b32 s2, 0, 0x2400
	v_add_u32_e32 v170, s2, v199
	ds_read_b128 v[64:67], v170
	ds_read_b128 v[160:163], v170 offset:32
	s_waitcnt lgkmcnt(1)
	v_mfma_f32_32x32x16_bf16 v[112:127], v[64:67], v[152:155], 0
	v_mfma_f32_32x32x16_bf16 v[96:111], v[64:67], v[156:159], 0
	ds_read_b128 v[64:67], v170 offset:4608
	ds_read_b128 v[164:167], v170 offset:4640
	ds_read_b128 v[182:185], v170 offset:64
	ds_read_b128 v[186:189], v170 offset:96
	ds_read_b128 v[204:207], v170 offset:4672
	ds_read_b128 v[208:211], v170 offset:4704
	s_waitcnt lgkmcnt(5)
	v_mfma_f32_32x32x16_bf16 v[80:95], v[64:67], v[152:155], 0
	v_mfma_f32_32x32x16_bf16 v[64:79], v[64:67], v[156:159], 0
	v_mfma_f32_32x32x16_bf16 v[112:127], v[160:163], v[144:147], v[112:127]
	v_mfma_f32_32x32x16_bf16 v[96:111], v[160:163], v[148:151], v[96:111]
	v_add_u32_e32 v160, s0, v198
	v_med3_i32 v160, v160, 0, v177
	v_lshlrev_b32_e32 v170, 11, v160
	s_waitcnt lgkmcnt(4)
	v_mfma_f32_32x32x16_bf16 v[80:95], v[164:167], v[144:147], v[80:95]
	v_mfma_f32_32x32x16_bf16 v[64:79], v[164:167], v[148:151], v[64:79]
	v_lshl_add_u64 v[164:165], v[180:181], 0, v[170:171]
	global_load_dwordx4 v[160:163], v[164:165], off
	s_nop 0
	global_load_dwordx4 v[164:167], v[164:165], off offset:512
	s_waitcnt lgkmcnt(3)
	v_mfma_f32_32x32x16_bf16 v[112:127], v[182:185], v[140:143], v[112:127]
	s_waitcnt lgkmcnt(1)
	v_mfma_f32_32x32x16_bf16 v[80:95], v[204:207], v[140:143], v[80:95]
	v_mfma_f32_32x32x16_bf16 v[96:111], v[182:185], v[132:135], v[96:111]
	v_mfma_f32_32x32x16_bf16 v[64:79], v[204:207], v[132:135], v[64:79]
	v_mfma_f32_32x32x16_bf16 v[112:127], v[186:189], v[136:139], v[112:127]
	s_waitcnt lgkmcnt(0)
	v_mfma_f32_32x32x16_bf16 v[80:95], v[208:211], v[136:139], v[80:95]
	s_nop 9
	v_max_f32_e32 v183, v113, v113
	v_max_f32_e32 v184, v115, v115
	v_max_f32_e32 v190, v112, v112
	v_mfma_f32_32x32x16_bf16 v[64:79], v[208:211], v[128:131], v[64:79]
	v_max_f32_e32 v182, v81, v81
	v_max_f32_e32 v182, v183, v182
	v_max_f32_e32 v183, v83, v83
	v_max_f32_e32 v170, v80, v80
	v_max_f32_e32 v183, v184, v183
	v_max_f32_e32 v170, v190, v170
	v_max3_f32 v184, v114, v82, v118
	v_mfma_f32_32x32x16_bf16 v[96:111], v[186:189], v[128:131], v[96:111]
	v_max3_f32 v183, v183, v119, v87
	v_max3_f32 v170, v170, v116, v84
	v_max3_f32 v182, v182, v117, v85
	v_max3_f32 v184, v184, v86, v122
	v_max3_f32 v183, v183, v123, v91
	v_max3_f32 v170, v170, v120, v88
	v_max3_f32 v182, v182, v121, v89
	v_max3_f32 v184, v184, v90, v126
	v_max3_f32 v183, v183, v127, v95
	v_max3_f32 v170, v170, v124, v92
	v_max3_f32 v182, v182, v125, v93
	v_max3_f32 v183, v184, v94, v183
	v_max3_f32 v170, v170, v182, v183
	v_max_f32_e32 v182, v64, v64
	v_max_f32_e32 v183, v96, v96
	v_max_f32_e32 v182, v183, v182
	v_max_f32_e32 v183, v65, v65
	v_max_f32_e32 v184, v97, v97
	v_max_f32_e32 v183, v184, v183
	v_max_f32_e32 v184, v67, v67
	v_max_f32_e32 v185, v99, v99
	v_max_f32_e32 v184, v185, v184
	v_max3_f32 v185, v98, v66, v102
	v_max3_f32 v184, v184, v103, v71
	v_max3_f32 v182, v182, v100, v68
	v_max3_f32 v183, v183, v101, v69
	v_max3_f32 v185, v185, v70, v106
	v_max3_f32 v184, v184, v107, v75
	v_max3_f32 v182, v182, v104, v72
	v_max3_f32 v183, v183, v105, v73
	v_max3_f32 v185, v185, v74, v110
	v_max3_f32 v184, v184, v111, v79
	v_max3_f32 v182, v182, v108, v76
	v_max3_f32 v183, v183, v109, v77
	v_max3_f32 v184, v185, v78, v184
	ds_bpermute_b32 v185, v196, v170
	v_max3_f32 v183, v182, v183, v184
	ds_bpermute_b32 v184, v196, v183
	s_waitcnt lgkmcnt(1)
	v_max_f32_e32 v182, v185, v185
	v_max_f32_e32 v182, v170, v182
	s_waitcnt lgkmcnt(0)
	v_max_f32_e32 v170, v184, v184
	v_max_f32_e32 v170, v183, v170
	v_add_f32_e32 v183, 0x42317218, v202
	v_cmp_gt_f32_e32 vcc, v182, v183
	v_add_f32_e32 v183, 0x42317218, v201
	v_cmp_gt_f32_e64 s[2:3], v170, v183
	s_or_b64 vcc, vcc, s[2:3]
	s_cbranch_vccz .LBB0_1346
	v_max_f32_e32 v182, v182, v182
	v_max_f32_e32 v183, v202, v202
	v_max_f32_e32 v184, v183, v182
	v_max_f32_e32 v170, v170, v170
	v_max_f32_e32 v182, v201, v201
	v_cmp_ngt_f32_e32 vcc, s15, v184
	v_max_f32_e32 v185, v182, v170
	s_nop 0
	v_cndmask_b32_e32 v170, 0, v184, vcc
	v_sub_f32_e32 v170, v202, v170
	v_mul_f32_e32 v170, 0x3e38aa3b, v170
	v_cmp_ngt_f32_e32 vcc, s15, v185
	v_exp_f32_e32 v183, v170
	v_mov_b32_e32 v202, v184
	v_cndmask_b32_e32 v170, 0, v185, vcc
	v_sub_f32_e32 v170, v201, v170
	v_mul_f32_e32 v170, 0x3e38aa3b, v170
	v_exp_f32_e32 v182, v170
	v_mov_b32_e32 v170, v183
	v_mul_f32_e32 v62, v62, v170
	v_mul_f32_e32 v63, v63, v170
	v_mul_f32_e32 v60, v60, v170
	v_mul_f32_e32 v61, v61, v170
	v_mul_f32_e32 v174, v174, v182
	v_mul_f32_e32 v175, v175, v183
	v_mul_f32_e32 v58, v58, v170
	v_mul_f32_e32 v59, v59, v170
	v_mul_f32_e32 v56, v56, v170
	v_mul_f32_e32 v57, v57, v170
	v_mul_f32_e32 v54, v54, v170
	v_mul_f32_e32 v55, v55, v170
	v_mul_f32_e32 v52, v52, v170
	v_mul_f32_e32 v53, v53, v170
	v_mul_f32_e32 v50, v50, v170
	v_mul_f32_e32 v51, v51, v170
	v_mul_f32_e32 v48, v48, v170
	v_mul_f32_e32 v49, v49, v170
	v_mul_f32_e32 v14, v14, v182
	v_mul_f32_e32 v15, v15, v182
	v_mul_f32_e32 v12, v12, v182
	v_mul_f32_e32 v13, v13, v182
	v_mul_f32_e32 v10, v10, v182
	v_mul_f32_e32 v11, v11, v182
	v_mul_f32_e32 v8, v8, v182
	v_mul_f32_e32 v9, v9, v182
	v_mul_f32_e32 v6, v6, v182
	v_mul_f32_e32 v7, v7, v182
	v_mul_f32_e32 v4, v4, v182
	v_mul_f32_e32 v5, v5, v182
	v_mul_f32_e32 v2, v2, v182
	v_mul_f32_e32 v3, v3, v182
	v_mul_f32_e32 v0, v0, v182
	v_mul_f32_e32 v1, v1, v182
	v_mul_f32_e32 v46, v46, v170
	v_mul_f32_e32 v47, v47, v170
	v_mul_f32_e32 v44, v44, v170
	v_mul_f32_e32 v45, v45, v170
	v_mul_f32_e32 v42, v42, v170
	v_mul_f32_e32 v43, v43, v170
	v_mul_f32_e32 v40, v40, v170
	v_mul_f32_e32 v41, v41, v170
	v_mul_f32_e32 v38, v38, v170
	v_mul_f32_e32 v39, v39, v170
	v_mul_f32_e32 v36, v36, v170
	v_mul_f32_e32 v37, v37, v170
	v_mul_f32_e32 v34, v34, v170
	v_mul_f32_e32 v35, v35, v170
	v_mul_f32_e32 v32, v32, v170
	v_mul_f32_e32 v33, v33, v170
	v_mul_f32_e32 v30, v30, v182
	v_mul_f32_e32 v31, v31, v182
	v_mul_f32_e32 v28, v28, v182
	v_mul_f32_e32 v29, v29, v182
	v_mul_f32_e32 v26, v26, v182
	v_mul_f32_e32 v27, v27, v182
	v_mul_f32_e32 v24, v24, v182
	v_mul_f32_e32 v25, v25, v182
	v_mul_f32_e32 v22, v22, v182
	v_mul_f32_e32 v23, v23, v182
	v_mul_f32_e32 v20, v20, v182
	v_mul_f32_e32 v21, v21, v182
	v_mul_f32_e32 v18, v18, v182
	v_mul_f32_e32 v19, v19, v182
	v_mul_f32_e32 v16, v16, v182
	v_mul_f32_e32 v17, v17, v182
	v_mov_b32_e32 v201, v185
	s_branch .LBB0_1346
.LBB0_1349:
	ds_read_b128 v[64:67], v199 offset:9216
	ds_read_b128 v[160:163], v199 offset:9248
	s_waitcnt lgkmcnt(1)
	v_mfma_f32_32x32x16_bf16 v[112:127], v[64:67], v[152:155], 0
	v_mfma_f32_32x32x16_bf16 v[96:111], v[64:67], v[156:159], 0
	ds_read_b128 v[64:67], v199 offset:13824
	ds_read_b128 v[164:167], v199 offset:13856
	s_waitcnt lgkmcnt(1)
	v_mfma_f32_32x32x16_bf16 v[80:95], v[64:67], v[152:155], 0
	v_mfma_f32_32x32x16_bf16 v[64:79], v[64:67], v[156:159], 0
	v_mfma_f32_32x32x16_bf16 v[112:127], v[160:163], v[144:147], v[112:127]
	s_waitcnt lgkmcnt(0)
	v_mfma_f32_32x32x16_bf16 v[80:95], v[164:167], v[144:147], v[80:95]
	v_mfma_f32_32x32x16_bf16 v[96:111], v[160:163], v[148:151], v[96:111]
	v_mfma_f32_32x32x16_bf16 v[64:79], v[164:167], v[148:151], v[64:79]
	ds_read_b128 v[144:147], v199 offset:9280
	ds_read_b128 v[148:151], v199 offset:9312
	ds_read_b128 v[152:155], v199 offset:13888
	ds_read_b128 v[156:159], v199 offset:13920
	s_waitcnt lgkmcnt(3)
	v_mfma_f32_32x32x16_bf16 v[112:127], v[144:147], v[140:143], v[112:127]
	s_waitcnt lgkmcnt(1)
	v_mfma_f32_32x32x16_bf16 v[80:95], v[152:155], v[140:143], v[80:95]
	v_mfma_f32_32x32x16_bf16 v[96:111], v[144:147], v[132:135], v[96:111]
	v_mfma_f32_32x32x16_bf16 v[64:79], v[152:155], v[132:135], v[64:79]
	v_mfma_f32_32x32x16_bf16 v[112:127], v[148:151], v[136:139], v[112:127]
	s_waitcnt lgkmcnt(0)
	v_mfma_f32_32x32x16_bf16 v[80:95], v[156:159], v[136:139], v[80:95]
	s_nop 9
	v_max_f32_e32 v137, v112, v112
	v_max_f32_e32 v138, v113, v113
	v_max_f32_e32 v139, v115, v115
	v_mfma_f32_32x32x16_bf16 v[64:79], v[156:159], v[128:131], v[64:79]
	v_max_f32_e32 v136, v80, v80
	v_max_f32_e32 v136, v137, v136
	v_max_f32_e32 v137, v81, v81
	v_max_f32_e32 v137, v138, v137
	v_max_f32_e32 v138, v83, v83
	v_max_f32_e32 v138, v139, v138
	v_max3_f32 v133, v114, v82, v118
	v_mfma_f32_32x32x16_bf16 v[96:111], v[148:151], v[128:131], v[96:111]
	v_max3_f32 v134, v138, v119, v87
	v_max3_f32 v136, v136, v116, v84
	v_max3_f32 v132, v137, v117, v85
	v_max3_f32 v133, v133, v86, v122
	v_max3_f32 v134, v134, v123, v91
	v_max3_f32 v135, v136, v120, v88
	v_max3_f32 v132, v132, v121, v89
	v_max3_f32 v133, v133, v90, v126
	v_max3_f32 v134, v134, v127, v95
	v_max_f32_e32 v129, v65, v65
	s_nop 1
	v_max_f32_e32 v130, v97, v97
	v_max3_f32 v135, v135, v124, v92
	v_max3_f32 v132, v132, v125, v93
	v_max3_f32 v133, v133, v94, v134
	v_max_f32_e32 v129, v130, v129
	v_max_f32_e32 v130, v67, v67
	v_max_f32_e32 v131, v99, v99
	v_max3_f32 v132, v135, v132, v133
	v_max_f32_e32 v133, v64, v64
	v_max_f32_e32 v128, v96, v96
	v_max_f32_e32 v130, v131, v130
	v_max_f32_e32 v128, v128, v133
	v_max3_f32 v131, v98, v66, v102
	v_max3_f32 v130, v130, v103, v71
	v_max3_f32 v128, v128, v100, v68
	v_max3_f32 v129, v129, v101, v69
	v_max3_f32 v131, v131, v70, v106
	v_max3_f32 v130, v130, v107, v75
	v_max3_f32 v128, v128, v104, v72
	v_max3_f32 v129, v129, v105, v73
	v_max3_f32 v131, v131, v74, v110
	v_max3_f32 v130, v130, v111, v79
	v_max3_f32 v128, v128, v108, v76
	v_max3_f32 v129, v129, v109, v77
	v_max3_f32 v130, v131, v78, v130
	v_max3_f32 v128, v128, v129, v130
	ds_bpermute_b32 v131, v196, v132
	ds_bpermute_b32 v130, v196, v128
	s_waitcnt lgkmcnt(1)
	v_max_f32_e32 v129, v131, v131
	s_waitcnt lgkmcnt(0)
	v_max_f32_e32 v130, v130, v130
	v_max_f32_e32 v129, v132, v129
	v_max_f32_e32 v128, v128, v130
	v_add_f32_e32 v130, 0x42317218, v202
	v_cmp_gt_f32_e32 vcc, v129, v130
	v_add_f32_e32 v130, 0x42317218, v201
	v_cmp_gt_f32_e64 s[2:3], v128, v130
	s_or_b64 vcc, vcc, s[2:3]
	s_cbranch_vccz .LBB0_1344
	v_max_f32_e32 v129, v129, v129
	v_max_f32_e32 v130, v202, v202
	v_max_f32_e32 v131, v130, v129
	v_max_f32_e32 v128, v128, v128
	v_max_f32_e32 v129, v201, v201
	v_cmp_gt_f32_e32 vcc, s15, v131
	v_max_f32_e32 v132, v129, v128
	v_cmp_gt_f32_e64 s[2:3], s15, v132
	v_cndmask_b32_e64 v128, v131, 0, vcc
	v_sub_f32_e32 v128, v202, v128
	v_mul_f32_e32 v128, 0x3e38aa3b, v128
	v_exp_f32_e32 v129, v128
	v_cndmask_b32_e64 v128, v132, 0, s[2:3]
	v_sub_f32_e32 v128, v201, v128
	v_mul_f32_e32 v128, 0x3e38aa3b, v128
	v_exp_f32_e32 v128, v128
	v_mov_b32_e32 v130, v129
	v_mul_f32_e32 v62, v62, v130
	v_mul_f32_e32 v63, v63, v130
	v_mul_f32_e32 v60, v60, v130
	v_mul_f32_e32 v61, v61, v130
	v_mul_f32_e32 v174, v174, v128
	v_mul_f32_e32 v175, v175, v129
	v_mul_f32_e32 v14, v14, v128
	v_mul_f32_e32 v15, v15, v128
	v_mul_f32_e32 v12, v12, v128
	v_mul_f32_e32 v13, v13, v128
	v_mul_f32_e32 v10, v10, v128
	v_mul_f32_e32 v11, v11, v128
	v_mul_f32_e32 v8, v8, v128
	v_mul_f32_e32 v9, v9, v128
	v_mul_f32_e32 v6, v6, v128
	v_mul_f32_e32 v7, v7, v128
	v_mul_f32_e32 v4, v4, v128
	v_mul_f32_e32 v5, v5, v128
	v_mul_f32_e32 v2, v2, v128
	v_mul_f32_e32 v3, v3, v128
	v_mul_f32_e32 v0, v0, v128
	v_mul_f32_e32 v1, v1, v128
	v_mul_f32_e32 v30, v30, v128
	v_mul_f32_e32 v31, v31, v128
	v_mul_f32_e32 v28, v28, v128
	v_mul_f32_e32 v29, v29, v128
	v_mul_f32_e32 v26, v26, v128
	v_mul_f32_e32 v27, v27, v128
	v_mul_f32_e32 v24, v24, v128
	v_mul_f32_e32 v25, v25, v128
	v_mul_f32_e32 v22, v22, v128
	v_mul_f32_e32 v23, v23, v128
	v_mul_f32_e32 v20, v20, v128
	v_mul_f32_e32 v21, v21, v128
	v_mul_f32_e32 v18, v18, v128
	v_mul_f32_e32 v19, v19, v128
	v_mul_f32_e32 v16, v16, v128
	v_mul_f32_e32 v17, v17, v128
	v_mul_f32_e32 v128, 0x3e38aa3b, v131
	v_cndmask_b32_e64 v170, v128, 0, vcc
	v_mul_f32_e32 v128, 0x3e38aa3b, v132
	v_mul_f32_e32 v58, v58, v130
	v_mul_f32_e32 v59, v59, v130
	v_mul_f32_e32 v56, v56, v130
	v_mul_f32_e32 v57, v57, v130
	v_mul_f32_e32 v54, v54, v130
	v_mul_f32_e32 v55, v55, v130
	v_mul_f32_e32 v52, v52, v130
	v_mul_f32_e32 v53, v53, v130
	v_mul_f32_e32 v50, v50, v130
	v_mul_f32_e32 v51, v51, v130
	v_mul_f32_e32 v48, v48, v130
	v_mul_f32_e32 v49, v49, v130
	v_mul_f32_e32 v46, v46, v130
	v_mul_f32_e32 v47, v47, v130
	v_mul_f32_e32 v44, v44, v130
	v_mul_f32_e32 v45, v45, v130
	v_mul_f32_e32 v42, v42, v130
	v_mul_f32_e32 v43, v43, v130
	v_mul_f32_e32 v40, v40, v130
	v_mul_f32_e32 v41, v41, v130
	v_mul_f32_e32 v38, v38, v130
	v_mul_f32_e32 v39, v39, v130
	v_mul_f32_e32 v36, v36, v130
	v_mul_f32_e32 v37, v37, v130
	v_mul_f32_e32 v34, v34, v130
	v_mul_f32_e32 v35, v35, v130
	v_mul_f32_e32 v32, v32, v130
	v_mul_f32_e32 v33, v33, v130
	v_cndmask_b32_e64 v197, v128, 0, s[2:3]
	s_branch .LBB0_1344
